# speedup vs baseline: 1.0289x; 1.0034x over previous
; template <int NS, bool LORA, int mat> ...
;     ...
;   const int ch = 64 * head + lane;
;   const float kk_c = p.k_k[ch], ka_c = p.k_a[ch], rk_c = p.r_k[ch];
;   const float mu_r = p.mu_shift[ch], mu_k = p.mu_shift[1024 + ch], mu_v = p.mu_shift[2048 + ch];
;   uint4 la[2][6];
;   u16 rv[2][NS][9];
.LBB0_1118:
	s_lshl_b32 s4, s89, 7
	s_add_i32 s4, s4, s60
	s_lshr_b32 s10, s4, 5
	s_lshl_b64 s[4:5], s[10:11], 11
	s_waitcnt vmcnt(17)
	v_mov_b32 v144, v146
	s_add_u32 s90, s4, 0x4000
	v_ashrrev_i32_e32 v7, 6, v144
	s_waitcnt vmcnt(13)
	v_and_b32_e32 v149, 63, v144
	v_cmp_lt_i32_e32 vcc, 3, v7
	s_and_saveexec_b64 s[4:5], vcc
	s_xor_b64 s[52:53], exec, s[4:5]
	s_cbranch_execz .LBB0_1213
	v_cmp_lt_i32_e32 vcc, 4, v7
	s_and_saveexec_b64 s[4:5], vcc
	s_xor_b64 s[54:55], exec, s[4:5]
	s_cbranch_execz .LBB0_1188
	v_cmp_ne_u32_e32 vcc, 5, v7
	s_and_saveexec_b64 s[4:5], vcc
	s_xor_b64 s[6:7], exec, s[4:5]
	s_cbranch_execz .LBB0_1155
	v_readfirstlane_b32 s4, v7
	v_and_b32_e32 v48, 7, v149
	v_lshrrev_b32_e32 v49, 3, v149
	s_sub_i32 s4, s4, 6
	s_lshl_b32 s4, s4, 3
	v_add_u32_e32 v50, s4, v49
	v_lshl_add_u32 v51, v48, 3, s62
	s_mul_i32 s4, s90, 0x1c00
	v_lshlrev_b32_e32 v52, 1, v51
	v_add_u32_e32 v52, 0x800, v52
	v_add_u32_e32 v52, s4, v52
	v_lshlrev_b32_e32 v51, 2, v51
	v_mov_b32_e32 v53, 0x1c00
	v_mov_b32_e32 v58, 0x7ff
	v_mov_b32_e32 v59, -16
	v_cndmask_b32_e64 v59, v59, 16, s[0:1]
	v_add_u32_e32 v205, 0x1000, v51
	v_add_u32_e32 v206, 0x2000, v51
	global_load_dwordx4 v[0:3], v51, s[50:51]
	global_load_dwordx4 v[4:7], v51, s[50:51] offset:16
	global_load_dwordx4 v[8:11], v51, s[16:17]
	global_load_dwordx4 v[12:15], v51, s[16:17] offset:16
	global_load_dwordx4 v[16:19], v51, s[18:19]
	global_load_dwordx4 v[20:23], v51, s[18:19] offset:16
	global_load_dwordx4 v[24:27], v51, s[38:39]
	global_load_dwordx4 v[28:31], v51, s[38:39] offset:16
	global_load_dwordx4 v[32:35], v205, s[38:39]
	global_load_dwordx4 v[36:39], v205, s[38:39] offset:16
	global_load_dwordx4 v[40:43], v206, s[38:39]
	global_load_dwordx4 v[44:47], v206, s[38:39] offset:16
	v_mul_u32_u24_e32 v54, 0x500, v50
	v_lshlrev_b32_e32 v55, 8, v50
	v_lshl_add_u32 v54, v48, 5, v54
	v_lshl_add_u32 v55, v48, 5, v55
	v_add_u32_e32 v54, 0x5000, v54
	v_add_u32_e32 v55, 0x3000, v55
	v_sub_u32_e32 v205, v58, v50
	v_cndmask_b32_e64 v56, v205, v50, s[0:1]
	v_cmp_eq_u32_e64 s[8:9], 0, v48
	s_waitcnt vmcnt(0)
	v_cmp_lt_i32_e64 s[4:5], 0, v56
	v_cmp_gt_i32_e64 s[58:59], v58, v56
	v_mad_u32_u24 v205, v56, v53, v52
	s_nop 0
	v_cndmask_b32_e64 v206, 0, v53, s[4:5]
	v_cndmask_b32_e64 v207, 0, v53, s[58:59]
	v_cndmask_b32_e64 v60, 0, 1.0, s[4:5]
	v_cndmask_b32_e64 v61, 0, 1.0, s[58:59]
	v_sub_u32_e32 v206, v205, v206
	v_add_u32_e32 v207, v205, v207
	global_load_dwordx4 v[64:67], v205, s[72:73] offset:-2048
	global_load_dwordx4 v[68:71], v205, s[72:73]
	global_load_dwordx4 v[72:75], v205, s[72:73] offset:2048
	global_load_dwordx4 v[76:79], v206, s[72:73] offset:-2048
	global_load_dwordx4 v[80:83], v206, s[72:73]
	global_load_dwordx4 v[84:87], v206, s[72:73] offset:2048
	global_load_dwordx4 v[88:91], v207, s[72:73] offset:-2048
	global_load_dwordx4 v[92:95], v207, s[72:73]
	global_load_dwordx4 v[96:99], v207, s[72:73] offset:2048
	v_add_u32_e32 v57, v59, v56
	v_cmp_lt_i32_e64 s[4:5], 0, v57
	v_cmp_gt_i32_e64 s[58:59], v58, v57
	v_mad_u32_u24 v205, v57, v53, v52
	s_nop 0
	v_cndmask_b32_e64 v206, 0, v53, s[4:5]
	v_cndmask_b32_e64 v207, 0, v53, s[58:59]
	v_cndmask_b32_e64 v62, 0, 1.0, s[4:5]
	v_cndmask_b32_e64 v63, 0, 1.0, s[58:59]
	v_sub_u32_e32 v206, v205, v206
	v_add_u32_e32 v207, v205, v207
	global_load_dwordx4 v[100:103], v205, s[72:73] offset:-2048
	global_load_dwordx4 v[104:107], v205, s[72:73]
	global_load_dwordx4 v[108:111], v205, s[72:73] offset:2048
	global_load_dwordx4 v[112:115], v206, s[72:73] offset:-2048
	global_load_dwordx4 v[116:119], v206, s[72:73]
	global_load_dwordx4 v[120:123], v206, s[72:73] offset:2048
	global_load_dwordx4 v[124:127], v207, s[72:73] offset:-2048
	global_load_dwordx4 v[128:131], v207, s[72:73]
	global_load_dwordx4 v[132:135], v207, s[72:73] offset:2048
	s_mov_b32 s10, 3
	s_waitcnt lgkmcnt(0)
	s_barrier
	ds_read_b128 v[184:187], v55 offset:0
	ds_read_b128 v[188:191], v55 offset:16
	s_waitcnt vmcnt(9)
	v_lshlrev_b32_e32 v136, 16, v64
	v_lshlrev_b32_e32 v192, 16, v76
	v_lshlrev_b32_e32 v193, 16, v88
	v_mul_f32_e32 v193, v61, v193
	v_fmac_f32_e32 v193, v60, v192
	v_fma_f32 v192, v193, 0.5, -v136
	v_fmac_f32_e32 v136, v24, v192
	v_and_b32_e32 v137, 0xffff0000, v64
	v_and_b32_e32 v192, 0xffff0000, v76
	v_and_b32_e32 v193, 0xffff0000, v88
	v_mul_f32_e32 v193, v61, v193
	v_fmac_f32_e32 v193, v60, v192
	v_fma_f32 v192, v193, 0.5, -v137
	v_fmac_f32_e32 v137, v25, v192
	v_lshlrev_b32_e32 v138, 16, v65
	v_lshlrev_b32_e32 v192, 16, v77
	v_lshlrev_b32_e32 v193, 16, v89
	v_mul_f32_e32 v193, v61, v193
	v_fmac_f32_e32 v193, v60, v192
	v_fma_f32 v192, v193, 0.5, -v138
	v_fmac_f32_e32 v138, v26, v192
	v_and_b32_e32 v139, 0xffff0000, v65
	v_and_b32_e32 v192, 0xffff0000, v77
	v_and_b32_e32 v193, 0xffff0000, v89
	v_mul_f32_e32 v193, v61, v193
	v_fmac_f32_e32 v193, v60, v192
	v_fma_f32 v192, v193, 0.5, -v139
	v_fmac_f32_e32 v139, v27, v192
	v_lshlrev_b32_e32 v140, 16, v66
	v_lshlrev_b32_e32 v192, 16, v78
	v_lshlrev_b32_e32 v193, 16, v90
	v_mul_f32_e32 v193, v61, v193
	v_fmac_f32_e32 v193, v60, v192
	v_fma_f32 v192, v193, 0.5, -v140
	v_fmac_f32_e32 v140, v28, v192
	v_and_b32_e32 v141, 0xffff0000, v66
	v_and_b32_e32 v192, 0xffff0000, v78
	v_and_b32_e32 v193, 0xffff0000, v90
	v_mul_f32_e32 v193, v61, v193
	v_fmac_f32_e32 v193, v60, v192
	v_fma_f32 v192, v193, 0.5, -v141
	v_fmac_f32_e32 v141, v29, v192
	v_lshlrev_b32_e32 v142, 16, v67
	v_lshlrev_b32_e32 v192, 16, v79
	v_lshlrev_b32_e32 v193, 16, v91
	v_mul_f32_e32 v193, v61, v193
	v_fmac_f32_e32 v193, v60, v192
	v_fma_f32 v192, v193, 0.5, -v142
	v_fmac_f32_e32 v142, v30, v192
	v_and_b32_e32 v143, 0xffff0000, v67
	v_and_b32_e32 v192, 0xffff0000, v79
	v_and_b32_e32 v193, 0xffff0000, v91
	v_mul_f32_e32 v193, v61, v193
	v_fmac_f32_e32 v193, v60, v192
	v_fma_f32 v192, v193, 0.5, -v143
	v_fmac_f32_e32 v143, v31, v192
	v_lshlrev_b32_e32 v208, 16, v68
	v_lshlrev_b32_e32 v192, 16, v80
	v_lshlrev_b32_e32 v193, 16, v92
	v_mul_f32_e32 v193, v61, v193
	v_fmac_f32_e32 v193, v60, v192
	v_fma_f32 v192, v193, 0.5, -v208
	v_fmac_f32_e32 v208, v32, v192
	v_and_b32_e32 v209, 0xffff0000, v68
	v_and_b32_e32 v192, 0xffff0000, v80
	v_and_b32_e32 v193, 0xffff0000, v92
	v_mul_f32_e32 v193, v61, v193
	v_fmac_f32_e32 v193, v60, v192
	v_fma_f32 v192, v193, 0.5, -v209
	v_fmac_f32_e32 v209, v33, v192
	v_lshlrev_b32_e32 v210, 16, v69
	v_lshlrev_b32_e32 v192, 16, v81
	v_lshlrev_b32_e32 v193, 16, v93
	v_mul_f32_e32 v193, v61, v193
	v_fmac_f32_e32 v193, v60, v192
	v_fma_f32 v192, v193, 0.5, -v210
	v_fmac_f32_e32 v210, v34, v192
	v_and_b32_e32 v211, 0xffff0000, v69
	v_and_b32_e32 v192, 0xffff0000, v81
	v_and_b32_e32 v193, 0xffff0000, v93
	v_mul_f32_e32 v193, v61, v193
	v_fmac_f32_e32 v193, v60, v192
	v_fma_f32 v192, v193, 0.5, -v211
	v_fmac_f32_e32 v211, v35, v192
	v_lshlrev_b32_e32 v212, 16, v70
	v_lshlrev_b32_e32 v192, 16, v82
	v_lshlrev_b32_e32 v193, 16, v94
	v_mul_f32_e32 v193, v61, v193
	v_fmac_f32_e32 v193, v60, v192
	v_fma_f32 v192, v193, 0.5, -v212
	v_fmac_f32_e32 v212, v36, v192
	v_and_b32_e32 v213, 0xffff0000, v70
	v_and_b32_e32 v192, 0xffff0000, v82
	v_and_b32_e32 v193, 0xffff0000, v94
	v_mul_f32_e32 v193, v61, v193
	v_fmac_f32_e32 v193, v60, v192
	v_fma_f32 v192, v193, 0.5, -v213
	v_fmac_f32_e32 v213, v37, v192
	v_lshlrev_b32_e32 v214, 16, v71
	v_lshlrev_b32_e32 v192, 16, v83
	v_lshlrev_b32_e32 v193, 16, v95
	v_mul_f32_e32 v193, v61, v193
	v_fmac_f32_e32 v193, v60, v192
	v_fma_f32 v192, v193, 0.5, -v214
	v_fmac_f32_e32 v214, v38, v192
	v_and_b32_e32 v215, 0xffff0000, v71
	v_and_b32_e32 v192, 0xffff0000, v83
	v_and_b32_e32 v193, 0xffff0000, v95
	v_mul_f32_e32 v193, v61, v193
	v_fmac_f32_e32 v193, v60, v192
	v_fma_f32 v192, v193, 0.5, -v215
	v_fmac_f32_e32 v215, v39, v192
	v_lshlrev_b32_e32 v152, 16, v72
	v_lshlrev_b32_e32 v192, 16, v84
	v_lshlrev_b32_e32 v193, 16, v96
	v_mul_f32_e32 v193, v61, v193
	v_fmac_f32_e32 v193, v60, v192
	v_fma_f32 v192, v193, 0.5, -v152
	v_fmac_f32_e32 v152, v40, v192
	v_and_b32_e32 v153, 0xffff0000, v72
	v_and_b32_e32 v192, 0xffff0000, v84
	v_and_b32_e32 v193, 0xffff0000, v96
	v_mul_f32_e32 v193, v61, v193
	v_fmac_f32_e32 v193, v60, v192
	v_fma_f32 v192, v193, 0.5, -v153
	v_fmac_f32_e32 v153, v41, v192
	v_lshlrev_b32_e32 v154, 16, v73
	v_lshlrev_b32_e32 v192, 16, v85
	v_lshlrev_b32_e32 v193, 16, v97
	v_mul_f32_e32 v193, v61, v193
	v_fmac_f32_e32 v193, v60, v192
	v_fma_f32 v192, v193, 0.5, -v154
	v_fmac_f32_e32 v154, v42, v192
	v_and_b32_e32 v155, 0xffff0000, v73
	v_and_b32_e32 v192, 0xffff0000, v85
	v_and_b32_e32 v193, 0xffff0000, v97
	v_mul_f32_e32 v193, v61, v193
	v_fmac_f32_e32 v193, v60, v192
	v_fma_f32 v192, v193, 0.5, -v155
	v_fmac_f32_e32 v155, v43, v192
	v_lshlrev_b32_e32 v156, 16, v74
	v_lshlrev_b32_e32 v192, 16, v86
	v_lshlrev_b32_e32 v193, 16, v98
	v_mul_f32_e32 v193, v61, v193
	v_fmac_f32_e32 v193, v60, v192
	v_fma_f32 v192, v193, 0.5, -v156
	v_fmac_f32_e32 v156, v44, v192
	v_and_b32_e32 v157, 0xffff0000, v74
	v_and_b32_e32 v192, 0xffff0000, v86
	v_and_b32_e32 v193, 0xffff0000, v98
	v_mul_f32_e32 v193, v61, v193
	v_fmac_f32_e32 v193, v60, v192
	v_fma_f32 v192, v193, 0.5, -v157
	v_fmac_f32_e32 v157, v45, v192
	v_lshlrev_b32_e32 v158, 16, v75
	v_lshlrev_b32_e32 v192, 16, v87
	v_lshlrev_b32_e32 v193, 16, v99
	v_mul_f32_e32 v193, v61, v193
	v_fmac_f32_e32 v193, v60, v192
	v_fma_f32 v192, v193, 0.5, -v158
	v_fmac_f32_e32 v158, v46, v192
	v_and_b32_e32 v159, 0xffff0000, v75
	v_and_b32_e32 v192, 0xffff0000, v87
	v_and_b32_e32 v193, 0xffff0000, v99
	v_mul_f32_e32 v193, v61, v193
	v_fmac_f32_e32 v193, v60, v192
	v_fma_f32 v192, v193, 0.5, -v159
	v_fmac_f32_e32 v159, v47, v192
	v_add_u32_e32 v57, v59, v56
	v_add_u32_e32 v57, v59, v57
	v_cmp_lt_i32_e64 s[4:5], 0, v57
	v_cmp_gt_i32_e64 s[58:59], v58, v57
	v_mad_u32_u24 v205, v57, v53, v52
	s_nop 0
	v_cndmask_b32_e64 v206, 0, v53, s[4:5]
	v_cndmask_b32_e64 v207, 0, v53, s[58:59]
	v_cndmask_b32_e64 v60, 0, 1.0, s[4:5]
	v_cndmask_b32_e64 v61, 0, 1.0, s[58:59]
	v_sub_u32_e32 v206, v205, v206
	v_add_u32_e32 v207, v205, v207
	global_load_dwordx4 v[64:67], v205, s[72:73] offset:-2048
	global_load_dwordx4 v[68:71], v205, s[72:73]
	global_load_dwordx4 v[72:75], v205, s[72:73] offset:2048
	global_load_dwordx4 v[76:79], v206, s[72:73] offset:-2048
	global_load_dwordx4 v[80:83], v206, s[72:73]
	global_load_dwordx4 v[84:87], v206, s[72:73] offset:2048
	global_load_dwordx4 v[88:91], v207, s[72:73] offset:-2048
	global_load_dwordx4 v[92:95], v207, s[72:73]
	global_load_dwordx4 v[96:99], v207, s[72:73] offset:2048
	v_mul_f32_e32 v160, v0, v208
	v_mul_f32_e32 v161, v1, v209
	v_mul_f32_e32 v162, v2, v210
	v_mul_f32_e32 v163, v3, v211
	v_mul_f32_e32 v164, v4, v212
	v_mul_f32_e32 v165, v5, v213
	v_mul_f32_e32 v166, v6, v214
	v_mul_f32_e32 v167, v7, v215
	v_mul_f32_e32 v200, v160, v160
	v_fmac_f32_e32 v200, v161, v161
	v_fmac_f32_e32 v200, v162, v162
	v_fmac_f32_e32 v200, v163, v163
	v_fmac_f32_e32 v200, v164, v164
	v_fmac_f32_e32 v200, v165, v165
	v_fmac_f32_e32 v200, v166, v166
	v_fmac_f32_e32 v200, v167, v167
	s_waitcnt lgkmcnt(0)
	v_add_f32_e32 v192, -1.0, v184
	v_fma_f32 v192, v8, v192, 1.0
	v_mul_f32_e32 v176, v208, v192
	v_add_f32_dpp v200, v200, v200 quad_perm:[1,0,3,2] row_mask:0xf bank_mask:0xf bound_ctrl:1
	v_add_f32_e32 v192, -1.0, v185
	v_fma_f32 v192, v9, v192, 1.0
	v_mul_f32_e32 v177, v209, v192
	v_add_f32_dpp v200, v200, v200 quad_perm:[2,3,0,1] row_mask:0xf bank_mask:0xf bound_ctrl:1
	v_add_f32_e32 v192, -1.0, v186
	v_fma_f32 v192, v10, v192, 1.0
	v_mul_f32_e32 v178, v210, v192
	v_add_f32_dpp v200, v200, v200 row_half_mirror row_mask:0xf bank_mask:0xf bound_ctrl:1
	v_add_f32_e32 v192, -1.0, v187
	v_fma_f32 v192, v11, v192, 1.0
	v_mul_f32_e32 v179, v211, v192
	v_add_f32_e32 v192, -1.0, v188
	v_fma_f32 v192, v12, v192, 1.0
	v_mul_f32_e32 v180, v212, v192
	v_add_f32_e32 v192, -1.0, v189
	v_fma_f32 v192, v13, v192, 1.0
	v_mul_f32_e32 v181, v213, v192
	v_add_f32_e32 v192, -1.0, v190
	v_fma_f32 v192, v14, v192, 1.0
	v_mul_f32_e32 v182, v214, v192
	v_add_f32_e32 v192, -1.0, v191
	v_fma_f32 v192, v15, v192, 1.0
	v_mul_f32_e32 v183, v215, v192
	v_max_f32_e32 v200, v200, v200
	v_max_f32_e32 v200, 0x179abe15, v200
	v_rsq_f32_e32 v201, v200
	v_mul_f32_e32 v192, v136, v176
	v_mul_f32_e32 v202, v16, v192
	v_mul_f32_e32 v160, v160, v201
	v_mul_f32_e32 v161, v161, v201
	v_mul_f32_e32 v162, v162, v201
	v_mul_f32_e32 v163, v163, v201
	v_mul_f32_e32 v164, v164, v201
	v_mul_f32_e32 v165, v165, v201
	v_mul_f32_e32 v166, v166, v201
	v_mul_f32_e32 v167, v167, v201
	v_mul_f32_e32 v168, v184, v160
	v_mul_f32_e32 v169, v185, v161
	v_mul_f32_e32 v170, v186, v162
	v_mul_f32_e32 v171, v187, v163
	v_mul_f32_e32 v172, v188, v164
	v_mul_f32_e32 v173, v189, v165
	v_mul_f32_e32 v174, v190, v166
	v_mul_f32_e32 v175, v191, v167
	ds_write_b128 v54, v[160:163] offset:0
	ds_write_b128 v54, v[164:167] offset:16
	ds_write_b128 v54, v[168:171] offset:256
	ds_write_b128 v54, v[172:175] offset:272
	ds_write_b128 v54, v[176:179] offset:512
	ds_write_b128 v54, v[180:183] offset:528
	ds_write_b128 v54, v[136:139] offset:768
	ds_write_b128 v54, v[140:143] offset:784
	ds_write_b128 v54, v[152:155] offset:1024
	ds_write_b128 v54, v[156:159] offset:1040
	v_mul_f32_e32 v192, v137, v177
	v_fmac_f32_e32 v202, v17, v192
	v_mul_f32_e32 v192, v138, v178
	v_fmac_f32_e32 v202, v18, v192
	v_mul_f32_e32 v192, v139, v179
	v_fmac_f32_e32 v202, v19, v192
	v_mul_f32_e32 v192, v140, v180
	v_fmac_f32_e32 v202, v20, v192
	v_mul_f32_e32 v192, v141, v181
	v_fmac_f32_e32 v202, v21, v192
	v_mul_f32_e32 v192, v142, v182
	v_fmac_f32_e32 v202, v22, v192
	v_mul_f32_e32 v192, v143, v183
	v_fmac_f32_e32 v202, v23, v192
	s_nop 1
	v_add_f32_dpp v202, v202, v202 quad_perm:[1,0,3,2] row_mask:0xf bank_mask:0xf bound_ctrl:1
	s_nop 1
	v_add_f32_dpp v202, v202, v202 quad_perm:[2,3,0,1] row_mask:0xf bank_mask:0xf bound_ctrl:1
	s_nop 1
	v_add_f32_dpp v202, v202, v202 row_half_mirror row_mask:0xf bank_mask:0xf bound_ctrl:1
	v_add_u32_e32 v205, s90, v56
	v_lshl_add_u32 v205, v205, 7, s64
	s_and_saveexec_b64 s[56:57], s[8:9]
	global_store_dword v205, v202, s[24:25]
	s_or_b64 exec, exec, s[56:57]
	v_add_u32_e32 v56, v59, v56
	s_waitcnt lgkmcnt(0)
	s_barrier
	ds_read_b128 v[184:187], v55 offset:4096
	ds_read_b128 v[188:191], v55 offset:4112
	s_waitcnt vmcnt(9)
	v_lshlrev_b32_e32 v136, 16, v100
	v_lshlrev_b32_e32 v192, 16, v112
	v_lshlrev_b32_e32 v193, 16, v124
	v_mul_f32_e32 v193, v63, v193
	v_fmac_f32_e32 v193, v62, v192
	v_fma_f32 v192, v193, 0.5, -v136
	v_fmac_f32_e32 v136, v24, v192
	v_and_b32_e32 v137, 0xffff0000, v100
	v_and_b32_e32 v192, 0xffff0000, v112
	v_and_b32_e32 v193, 0xffff0000, v124
	v_mul_f32_e32 v193, v63, v193
	v_fmac_f32_e32 v193, v62, v192
	v_fma_f32 v192, v193, 0.5, -v137
	v_fmac_f32_e32 v137, v25, v192
	v_lshlrev_b32_e32 v138, 16, v101
	v_lshlrev_b32_e32 v192, 16, v113
	v_lshlrev_b32_e32 v193, 16, v125
	v_mul_f32_e32 v193, v63, v193
	v_fmac_f32_e32 v193, v62, v192
	v_fma_f32 v192, v193, 0.5, -v138
	v_fmac_f32_e32 v138, v26, v192
	v_and_b32_e32 v139, 0xffff0000, v101
	v_and_b32_e32 v192, 0xffff0000, v113
	v_and_b32_e32 v193, 0xffff0000, v125
	v_mul_f32_e32 v193, v63, v193
	v_fmac_f32_e32 v193, v62, v192
	v_fma_f32 v192, v193, 0.5, -v139
	v_fmac_f32_e32 v139, v27, v192
	v_lshlrev_b32_e32 v140, 16, v102
	v_lshlrev_b32_e32 v192, 16, v114
	v_lshlrev_b32_e32 v193, 16, v126
	v_mul_f32_e32 v193, v63, v193
	v_fmac_f32_e32 v193, v62, v192
	v_fma_f32 v192, v193, 0.5, -v140
	v_fmac_f32_e32 v140, v28, v192
	v_and_b32_e32 v141, 0xffff0000, v102
	v_and_b32_e32 v192, 0xffff0000, v114
	v_and_b32_e32 v193, 0xffff0000, v126
	v_mul_f32_e32 v193, v63, v193
	v_fmac_f32_e32 v193, v62, v192
	v_fma_f32 v192, v193, 0.5, -v141
	v_fmac_f32_e32 v141, v29, v192
	v_lshlrev_b32_e32 v142, 16, v103
	v_lshlrev_b32_e32 v192, 16, v115
	v_lshlrev_b32_e32 v193, 16, v127
	v_mul_f32_e32 v193, v63, v193
	v_fmac_f32_e32 v193, v62, v192
	v_fma_f32 v192, v193, 0.5, -v142
	v_fmac_f32_e32 v142, v30, v192
	v_and_b32_e32 v143, 0xffff0000, v103
	v_and_b32_e32 v192, 0xffff0000, v115
	v_and_b32_e32 v193, 0xffff0000, v127
	v_mul_f32_e32 v193, v63, v193
	v_fmac_f32_e32 v193, v62, v192
	v_fma_f32 v192, v193, 0.5, -v143
	v_fmac_f32_e32 v143, v31, v192
	v_lshlrev_b32_e32 v208, 16, v104
	v_lshlrev_b32_e32 v192, 16, v116
	v_lshlrev_b32_e32 v193, 16, v128
	v_mul_f32_e32 v193, v63, v193
	v_fmac_f32_e32 v193, v62, v192
	v_fma_f32 v192, v193, 0.5, -v208
	v_fmac_f32_e32 v208, v32, v192
	v_and_b32_e32 v209, 0xffff0000, v104
	v_and_b32_e32 v192, 0xffff0000, v116
	v_and_b32_e32 v193, 0xffff0000, v128
	v_mul_f32_e32 v193, v63, v193
	v_fmac_f32_e32 v193, v62, v192
	v_fma_f32 v192, v193, 0.5, -v209
	v_fmac_f32_e32 v209, v33, v192
	v_lshlrev_b32_e32 v210, 16, v105
	v_lshlrev_b32_e32 v192, 16, v117
	v_lshlrev_b32_e32 v193, 16, v129
	v_mul_f32_e32 v193, v63, v193
	v_fmac_f32_e32 v193, v62, v192
	v_fma_f32 v192, v193, 0.5, -v210
	v_fmac_f32_e32 v210, v34, v192
	v_and_b32_e32 v211, 0xffff0000, v105
	v_and_b32_e32 v192, 0xffff0000, v117
	v_and_b32_e32 v193, 0xffff0000, v129
	v_mul_f32_e32 v193, v63, v193
	v_fmac_f32_e32 v193, v62, v192
	v_fma_f32 v192, v193, 0.5, -v211
	v_fmac_f32_e32 v211, v35, v192
	v_lshlrev_b32_e32 v212, 16, v106
	v_lshlrev_b32_e32 v192, 16, v118
	v_lshlrev_b32_e32 v193, 16, v130
	v_mul_f32_e32 v193, v63, v193
	v_fmac_f32_e32 v193, v62, v192
	v_fma_f32 v192, v193, 0.5, -v212
	v_fmac_f32_e32 v212, v36, v192
	v_and_b32_e32 v213, 0xffff0000, v106
	v_and_b32_e32 v192, 0xffff0000, v118
	v_and_b32_e32 v193, 0xffff0000, v130
	v_mul_f32_e32 v193, v63, v193
	v_fmac_f32_e32 v193, v62, v192
	v_fma_f32 v192, v193, 0.5, -v213
	v_fmac_f32_e32 v213, v37, v192
	v_lshlrev_b32_e32 v214, 16, v107
	v_lshlrev_b32_e32 v192, 16, v119
	v_lshlrev_b32_e32 v193, 16, v131
	v_mul_f32_e32 v193, v63, v193
	v_fmac_f32_e32 v193, v62, v192
	v_fma_f32 v192, v193, 0.5, -v214
	v_fmac_f32_e32 v214, v38, v192
	v_and_b32_e32 v215, 0xffff0000, v107
	v_and_b32_e32 v192, 0xffff0000, v119
	v_and_b32_e32 v193, 0xffff0000, v131
	v_mul_f32_e32 v193, v63, v193
	v_fmac_f32_e32 v193, v62, v192
	v_fma_f32 v192, v193, 0.5, -v215
	v_fmac_f32_e32 v215, v39, v192
	v_lshlrev_b32_e32 v152, 16, v108
	v_lshlrev_b32_e32 v192, 16, v120
	v_lshlrev_b32_e32 v193, 16, v132
	v_mul_f32_e32 v193, v63, v193
	v_fmac_f32_e32 v193, v62, v192
	v_fma_f32 v192, v193, 0.5, -v152
	v_fmac_f32_e32 v152, v40, v192
	v_and_b32_e32 v153, 0xffff0000, v108
	v_and_b32_e32 v192, 0xffff0000, v120
	v_and_b32_e32 v193, 0xffff0000, v132
	v_mul_f32_e32 v193, v63, v193
	v_fmac_f32_e32 v193, v62, v192
	v_fma_f32 v192, v193, 0.5, -v153
	v_fmac_f32_e32 v153, v41, v192
	v_lshlrev_b32_e32 v154, 16, v109
	v_lshlrev_b32_e32 v192, 16, v121
	v_lshlrev_b32_e32 v193, 16, v133
	v_mul_f32_e32 v193, v63, v193
	v_fmac_f32_e32 v193, v62, v192
	v_fma_f32 v192, v193, 0.5, -v154
	v_fmac_f32_e32 v154, v42, v192
	v_and_b32_e32 v155, 0xffff0000, v109
	v_and_b32_e32 v192, 0xffff0000, v121
	v_and_b32_e32 v193, 0xffff0000, v133
	v_mul_f32_e32 v193, v63, v193
	v_fmac_f32_e32 v193, v62, v192
	v_fma_f32 v192, v193, 0.5, -v155
	v_fmac_f32_e32 v155, v43, v192
	v_lshlrev_b32_e32 v156, 16, v110
	v_lshlrev_b32_e32 v192, 16, v122
	v_lshlrev_b32_e32 v193, 16, v134
	v_mul_f32_e32 v193, v63, v193
	v_fmac_f32_e32 v193, v62, v192
	v_fma_f32 v192, v193, 0.5, -v156
	v_fmac_f32_e32 v156, v44, v192
	v_and_b32_e32 v157, 0xffff0000, v110
	v_and_b32_e32 v192, 0xffff0000, v122
	v_and_b32_e32 v193, 0xffff0000, v134
	v_mul_f32_e32 v193, v63, v193
	v_fmac_f32_e32 v193, v62, v192
	v_fma_f32 v192, v193, 0.5, -v157
	v_fmac_f32_e32 v157, v45, v192
	v_lshlrev_b32_e32 v158, 16, v111
	v_lshlrev_b32_e32 v192, 16, v123
	v_lshlrev_b32_e32 v193, 16, v135
	v_mul_f32_e32 v193, v63, v193
	v_fmac_f32_e32 v193, v62, v192
	v_fma_f32 v192, v193, 0.5, -v158
	v_fmac_f32_e32 v158, v46, v192
	v_and_b32_e32 v159, 0xffff0000, v111
	v_and_b32_e32 v192, 0xffff0000, v123
	v_and_b32_e32 v193, 0xffff0000, v135
	v_mul_f32_e32 v193, v63, v193
	v_fmac_f32_e32 v193, v62, v192
	v_fma_f32 v192, v193, 0.5, -v159
	v_fmac_f32_e32 v159, v47, v192
	v_add_u32_e32 v57, v59, v56
	v_add_u32_e32 v57, v59, v57
	v_cmp_lt_i32_e64 s[4:5], 0, v57
	v_cmp_gt_i32_e64 s[58:59], v58, v57
	v_mad_u32_u24 v205, v57, v53, v52
	s_nop 0
	v_cndmask_b32_e64 v206, 0, v53, s[4:5]
	v_cndmask_b32_e64 v207, 0, v53, s[58:59]
	v_cndmask_b32_e64 v62, 0, 1.0, s[4:5]
	v_cndmask_b32_e64 v63, 0, 1.0, s[58:59]
	v_sub_u32_e32 v206, v205, v206
	v_add_u32_e32 v207, v205, v207
	global_load_dwordx4 v[100:103], v205, s[72:73] offset:-2048
	global_load_dwordx4 v[104:107], v205, s[72:73]
	global_load_dwordx4 v[108:111], v205, s[72:73] offset:2048
	global_load_dwordx4 v[112:115], v206, s[72:73] offset:-2048
	global_load_dwordx4 v[116:119], v206, s[72:73]
	global_load_dwordx4 v[120:123], v206, s[72:73] offset:2048
	global_load_dwordx4 v[124:127], v207, s[72:73] offset:-2048
	global_load_dwordx4 v[128:131], v207, s[72:73]
	global_load_dwordx4 v[132:135], v207, s[72:73] offset:2048
	v_mul_f32_e32 v160, v0, v208
	v_mul_f32_e32 v161, v1, v209
	v_mul_f32_e32 v162, v2, v210
	v_mul_f32_e32 v163, v3, v211
	v_mul_f32_e32 v164, v4, v212
	v_mul_f32_e32 v165, v5, v213
	v_mul_f32_e32 v166, v6, v214
	v_mul_f32_e32 v167, v7, v215
	v_mul_f32_e32 v200, v160, v160
	v_fmac_f32_e32 v200, v161, v161
	v_fmac_f32_e32 v200, v162, v162
	v_fmac_f32_e32 v200, v163, v163
	v_fmac_f32_e32 v200, v164, v164
	v_fmac_f32_e32 v200, v165, v165
	v_fmac_f32_e32 v200, v166, v166
	v_fmac_f32_e32 v200, v167, v167
	s_waitcnt lgkmcnt(0)
	v_add_f32_e32 v192, -1.0, v184
	v_fma_f32 v192, v8, v192, 1.0
	v_mul_f32_e32 v176, v208, v192
	v_add_f32_dpp v200, v200, v200 quad_perm:[1,0,3,2] row_mask:0xf bank_mask:0xf bound_ctrl:1
	v_add_f32_e32 v192, -1.0, v185
	v_fma_f32 v192, v9, v192, 1.0
	v_mul_f32_e32 v177, v209, v192
	v_add_f32_dpp v200, v200, v200 quad_perm:[2,3,0,1] row_mask:0xf bank_mask:0xf bound_ctrl:1
	v_add_f32_e32 v192, -1.0, v186
	v_fma_f32 v192, v10, v192, 1.0
	v_mul_f32_e32 v178, v210, v192
	v_add_f32_dpp v200, v200, v200 row_half_mirror row_mask:0xf bank_mask:0xf bound_ctrl:1
	v_add_f32_e32 v192, -1.0, v187
	v_fma_f32 v192, v11, v192, 1.0
	v_mul_f32_e32 v179, v211, v192
	v_add_f32_e32 v192, -1.0, v188
	v_fma_f32 v192, v12, v192, 1.0
	v_mul_f32_e32 v180, v212, v192
	v_add_f32_e32 v192, -1.0, v189
	v_fma_f32 v192, v13, v192, 1.0
	v_mul_f32_e32 v181, v213, v192
	v_add_f32_e32 v192, -1.0, v190
	v_fma_f32 v192, v14, v192, 1.0
	v_mul_f32_e32 v182, v214, v192
	v_add_f32_e32 v192, -1.0, v191
	v_fma_f32 v192, v15, v192, 1.0
	v_mul_f32_e32 v183, v215, v192
	v_max_f32_e32 v200, v200, v200
	v_max_f32_e32 v200, 0x179abe15, v200
	v_rsq_f32_e32 v201, v200
	v_mul_f32_e32 v192, v136, v176
	v_mul_f32_e32 v202, v16, v192
	v_mul_f32_e32 v160, v160, v201
	v_mul_f32_e32 v161, v161, v201
	v_mul_f32_e32 v162, v162, v201
	v_mul_f32_e32 v163, v163, v201
	v_mul_f32_e32 v164, v164, v201
	v_mul_f32_e32 v165, v165, v201
	v_mul_f32_e32 v166, v166, v201
	v_mul_f32_e32 v167, v167, v201
	v_mul_f32_e32 v168, v184, v160
	v_mul_f32_e32 v169, v185, v161
	v_mul_f32_e32 v170, v186, v162
	v_mul_f32_e32 v171, v187, v163
	v_mul_f32_e32 v172, v188, v164
	v_mul_f32_e32 v173, v189, v165
	v_mul_f32_e32 v174, v190, v166
	v_mul_f32_e32 v175, v191, v167
	ds_write_b128 v54, v[160:163] offset:20480
	ds_write_b128 v54, v[164:167] offset:20496
	ds_write_b128 v54, v[168:171] offset:20736
	ds_write_b128 v54, v[172:175] offset:20752
	ds_write_b128 v54, v[176:179] offset:20992
	ds_write_b128 v54, v[180:183] offset:21008
	ds_write_b128 v54, v[136:139] offset:21248
	ds_write_b128 v54, v[140:143] offset:21264
	ds_write_b128 v54, v[152:155] offset:21504
	ds_write_b128 v54, v[156:159] offset:21520
	v_mul_f32_e32 v192, v137, v177
	v_fmac_f32_e32 v202, v17, v192
	v_mul_f32_e32 v192, v138, v178
	v_fmac_f32_e32 v202, v18, v192
	v_mul_f32_e32 v192, v139, v179
	v_fmac_f32_e32 v202, v19, v192
	v_mul_f32_e32 v192, v140, v180
	v_fmac_f32_e32 v202, v20, v192
	v_mul_f32_e32 v192, v141, v181
	v_fmac_f32_e32 v202, v21, v192
	v_mul_f32_e32 v192, v142, v182
	v_fmac_f32_e32 v202, v22, v192
	v_mul_f32_e32 v192, v143, v183
	v_fmac_f32_e32 v202, v23, v192
	s_nop 1
	v_add_f32_dpp v202, v202, v202 quad_perm:[1,0,3,2] row_mask:0xf bank_mask:0xf bound_ctrl:1
	s_nop 1
	v_add_f32_dpp v202, v202, v202 quad_perm:[2,3,0,1] row_mask:0xf bank_mask:0xf bound_ctrl:1
	s_nop 1
	v_add_f32_dpp v202, v202, v202 row_half_mirror row_mask:0xf bank_mask:0xf bound_ctrl:1
	v_add_u32_e32 v205, s90, v56
	v_lshl_add_u32 v205, v205, 7, s64
	s_and_saveexec_b64 s[56:57], s[8:9]
	global_store_dword v205, v202, s[24:25]
	s_or_b64 exec, exec, s[56:57]
	v_add_u32_e32 v56, v59, v56
	s_waitcnt lgkmcnt(0)
	s_barrier
.Lmy_ks_loop:
	ds_read_b128 v[184:187], v55 offset:0
	ds_read_b128 v[188:191], v55 offset:16
	s_waitcnt vmcnt(9)
	v_lshlrev_b32_e32 v136, 16, v64
	v_lshlrev_b32_e32 v192, 16, v76
	v_lshlrev_b32_e32 v193, 16, v88
	v_add_f32_e32 v193, v193, v192
	v_fma_f32 v192, v193, 0.5, -v136
	v_fmac_f32_e32 v136, v24, v192
	v_and_b32_e32 v137, 0xffff0000, v64
	v_and_b32_e32 v192, 0xffff0000, v76
	v_and_b32_e32 v193, 0xffff0000, v88
	v_add_f32_e32 v193, v193, v192
	v_fma_f32 v192, v193, 0.5, -v137
	v_fmac_f32_e32 v137, v25, v192
	v_lshlrev_b32_e32 v138, 16, v65
	v_lshlrev_b32_e32 v192, 16, v77
	v_lshlrev_b32_e32 v193, 16, v89
	v_add_f32_e32 v193, v193, v192
	v_fma_f32 v192, v193, 0.5, -v138
	v_fmac_f32_e32 v138, v26, v192
	v_and_b32_e32 v139, 0xffff0000, v65
	v_and_b32_e32 v192, 0xffff0000, v77
	v_and_b32_e32 v193, 0xffff0000, v89
	v_add_f32_e32 v193, v193, v192
	v_fma_f32 v192, v193, 0.5, -v139
	v_fmac_f32_e32 v139, v27, v192
	v_lshlrev_b32_e32 v140, 16, v66
	v_lshlrev_b32_e32 v192, 16, v78
	v_lshlrev_b32_e32 v193, 16, v90
	v_add_f32_e32 v193, v193, v192
	v_fma_f32 v192, v193, 0.5, -v140
	v_fmac_f32_e32 v140, v28, v192
	v_and_b32_e32 v141, 0xffff0000, v66
	v_and_b32_e32 v192, 0xffff0000, v78
	v_and_b32_e32 v193, 0xffff0000, v90
	v_add_f32_e32 v193, v193, v192
	v_fma_f32 v192, v193, 0.5, -v141
	v_fmac_f32_e32 v141, v29, v192
	v_lshlrev_b32_e32 v142, 16, v67
	v_lshlrev_b32_e32 v192, 16, v79
	v_lshlrev_b32_e32 v193, 16, v91
	v_add_f32_e32 v193, v193, v192
	v_fma_f32 v192, v193, 0.5, -v142
	v_fmac_f32_e32 v142, v30, v192
	v_and_b32_e32 v143, 0xffff0000, v67
	v_and_b32_e32 v192, 0xffff0000, v79
	v_and_b32_e32 v193, 0xffff0000, v91
	v_add_f32_e32 v193, v193, v192
	v_fma_f32 v192, v193, 0.5, -v143
	v_fmac_f32_e32 v143, v31, v192
	v_lshlrev_b32_e32 v208, 16, v68
	v_lshlrev_b32_e32 v192, 16, v80
	v_lshlrev_b32_e32 v193, 16, v92
	v_add_f32_e32 v193, v193, v192
	v_fma_f32 v192, v193, 0.5, -v208
	v_fmac_f32_e32 v208, v32, v192
	v_and_b32_e32 v209, 0xffff0000, v68
	v_and_b32_e32 v192, 0xffff0000, v80
	v_and_b32_e32 v193, 0xffff0000, v92
	v_add_f32_e32 v193, v193, v192
	v_fma_f32 v192, v193, 0.5, -v209
	v_fmac_f32_e32 v209, v33, v192
	v_lshlrev_b32_e32 v210, 16, v69
	v_lshlrev_b32_e32 v192, 16, v81
	v_lshlrev_b32_e32 v193, 16, v93
	v_add_f32_e32 v193, v193, v192
	v_fma_f32 v192, v193, 0.5, -v210
	v_fmac_f32_e32 v210, v34, v192
	v_and_b32_e32 v211, 0xffff0000, v69
	v_and_b32_e32 v192, 0xffff0000, v81
	v_and_b32_e32 v193, 0xffff0000, v93
	v_add_f32_e32 v193, v193, v192
	v_fma_f32 v192, v193, 0.5, -v211
	v_fmac_f32_e32 v211, v35, v192
	v_lshlrev_b32_e32 v212, 16, v70
	v_lshlrev_b32_e32 v192, 16, v82
	v_lshlrev_b32_e32 v193, 16, v94
	v_add_f32_e32 v193, v193, v192
	v_fma_f32 v192, v193, 0.5, -v212
	v_fmac_f32_e32 v212, v36, v192
	v_and_b32_e32 v213, 0xffff0000, v70
	v_and_b32_e32 v192, 0xffff0000, v82
	v_and_b32_e32 v193, 0xffff0000, v94
	v_add_f32_e32 v193, v193, v192
	v_fma_f32 v192, v193, 0.5, -v213
	v_fmac_f32_e32 v213, v37, v192
	v_lshlrev_b32_e32 v214, 16, v71
	v_lshlrev_b32_e32 v192, 16, v83
	v_lshlrev_b32_e32 v193, 16, v95
	v_add_f32_e32 v193, v193, v192
	v_fma_f32 v192, v193, 0.5, -v214
	v_fmac_f32_e32 v214, v38, v192
	v_and_b32_e32 v215, 0xffff0000, v71
	v_and_b32_e32 v192, 0xffff0000, v83
	v_and_b32_e32 v193, 0xffff0000, v95
	v_add_f32_e32 v193, v193, v192
	v_fma_f32 v192, v193, 0.5, -v215
	v_fmac_f32_e32 v215, v39, v192
	v_lshlrev_b32_e32 v152, 16, v72
	v_lshlrev_b32_e32 v192, 16, v84
	v_lshlrev_b32_e32 v193, 16, v96
	v_add_f32_e32 v193, v193, v192
	v_fma_f32 v192, v193, 0.5, -v152
	v_fmac_f32_e32 v152, v40, v192
	v_and_b32_e32 v153, 0xffff0000, v72
	v_and_b32_e32 v192, 0xffff0000, v84
	v_and_b32_e32 v193, 0xffff0000, v96
	v_add_f32_e32 v193, v193, v192
	v_fma_f32 v192, v193, 0.5, -v153
	v_fmac_f32_e32 v153, v41, v192
	v_lshlrev_b32_e32 v154, 16, v73
	v_lshlrev_b32_e32 v192, 16, v85
	v_lshlrev_b32_e32 v193, 16, v97
	v_add_f32_e32 v193, v193, v192
	v_fma_f32 v192, v193, 0.5, -v154
	v_fmac_f32_e32 v154, v42, v192
	v_and_b32_e32 v155, 0xffff0000, v73
	v_and_b32_e32 v192, 0xffff0000, v85
	v_and_b32_e32 v193, 0xffff0000, v97
	v_add_f32_e32 v193, v193, v192
	v_fma_f32 v192, v193, 0.5, -v155
	v_fmac_f32_e32 v155, v43, v192
	v_lshlrev_b32_e32 v156, 16, v74
	v_lshlrev_b32_e32 v192, 16, v86
	v_lshlrev_b32_e32 v193, 16, v98
	v_add_f32_e32 v193, v193, v192
	v_fma_f32 v192, v193, 0.5, -v156
	v_fmac_f32_e32 v156, v44, v192
	v_and_b32_e32 v157, 0xffff0000, v74
	v_and_b32_e32 v192, 0xffff0000, v86
	v_and_b32_e32 v193, 0xffff0000, v98
	v_add_f32_e32 v193, v193, v192
	v_fma_f32 v192, v193, 0.5, -v157
	v_fmac_f32_e32 v157, v45, v192
	v_lshlrev_b32_e32 v158, 16, v75
	v_lshlrev_b32_e32 v192, 16, v87
	v_lshlrev_b32_e32 v193, 16, v99
	v_add_f32_e32 v193, v193, v192
	v_fma_f32 v192, v193, 0.5, -v158
	v_fmac_f32_e32 v158, v46, v192
	v_and_b32_e32 v159, 0xffff0000, v75
	v_and_b32_e32 v192, 0xffff0000, v87
	v_and_b32_e32 v193, 0xffff0000, v99
	v_add_f32_e32 v193, v193, v192
	v_fma_f32 v192, v193, 0.5, -v159
	v_fmac_f32_e32 v159, v47, v192
	v_add_u32_e32 v57, v59, v56
	v_add_u32_e32 v57, v59, v57
	v_cmp_lt_i32_e64 s[4:5], 0, v57
	v_cmp_gt_i32_e64 s[58:59], v58, v57
	v_mad_u32_u24 v205, v57, v53, v52
	s_nop 0
	v_cndmask_b32_e64 v206, 0, v53, s[4:5]
	v_cndmask_b32_e64 v207, 0, v53, s[58:59]
	v_cndmask_b32_e64 v60, 0, 1.0, s[4:5]
	v_cndmask_b32_e64 v61, 0, 1.0, s[58:59]
	v_sub_u32_e32 v206, v205, v206
	v_add_u32_e32 v207, v205, v207
	global_load_dwordx4 v[64:67], v205, s[72:73] offset:-2048
	global_load_dwordx4 v[68:71], v205, s[72:73]
	global_load_dwordx4 v[72:75], v205, s[72:73] offset:2048
	global_load_dwordx4 v[76:79], v206, s[72:73] offset:-2048
	global_load_dwordx4 v[80:83], v206, s[72:73]
	global_load_dwordx4 v[84:87], v206, s[72:73] offset:2048
	global_load_dwordx4 v[88:91], v207, s[72:73] offset:-2048
	global_load_dwordx4 v[92:95], v207, s[72:73]
	global_load_dwordx4 v[96:99], v207, s[72:73] offset:2048
	v_mul_f32_e32 v160, v0, v208
	v_mul_f32_e32 v161, v1, v209
	v_mul_f32_e32 v162, v2, v210
	v_mul_f32_e32 v163, v3, v211
	v_mul_f32_e32 v164, v4, v212
	v_mul_f32_e32 v165, v5, v213
	v_mul_f32_e32 v166, v6, v214
	v_mul_f32_e32 v167, v7, v215
	v_mul_f32_e32 v200, v160, v160
	v_fmac_f32_e32 v200, v161, v161
	v_fmac_f32_e32 v200, v162, v162
	v_fmac_f32_e32 v200, v163, v163
	v_fmac_f32_e32 v200, v164, v164
	v_fmac_f32_e32 v200, v165, v165
	v_fmac_f32_e32 v200, v166, v166
	v_fmac_f32_e32 v200, v167, v167
	s_waitcnt lgkmcnt(0)
	v_add_f32_e32 v192, -1.0, v184
	v_fma_f32 v192, v8, v192, 1.0
	v_mul_f32_e32 v176, v208, v192
	v_add_f32_dpp v200, v200, v200 quad_perm:[1,0,3,2] row_mask:0xf bank_mask:0xf bound_ctrl:1
	v_add_f32_e32 v192, -1.0, v185
	v_fma_f32 v192, v9, v192, 1.0
	v_mul_f32_e32 v177, v209, v192
	v_add_f32_dpp v200, v200, v200 quad_perm:[2,3,0,1] row_mask:0xf bank_mask:0xf bound_ctrl:1
	v_add_f32_e32 v192, -1.0, v186
	v_fma_f32 v192, v10, v192, 1.0
	v_mul_f32_e32 v178, v210, v192
	v_add_f32_dpp v200, v200, v200 row_half_mirror row_mask:0xf bank_mask:0xf bound_ctrl:1
	v_add_f32_e32 v192, -1.0, v187
	v_fma_f32 v192, v11, v192, 1.0
	v_mul_f32_e32 v179, v211, v192
	v_add_f32_e32 v192, -1.0, v188
	v_fma_f32 v192, v12, v192, 1.0
	v_mul_f32_e32 v180, v212, v192
	v_add_f32_e32 v192, -1.0, v189
	v_fma_f32 v192, v13, v192, 1.0
	v_mul_f32_e32 v181, v213, v192
	v_add_f32_e32 v192, -1.0, v190
	v_fma_f32 v192, v14, v192, 1.0
	v_mul_f32_e32 v182, v214, v192
	v_add_f32_e32 v192, -1.0, v191
	v_fma_f32 v192, v15, v192, 1.0
	v_mul_f32_e32 v183, v215, v192
	v_max_f32_e32 v200, v200, v200
	v_max_f32_e32 v200, 0x179abe15, v200
	v_rsq_f32_e32 v201, v200
	v_mul_f32_e32 v192, v136, v176
	v_mul_f32_e32 v202, v16, v192
	v_mul_f32_e32 v160, v160, v201
	v_mul_f32_e32 v161, v161, v201
	v_mul_f32_e32 v162, v162, v201
	v_mul_f32_e32 v163, v163, v201
	v_mul_f32_e32 v164, v164, v201
	v_mul_f32_e32 v165, v165, v201
	v_mul_f32_e32 v166, v166, v201
	v_mul_f32_e32 v167, v167, v201
	v_mul_f32_e32 v168, v184, v160
	v_mul_f32_e32 v169, v185, v161
	v_mul_f32_e32 v170, v186, v162
	v_mul_f32_e32 v171, v187, v163
	v_mul_f32_e32 v172, v188, v164
	v_mul_f32_e32 v173, v189, v165
	v_mul_f32_e32 v174, v190, v166
	v_mul_f32_e32 v175, v191, v167
	ds_write_b128 v54, v[160:163] offset:0
	ds_write_b128 v54, v[164:167] offset:16
	ds_write_b128 v54, v[168:171] offset:256
	ds_write_b128 v54, v[172:175] offset:272
	ds_write_b128 v54, v[176:179] offset:512
	ds_write_b128 v54, v[180:183] offset:528
	ds_write_b128 v54, v[136:139] offset:768
	ds_write_b128 v54, v[140:143] offset:784
	ds_write_b128 v54, v[152:155] offset:1024
	ds_write_b128 v54, v[156:159] offset:1040
	v_mul_f32_e32 v192, v137, v177
	v_fmac_f32_e32 v202, v17, v192
	v_mul_f32_e32 v192, v138, v178
	v_fmac_f32_e32 v202, v18, v192
	v_mul_f32_e32 v192, v139, v179
	v_fmac_f32_e32 v202, v19, v192
	v_mul_f32_e32 v192, v140, v180
	v_fmac_f32_e32 v202, v20, v192
	v_mul_f32_e32 v192, v141, v181
	v_fmac_f32_e32 v202, v21, v192
	v_mul_f32_e32 v192, v142, v182
	v_fmac_f32_e32 v202, v22, v192
	v_mul_f32_e32 v192, v143, v183
	v_fmac_f32_e32 v202, v23, v192
	s_nop 1
	v_add_f32_dpp v202, v202, v202 quad_perm:[1,0,3,2] row_mask:0xf bank_mask:0xf bound_ctrl:1
	s_nop 1
	v_add_f32_dpp v202, v202, v202 quad_perm:[2,3,0,1] row_mask:0xf bank_mask:0xf bound_ctrl:1
	s_nop 1
	v_add_f32_dpp v202, v202, v202 row_half_mirror row_mask:0xf bank_mask:0xf bound_ctrl:1
	v_add_u32_e32 v205, s90, v56
	v_lshl_add_u32 v205, v205, 7, s64
	s_and_saveexec_b64 s[56:57], s[8:9]
	global_store_dword v205, v202, s[24:25]
	s_or_b64 exec, exec, s[56:57]
	v_add_u32_e32 v56, v59, v56
	s_waitcnt lgkmcnt(0)
	s_barrier
	ds_read_b128 v[184:187], v55 offset:4096
	ds_read_b128 v[188:191], v55 offset:4112
	s_waitcnt vmcnt(9)
	v_lshlrev_b32_e32 v136, 16, v100
	v_lshlrev_b32_e32 v192, 16, v112
	v_lshlrev_b32_e32 v193, 16, v124
	v_add_f32_e32 v193, v193, v192
	v_fma_f32 v192, v193, 0.5, -v136
	v_fmac_f32_e32 v136, v24, v192
	v_and_b32_e32 v137, 0xffff0000, v100
	v_and_b32_e32 v192, 0xffff0000, v112
	v_and_b32_e32 v193, 0xffff0000, v124
	v_add_f32_e32 v193, v193, v192
	v_fma_f32 v192, v193, 0.5, -v137
	v_fmac_f32_e32 v137, v25, v192
	v_lshlrev_b32_e32 v138, 16, v101
	v_lshlrev_b32_e32 v192, 16, v113
	v_lshlrev_b32_e32 v193, 16, v125
	v_add_f32_e32 v193, v193, v192
	v_fma_f32 v192, v193, 0.5, -v138
	v_fmac_f32_e32 v138, v26, v192
	v_and_b32_e32 v139, 0xffff0000, v101
	v_and_b32_e32 v192, 0xffff0000, v113
	v_and_b32_e32 v193, 0xffff0000, v125
	v_add_f32_e32 v193, v193, v192
	v_fma_f32 v192, v193, 0.5, -v139
	v_fmac_f32_e32 v139, v27, v192
	v_lshlrev_b32_e32 v140, 16, v102
	v_lshlrev_b32_e32 v192, 16, v114
	v_lshlrev_b32_e32 v193, 16, v126
	v_add_f32_e32 v193, v193, v192
	v_fma_f32 v192, v193, 0.5, -v140
	v_fmac_f32_e32 v140, v28, v192
	v_and_b32_e32 v141, 0xffff0000, v102
	v_and_b32_e32 v192, 0xffff0000, v114
	v_and_b32_e32 v193, 0xffff0000, v126
	v_add_f32_e32 v193, v193, v192
	v_fma_f32 v192, v193, 0.5, -v141
	v_fmac_f32_e32 v141, v29, v192
	v_lshlrev_b32_e32 v142, 16, v103
	v_lshlrev_b32_e32 v192, 16, v115
	v_lshlrev_b32_e32 v193, 16, v127
	v_add_f32_e32 v193, v193, v192
	v_fma_f32 v192, v193, 0.5, -v142
	v_fmac_f32_e32 v142, v30, v192
	v_and_b32_e32 v143, 0xffff0000, v103
	v_and_b32_e32 v192, 0xffff0000, v115
	v_and_b32_e32 v193, 0xffff0000, v127
	v_add_f32_e32 v193, v193, v192
	v_fma_f32 v192, v193, 0.5, -v143
	v_fmac_f32_e32 v143, v31, v192
	v_lshlrev_b32_e32 v208, 16, v104
	v_lshlrev_b32_e32 v192, 16, v116
	v_lshlrev_b32_e32 v193, 16, v128
	v_add_f32_e32 v193, v193, v192
	v_fma_f32 v192, v193, 0.5, -v208
	v_fmac_f32_e32 v208, v32, v192
	v_and_b32_e32 v209, 0xffff0000, v104
	v_and_b32_e32 v192, 0xffff0000, v116
	v_and_b32_e32 v193, 0xffff0000, v128
	v_add_f32_e32 v193, v193, v192
	v_fma_f32 v192, v193, 0.5, -v209
	v_fmac_f32_e32 v209, v33, v192
	v_lshlrev_b32_e32 v210, 16, v105
	v_lshlrev_b32_e32 v192, 16, v117
	v_lshlrev_b32_e32 v193, 16, v129
	v_add_f32_e32 v193, v193, v192
	v_fma_f32 v192, v193, 0.5, -v210
	v_fmac_f32_e32 v210, v34, v192
	v_and_b32_e32 v211, 0xffff0000, v105
	v_and_b32_e32 v192, 0xffff0000, v117
	v_and_b32_e32 v193, 0xffff0000, v129
	v_add_f32_e32 v193, v193, v192
	v_fma_f32 v192, v193, 0.5, -v211
	v_fmac_f32_e32 v211, v35, v192
	v_lshlrev_b32_e32 v212, 16, v106
	v_lshlrev_b32_e32 v192, 16, v118
	v_lshlrev_b32_e32 v193, 16, v130
	v_add_f32_e32 v193, v193, v192
	v_fma_f32 v192, v193, 0.5, -v212
	v_fmac_f32_e32 v212, v36, v192
	v_and_b32_e32 v213, 0xffff0000, v106
	v_and_b32_e32 v192, 0xffff0000, v118
	v_and_b32_e32 v193, 0xffff0000, v130
	v_add_f32_e32 v193, v193, v192
	v_fma_f32 v192, v193, 0.5, -v213
	v_fmac_f32_e32 v213, v37, v192
	v_lshlrev_b32_e32 v214, 16, v107
	v_lshlrev_b32_e32 v192, 16, v119
	v_lshlrev_b32_e32 v193, 16, v131
	v_add_f32_e32 v193, v193, v192
	v_fma_f32 v192, v193, 0.5, -v214
	v_fmac_f32_e32 v214, v38, v192
	v_and_b32_e32 v215, 0xffff0000, v107
	v_and_b32_e32 v192, 0xffff0000, v119
	v_and_b32_e32 v193, 0xffff0000, v131
	v_add_f32_e32 v193, v193, v192
	v_fma_f32 v192, v193, 0.5, -v215
	v_fmac_f32_e32 v215, v39, v192
	v_lshlrev_b32_e32 v152, 16, v108
	v_lshlrev_b32_e32 v192, 16, v120
	v_lshlrev_b32_e32 v193, 16, v132
	v_add_f32_e32 v193, v193, v192
	v_fma_f32 v192, v193, 0.5, -v152
	v_fmac_f32_e32 v152, v40, v192
	v_and_b32_e32 v153, 0xffff0000, v108
	v_and_b32_e32 v192, 0xffff0000, v120
	v_and_b32_e32 v193, 0xffff0000, v132
	v_add_f32_e32 v193, v193, v192
	v_fma_f32 v192, v193, 0.5, -v153
	v_fmac_f32_e32 v153, v41, v192
	v_lshlrev_b32_e32 v154, 16, v109
	v_lshlrev_b32_e32 v192, 16, v121
	v_lshlrev_b32_e32 v193, 16, v133
	v_add_f32_e32 v193, v193, v192
	v_fma_f32 v192, v193, 0.5, -v154
	v_fmac_f32_e32 v154, v42, v192
	v_and_b32_e32 v155, 0xffff0000, v109
	v_and_b32_e32 v192, 0xffff0000, v121
	v_and_b32_e32 v193, 0xffff0000, v133
	v_add_f32_e32 v193, v193, v192
	v_fma_f32 v192, v193, 0.5, -v155
	v_fmac_f32_e32 v155, v43, v192
	v_lshlrev_b32_e32 v156, 16, v110
	v_lshlrev_b32_e32 v192, 16, v122
	v_lshlrev_b32_e32 v193, 16, v134
	v_add_f32_e32 v193, v193, v192
	v_fma_f32 v192, v193, 0.5, -v156
	v_fmac_f32_e32 v156, v44, v192
	v_and_b32_e32 v157, 0xffff0000, v110
	v_and_b32_e32 v192, 0xffff0000, v122
	v_and_b32_e32 v193, 0xffff0000, v134
	v_add_f32_e32 v193, v193, v192
	v_fma_f32 v192, v193, 0.5, -v157
	v_fmac_f32_e32 v157, v45, v192
	v_lshlrev_b32_e32 v158, 16, v111
	v_lshlrev_b32_e32 v192, 16, v123
	v_lshlrev_b32_e32 v193, 16, v135
	v_add_f32_e32 v193, v193, v192
	v_fma_f32 v192, v193, 0.5, -v158
	v_fmac_f32_e32 v158, v46, v192
	v_and_b32_e32 v159, 0xffff0000, v111
	v_and_b32_e32 v192, 0xffff0000, v123
	v_and_b32_e32 v193, 0xffff0000, v135
	v_add_f32_e32 v193, v193, v192
	v_fma_f32 v192, v193, 0.5, -v159
	v_fmac_f32_e32 v159, v47, v192
	v_add_u32_e32 v57, v59, v56
	v_add_u32_e32 v57, v59, v57
	v_cmp_lt_i32_e64 s[4:5], 0, v57
	v_cmp_gt_i32_e64 s[58:59], v58, v57
	v_mad_u32_u24 v205, v57, v53, v52
	s_nop 0
	v_cndmask_b32_e64 v206, 0, v53, s[4:5]
	v_cndmask_b32_e64 v207, 0, v53, s[58:59]
	v_cndmask_b32_e64 v62, 0, 1.0, s[4:5]
	v_cndmask_b32_e64 v63, 0, 1.0, s[58:59]
	v_sub_u32_e32 v206, v205, v206
	v_add_u32_e32 v207, v205, v207
	global_load_dwordx4 v[100:103], v205, s[72:73] offset:-2048
	global_load_dwordx4 v[104:107], v205, s[72:73]
	global_load_dwordx4 v[108:111], v205, s[72:73] offset:2048
	global_load_dwordx4 v[112:115], v206, s[72:73] offset:-2048
	global_load_dwordx4 v[116:119], v206, s[72:73]
	global_load_dwordx4 v[120:123], v206, s[72:73] offset:2048
	global_load_dwordx4 v[124:127], v207, s[72:73] offset:-2048
	global_load_dwordx4 v[128:131], v207, s[72:73]
	global_load_dwordx4 v[132:135], v207, s[72:73] offset:2048
	v_mul_f32_e32 v160, v0, v208
	v_mul_f32_e32 v161, v1, v209
	v_mul_f32_e32 v162, v2, v210
	v_mul_f32_e32 v163, v3, v211
	v_mul_f32_e32 v164, v4, v212
	v_mul_f32_e32 v165, v5, v213
	v_mul_f32_e32 v166, v6, v214
	v_mul_f32_e32 v167, v7, v215
	v_mul_f32_e32 v200, v160, v160
	v_fmac_f32_e32 v200, v161, v161
	v_fmac_f32_e32 v200, v162, v162
	v_fmac_f32_e32 v200, v163, v163
	v_fmac_f32_e32 v200, v164, v164
	v_fmac_f32_e32 v200, v165, v165
	v_fmac_f32_e32 v200, v166, v166
	v_fmac_f32_e32 v200, v167, v167
	s_waitcnt lgkmcnt(0)
	v_add_f32_e32 v192, -1.0, v184
	v_fma_f32 v192, v8, v192, 1.0
	v_mul_f32_e32 v176, v208, v192
	v_add_f32_dpp v200, v200, v200 quad_perm:[1,0,3,2] row_mask:0xf bank_mask:0xf bound_ctrl:1
	v_add_f32_e32 v192, -1.0, v185
	v_fma_f32 v192, v9, v192, 1.0
	v_mul_f32_e32 v177, v209, v192
	v_add_f32_dpp v200, v200, v200 quad_perm:[2,3,0,1] row_mask:0xf bank_mask:0xf bound_ctrl:1
	v_add_f32_e32 v192, -1.0, v186
	v_fma_f32 v192, v10, v192, 1.0
	v_mul_f32_e32 v178, v210, v192
	v_add_f32_dpp v200, v200, v200 row_half_mirror row_mask:0xf bank_mask:0xf bound_ctrl:1
	v_add_f32_e32 v192, -1.0, v187
	v_fma_f32 v192, v11, v192, 1.0
	v_mul_f32_e32 v179, v211, v192
	v_add_f32_e32 v192, -1.0, v188
	v_fma_f32 v192, v12, v192, 1.0
	v_mul_f32_e32 v180, v212, v192
	v_add_f32_e32 v192, -1.0, v189
	v_fma_f32 v192, v13, v192, 1.0
	v_mul_f32_e32 v181, v213, v192
	v_add_f32_e32 v192, -1.0, v190
	v_fma_f32 v192, v14, v192, 1.0
	v_mul_f32_e32 v182, v214, v192
	v_add_f32_e32 v192, -1.0, v191
	v_fma_f32 v192, v15, v192, 1.0
	v_mul_f32_e32 v183, v215, v192
	v_max_f32_e32 v200, v200, v200
	v_max_f32_e32 v200, 0x179abe15, v200
	v_rsq_f32_e32 v201, v200
	v_mul_f32_e32 v192, v136, v176
	v_mul_f32_e32 v202, v16, v192
	v_mul_f32_e32 v160, v160, v201
	v_mul_f32_e32 v161, v161, v201
	v_mul_f32_e32 v162, v162, v201
	v_mul_f32_e32 v163, v163, v201
	v_mul_f32_e32 v164, v164, v201
	v_mul_f32_e32 v165, v165, v201
	v_mul_f32_e32 v166, v166, v201
	v_mul_f32_e32 v167, v167, v201
	v_mul_f32_e32 v168, v184, v160
	v_mul_f32_e32 v169, v185, v161
	v_mul_f32_e32 v170, v186, v162
	v_mul_f32_e32 v171, v187, v163
	v_mul_f32_e32 v172, v188, v164
	v_mul_f32_e32 v173, v189, v165
	v_mul_f32_e32 v174, v190, v166
	v_mul_f32_e32 v175, v191, v167
	ds_write_b128 v54, v[160:163] offset:20480
	ds_write_b128 v54, v[164:167] offset:20496
	ds_write_b128 v54, v[168:171] offset:20736
	ds_write_b128 v54, v[172:175] offset:20752
	ds_write_b128 v54, v[176:179] offset:20992
	ds_write_b128 v54, v[180:183] offset:21008
	ds_write_b128 v54, v[136:139] offset:21248
	ds_write_b128 v54, v[140:143] offset:21264
	ds_write_b128 v54, v[152:155] offset:21504
	ds_write_b128 v54, v[156:159] offset:21520
	v_mul_f32_e32 v192, v137, v177
	v_fmac_f32_e32 v202, v17, v192
	v_mul_f32_e32 v192, v138, v178
	v_fmac_f32_e32 v202, v18, v192
	v_mul_f32_e32 v192, v139, v179
	v_fmac_f32_e32 v202, v19, v192
	v_mul_f32_e32 v192, v140, v180
	v_fmac_f32_e32 v202, v20, v192
	v_mul_f32_e32 v192, v141, v181
	v_fmac_f32_e32 v202, v21, v192
	v_mul_f32_e32 v192, v142, v182
	v_fmac_f32_e32 v202, v22, v192
	v_mul_f32_e32 v192, v143, v183
	v_fmac_f32_e32 v202, v23, v192
	s_nop 1
	v_add_f32_dpp v202, v202, v202 quad_perm:[1,0,3,2] row_mask:0xf bank_mask:0xf bound_ctrl:1
	s_nop 1
	v_add_f32_dpp v202, v202, v202 quad_perm:[2,3,0,1] row_mask:0xf bank_mask:0xf bound_ctrl:1
	s_nop 1
	v_add_f32_dpp v202, v202, v202 row_half_mirror row_mask:0xf bank_mask:0xf bound_ctrl:1
	v_add_u32_e32 v205, s90, v56
	v_lshl_add_u32 v205, v205, 7, s64
	s_and_saveexec_b64 s[56:57], s[8:9]
	global_store_dword v205, v202, s[24:25]
	s_or_b64 exec, exec, s[56:57]
	v_add_u32_e32 v56, v59, v56
	s_waitcnt lgkmcnt(0)
	s_barrier
	s_add_i32 s10, s10, 2
	s_cmp_lt_u32 s10, 127
	s_cbranch_scc1 .Lmy_ks_loop
	ds_read_b128 v[184:187], v55 offset:0
	ds_read_b128 v[188:191], v55 offset:16
	s_waitcnt vmcnt(9)
	v_lshlrev_b32_e32 v136, 16, v64
	v_lshlrev_b32_e32 v192, 16, v76
	v_lshlrev_b32_e32 v193, 16, v88
	v_mul_f32_e32 v193, v61, v193
	v_fmac_f32_e32 v193, v60, v192
	v_fma_f32 v192, v193, 0.5, -v136
	v_fmac_f32_e32 v136, v24, v192
	v_and_b32_e32 v137, 0xffff0000, v64
	v_and_b32_e32 v192, 0xffff0000, v76
	v_and_b32_e32 v193, 0xffff0000, v88
	v_mul_f32_e32 v193, v61, v193
	v_fmac_f32_e32 v193, v60, v192
	v_fma_f32 v192, v193, 0.5, -v137
	v_fmac_f32_e32 v137, v25, v192
	v_lshlrev_b32_e32 v138, 16, v65
	v_lshlrev_b32_e32 v192, 16, v77
	v_lshlrev_b32_e32 v193, 16, v89
	v_mul_f32_e32 v193, v61, v193
	v_fmac_f32_e32 v193, v60, v192
	v_fma_f32 v192, v193, 0.5, -v138
	v_fmac_f32_e32 v138, v26, v192
	v_and_b32_e32 v139, 0xffff0000, v65
	v_and_b32_e32 v192, 0xffff0000, v77
	v_and_b32_e32 v193, 0xffff0000, v89
	v_mul_f32_e32 v193, v61, v193
	v_fmac_f32_e32 v193, v60, v192
	v_fma_f32 v192, v193, 0.5, -v139
	v_fmac_f32_e32 v139, v27, v192
	v_lshlrev_b32_e32 v140, 16, v66
	v_lshlrev_b32_e32 v192, 16, v78
	v_lshlrev_b32_e32 v193, 16, v90
	v_mul_f32_e32 v193, v61, v193
	v_fmac_f32_e32 v193, v60, v192
	v_fma_f32 v192, v193, 0.5, -v140
	v_fmac_f32_e32 v140, v28, v192
	v_and_b32_e32 v141, 0xffff0000, v66
	v_and_b32_e32 v192, 0xffff0000, v78
	v_and_b32_e32 v193, 0xffff0000, v90
	v_mul_f32_e32 v193, v61, v193
	v_fmac_f32_e32 v193, v60, v192
	v_fma_f32 v192, v193, 0.5, -v141
	v_fmac_f32_e32 v141, v29, v192
	v_lshlrev_b32_e32 v142, 16, v67
	v_lshlrev_b32_e32 v192, 16, v79
	v_lshlrev_b32_e32 v193, 16, v91
	v_mul_f32_e32 v193, v61, v193
	v_fmac_f32_e32 v193, v60, v192
	v_fma_f32 v192, v193, 0.5, -v142
	v_fmac_f32_e32 v142, v30, v192
	v_and_b32_e32 v143, 0xffff0000, v67
	v_and_b32_e32 v192, 0xffff0000, v79
	v_and_b32_e32 v193, 0xffff0000, v91
	v_mul_f32_e32 v193, v61, v193
	v_fmac_f32_e32 v193, v60, v192
	v_fma_f32 v192, v193, 0.5, -v143
	v_fmac_f32_e32 v143, v31, v192
	v_lshlrev_b32_e32 v208, 16, v68
	v_lshlrev_b32_e32 v192, 16, v80
	v_lshlrev_b32_e32 v193, 16, v92
	v_mul_f32_e32 v193, v61, v193
	v_fmac_f32_e32 v193, v60, v192
	v_fma_f32 v192, v193, 0.5, -v208
	v_fmac_f32_e32 v208, v32, v192
	v_and_b32_e32 v209, 0xffff0000, v68
	v_and_b32_e32 v192, 0xffff0000, v80
	v_and_b32_e32 v193, 0xffff0000, v92
	v_mul_f32_e32 v193, v61, v193
	v_fmac_f32_e32 v193, v60, v192
	v_fma_f32 v192, v193, 0.5, -v209
	v_fmac_f32_e32 v209, v33, v192
	v_lshlrev_b32_e32 v210, 16, v69
	v_lshlrev_b32_e32 v192, 16, v81
	v_lshlrev_b32_e32 v193, 16, v93
	v_mul_f32_e32 v193, v61, v193
	v_fmac_f32_e32 v193, v60, v192
	v_fma_f32 v192, v193, 0.5, -v210
	v_fmac_f32_e32 v210, v34, v192
	v_and_b32_e32 v211, 0xffff0000, v69
	v_and_b32_e32 v192, 0xffff0000, v81
	v_and_b32_e32 v193, 0xffff0000, v93
	v_mul_f32_e32 v193, v61, v193
	v_fmac_f32_e32 v193, v60, v192
	v_fma_f32 v192, v193, 0.5, -v211
	v_fmac_f32_e32 v211, v35, v192
	v_lshlrev_b32_e32 v212, 16, v70
	v_lshlrev_b32_e32 v192, 16, v82
	v_lshlrev_b32_e32 v193, 16, v94
	v_mul_f32_e32 v193, v61, v193
	v_fmac_f32_e32 v193, v60, v192
	v_fma_f32 v192, v193, 0.5, -v212
	v_fmac_f32_e32 v212, v36, v192
	v_and_b32_e32 v213, 0xffff0000, v70
	v_and_b32_e32 v192, 0xffff0000, v82
	v_and_b32_e32 v193, 0xffff0000, v94
	v_mul_f32_e32 v193, v61, v193
	v_fmac_f32_e32 v193, v60, v192
	v_fma_f32 v192, v193, 0.5, -v213
	v_fmac_f32_e32 v213, v37, v192
	v_lshlrev_b32_e32 v214, 16, v71
	v_lshlrev_b32_e32 v192, 16, v83
	v_lshlrev_b32_e32 v193, 16, v95
	v_mul_f32_e32 v193, v61, v193
	v_fmac_f32_e32 v193, v60, v192
	v_fma_f32 v192, v193, 0.5, -v214
	v_fmac_f32_e32 v214, v38, v192
	v_and_b32_e32 v215, 0xffff0000, v71
	v_and_b32_e32 v192, 0xffff0000, v83
	v_and_b32_e32 v193, 0xffff0000, v95
	v_mul_f32_e32 v193, v61, v193
	v_fmac_f32_e32 v193, v60, v192
	v_fma_f32 v192, v193, 0.5, -v215
	v_fmac_f32_e32 v215, v39, v192
	v_lshlrev_b32_e32 v152, 16, v72
	v_lshlrev_b32_e32 v192, 16, v84
	v_lshlrev_b32_e32 v193, 16, v96
	v_mul_f32_e32 v193, v61, v193
	v_fmac_f32_e32 v193, v60, v192
	v_fma_f32 v192, v193, 0.5, -v152
	v_fmac_f32_e32 v152, v40, v192
	v_and_b32_e32 v153, 0xffff0000, v72
	v_and_b32_e32 v192, 0xffff0000, v84
	v_and_b32_e32 v193, 0xffff0000, v96
	v_mul_f32_e32 v193, v61, v193
	v_fmac_f32_e32 v193, v60, v192
	v_fma_f32 v192, v193, 0.5, -v153
	v_fmac_f32_e32 v153, v41, v192
	v_lshlrev_b32_e32 v154, 16, v73
	v_lshlrev_b32_e32 v192, 16, v85
	v_lshlrev_b32_e32 v193, 16, v97
	v_mul_f32_e32 v193, v61, v193
	v_fmac_f32_e32 v193, v60, v192
	v_fma_f32 v192, v193, 0.5, -v154
	v_fmac_f32_e32 v154, v42, v192
	v_and_b32_e32 v155, 0xffff0000, v73
	v_and_b32_e32 v192, 0xffff0000, v85
	v_and_b32_e32 v193, 0xffff0000, v97
	v_mul_f32_e32 v193, v61, v193
	v_fmac_f32_e32 v193, v60, v192
	v_fma_f32 v192, v193, 0.5, -v155
	v_fmac_f32_e32 v155, v43, v192
	v_lshlrev_b32_e32 v156, 16, v74
	v_lshlrev_b32_e32 v192, 16, v86
	v_lshlrev_b32_e32 v193, 16, v98
	v_mul_f32_e32 v193, v61, v193
	v_fmac_f32_e32 v193, v60, v192
	v_fma_f32 v192, v193, 0.5, -v156
	v_fmac_f32_e32 v156, v44, v192
	v_and_b32_e32 v157, 0xffff0000, v74
	v_and_b32_e32 v192, 0xffff0000, v86
	v_and_b32_e32 v193, 0xffff0000, v98
	v_mul_f32_e32 v193, v61, v193
	v_fmac_f32_e32 v193, v60, v192
	v_fma_f32 v192, v193, 0.5, -v157
	v_fmac_f32_e32 v157, v45, v192
	v_lshlrev_b32_e32 v158, 16, v75
	v_lshlrev_b32_e32 v192, 16, v87
	v_lshlrev_b32_e32 v193, 16, v99
	v_mul_f32_e32 v193, v61, v193
	v_fmac_f32_e32 v193, v60, v192
	v_fma_f32 v192, v193, 0.5, -v158
	v_fmac_f32_e32 v158, v46, v192
	v_and_b32_e32 v159, 0xffff0000, v75
	v_and_b32_e32 v192, 0xffff0000, v87
	v_and_b32_e32 v193, 0xffff0000, v99
	v_mul_f32_e32 v193, v61, v193
	v_fmac_f32_e32 v193, v60, v192
	v_fma_f32 v192, v193, 0.5, -v159
	v_fmac_f32_e32 v159, v47, v192
	v_mul_f32_e32 v160, v0, v208
	v_mul_f32_e32 v161, v1, v209
	v_mul_f32_e32 v162, v2, v210
	v_mul_f32_e32 v163, v3, v211
	v_mul_f32_e32 v164, v4, v212
	v_mul_f32_e32 v165, v5, v213
	v_mul_f32_e32 v166, v6, v214
	v_mul_f32_e32 v167, v7, v215
	v_mul_f32_e32 v200, v160, v160
	v_fmac_f32_e32 v200, v161, v161
	v_fmac_f32_e32 v200, v162, v162
	v_fmac_f32_e32 v200, v163, v163
	v_fmac_f32_e32 v200, v164, v164
	v_fmac_f32_e32 v200, v165, v165
	v_fmac_f32_e32 v200, v166, v166
	v_fmac_f32_e32 v200, v167, v167
	s_waitcnt lgkmcnt(0)
	v_add_f32_e32 v192, -1.0, v184
	v_fma_f32 v192, v8, v192, 1.0
	v_mul_f32_e32 v176, v208, v192
	v_add_f32_dpp v200, v200, v200 quad_perm:[1,0,3,2] row_mask:0xf bank_mask:0xf bound_ctrl:1
	v_add_f32_e32 v192, -1.0, v185
	v_fma_f32 v192, v9, v192, 1.0
	v_mul_f32_e32 v177, v209, v192
	v_add_f32_dpp v200, v200, v200 quad_perm:[2,3,0,1] row_mask:0xf bank_mask:0xf bound_ctrl:1
	v_add_f32_e32 v192, -1.0, v186
	v_fma_f32 v192, v10, v192, 1.0
	v_mul_f32_e32 v178, v210, v192
	v_add_f32_dpp v200, v200, v200 row_half_mirror row_mask:0xf bank_mask:0xf bound_ctrl:1
	v_add_f32_e32 v192, -1.0, v187
	v_fma_f32 v192, v11, v192, 1.0
	v_mul_f32_e32 v179, v211, v192
	v_add_f32_e32 v192, -1.0, v188
	v_fma_f32 v192, v12, v192, 1.0
	v_mul_f32_e32 v180, v212, v192
	v_add_f32_e32 v192, -1.0, v189
	v_fma_f32 v192, v13, v192, 1.0
	v_mul_f32_e32 v181, v213, v192
	v_add_f32_e32 v192, -1.0, v190
	v_fma_f32 v192, v14, v192, 1.0
	v_mul_f32_e32 v182, v214, v192
	v_add_f32_e32 v192, -1.0, v191
	v_fma_f32 v192, v15, v192, 1.0
	v_mul_f32_e32 v183, v215, v192
	v_max_f32_e32 v200, v200, v200
	v_max_f32_e32 v200, 0x179abe15, v200
	v_rsq_f32_e32 v201, v200
	v_mul_f32_e32 v192, v136, v176
	v_mul_f32_e32 v202, v16, v192
	v_mul_f32_e32 v160, v160, v201
	v_mul_f32_e32 v161, v161, v201
	v_mul_f32_e32 v162, v162, v201
	v_mul_f32_e32 v163, v163, v201
	v_mul_f32_e32 v164, v164, v201
	v_mul_f32_e32 v165, v165, v201
	v_mul_f32_e32 v166, v166, v201
	v_mul_f32_e32 v167, v167, v201
	v_mul_f32_e32 v168, v184, v160
	v_mul_f32_e32 v169, v185, v161
	v_mul_f32_e32 v170, v186, v162
	v_mul_f32_e32 v171, v187, v163
	v_mul_f32_e32 v172, v188, v164
	v_mul_f32_e32 v173, v189, v165
	v_mul_f32_e32 v174, v190, v166
	v_mul_f32_e32 v175, v191, v167
	ds_write_b128 v54, v[160:163] offset:0
	ds_write_b128 v54, v[164:167] offset:16
	ds_write_b128 v54, v[168:171] offset:256
	ds_write_b128 v54, v[172:175] offset:272
	ds_write_b128 v54, v[176:179] offset:512
	ds_write_b128 v54, v[180:183] offset:528
	ds_write_b128 v54, v[136:139] offset:768
	ds_write_b128 v54, v[140:143] offset:784
	ds_write_b128 v54, v[152:155] offset:1024
	ds_write_b128 v54, v[156:159] offset:1040
	v_mul_f32_e32 v192, v137, v177
	v_fmac_f32_e32 v202, v17, v192
	v_mul_f32_e32 v192, v138, v178
	v_fmac_f32_e32 v202, v18, v192
	v_mul_f32_e32 v192, v139, v179
	v_fmac_f32_e32 v202, v19, v192
	v_mul_f32_e32 v192, v140, v180
	v_fmac_f32_e32 v202, v20, v192
	v_mul_f32_e32 v192, v141, v181
	v_fmac_f32_e32 v202, v21, v192
	v_mul_f32_e32 v192, v142, v182
	v_fmac_f32_e32 v202, v22, v192
	v_mul_f32_e32 v192, v143, v183
	v_fmac_f32_e32 v202, v23, v192
	s_nop 1
	v_add_f32_dpp v202, v202, v202 quad_perm:[1,0,3,2] row_mask:0xf bank_mask:0xf bound_ctrl:1
	s_nop 1
	v_add_f32_dpp v202, v202, v202 quad_perm:[2,3,0,1] row_mask:0xf bank_mask:0xf bound_ctrl:1
	s_nop 1
	v_add_f32_dpp v202, v202, v202 row_half_mirror row_mask:0xf bank_mask:0xf bound_ctrl:1
	v_add_u32_e32 v205, s90, v56
	v_lshl_add_u32 v205, v205, 7, s64
	s_and_saveexec_b64 s[56:57], s[8:9]
	global_store_dword v205, v202, s[24:25]
	s_or_b64 exec, exec, s[56:57]
	v_add_u32_e32 v56, v59, v56
	s_waitcnt lgkmcnt(0)
	s_barrier
	ds_read_b128 v[184:187], v55 offset:4096
	ds_read_b128 v[188:191], v55 offset:4112
	s_waitcnt vmcnt(0)
	v_lshlrev_b32_e32 v136, 16, v100
	v_lshlrev_b32_e32 v192, 16, v112
	v_lshlrev_b32_e32 v193, 16, v124
	v_mul_f32_e32 v193, v63, v193
	v_fmac_f32_e32 v193, v62, v192
	v_fma_f32 v192, v193, 0.5, -v136
	v_fmac_f32_e32 v136, v24, v192
	v_and_b32_e32 v137, 0xffff0000, v100
	v_and_b32_e32 v192, 0xffff0000, v112
	v_and_b32_e32 v193, 0xffff0000, v124
	v_mul_f32_e32 v193, v63, v193
	v_fmac_f32_e32 v193, v62, v192
	v_fma_f32 v192, v193, 0.5, -v137
	v_fmac_f32_e32 v137, v25, v192
	v_lshlrev_b32_e32 v138, 16, v101
	v_lshlrev_b32_e32 v192, 16, v113
	v_lshlrev_b32_e32 v193, 16, v125
	v_mul_f32_e32 v193, v63, v193
	v_fmac_f32_e32 v193, v62, v192
	v_fma_f32 v192, v193, 0.5, -v138
	v_fmac_f32_e32 v138, v26, v192
	v_and_b32_e32 v139, 0xffff0000, v101
	v_and_b32_e32 v192, 0xffff0000, v113
	v_and_b32_e32 v193, 0xffff0000, v125
	v_mul_f32_e32 v193, v63, v193
	v_fmac_f32_e32 v193, v62, v192
	v_fma_f32 v192, v193, 0.5, -v139
	v_fmac_f32_e32 v139, v27, v192
	v_lshlrev_b32_e32 v140, 16, v102
	v_lshlrev_b32_e32 v192, 16, v114
	v_lshlrev_b32_e32 v193, 16, v126
	v_mul_f32_e32 v193, v63, v193
	v_fmac_f32_e32 v193, v62, v192
	v_fma_f32 v192, v193, 0.5, -v140
	v_fmac_f32_e32 v140, v28, v192
	v_and_b32_e32 v141, 0xffff0000, v102
	v_and_b32_e32 v192, 0xffff0000, v114
	v_and_b32_e32 v193, 0xffff0000, v126
	v_mul_f32_e32 v193, v63, v193
	v_fmac_f32_e32 v193, v62, v192
	v_fma_f32 v192, v193, 0.5, -v141
	v_fmac_f32_e32 v141, v29, v192
	v_lshlrev_b32_e32 v142, 16, v103
	v_lshlrev_b32_e32 v192, 16, v115
	v_lshlrev_b32_e32 v193, 16, v127
	v_mul_f32_e32 v193, v63, v193
	v_fmac_f32_e32 v193, v62, v192
	v_fma_f32 v192, v193, 0.5, -v142
	v_fmac_f32_e32 v142, v30, v192
	v_and_b32_e32 v143, 0xffff0000, v103
	v_and_b32_e32 v192, 0xffff0000, v115
	v_and_b32_e32 v193, 0xffff0000, v127
	v_mul_f32_e32 v193, v63, v193
	v_fmac_f32_e32 v193, v62, v192
	v_fma_f32 v192, v193, 0.5, -v143
	v_fmac_f32_e32 v143, v31, v192
	v_lshlrev_b32_e32 v208, 16, v104
	v_lshlrev_b32_e32 v192, 16, v116
	v_lshlrev_b32_e32 v193, 16, v128
	v_mul_f32_e32 v193, v63, v193
	v_fmac_f32_e32 v193, v62, v192
	v_fma_f32 v192, v193, 0.5, -v208
	v_fmac_f32_e32 v208, v32, v192
	v_and_b32_e32 v209, 0xffff0000, v104
	v_and_b32_e32 v192, 0xffff0000, v116
	v_and_b32_e32 v193, 0xffff0000, v128
	v_mul_f32_e32 v193, v63, v193
	v_fmac_f32_e32 v193, v62, v192
	v_fma_f32 v192, v193, 0.5, -v209
	v_fmac_f32_e32 v209, v33, v192
	v_lshlrev_b32_e32 v210, 16, v105
	v_lshlrev_b32_e32 v192, 16, v117
	v_lshlrev_b32_e32 v193, 16, v129
	v_mul_f32_e32 v193, v63, v193
	v_fmac_f32_e32 v193, v62, v192
	v_fma_f32 v192, v193, 0.5, -v210
	v_fmac_f32_e32 v210, v34, v192
	v_and_b32_e32 v211, 0xffff0000, v105
	v_and_b32_e32 v192, 0xffff0000, v117
	v_and_b32_e32 v193, 0xffff0000, v129
	v_mul_f32_e32 v193, v63, v193
	v_fmac_f32_e32 v193, v62, v192
	v_fma_f32 v192, v193, 0.5, -v211
	v_fmac_f32_e32 v211, v35, v192
	v_lshlrev_b32_e32 v212, 16, v106
	v_lshlrev_b32_e32 v192, 16, v118
	v_lshlrev_b32_e32 v193, 16, v130
	v_mul_f32_e32 v193, v63, v193
	v_fmac_f32_e32 v193, v62, v192
	v_fma_f32 v192, v193, 0.5, -v212
	v_fmac_f32_e32 v212, v36, v192
	v_and_b32_e32 v213, 0xffff0000, v106
	v_and_b32_e32 v192, 0xffff0000, v118
	v_and_b32_e32 v193, 0xffff0000, v130
	v_mul_f32_e32 v193, v63, v193
	v_fmac_f32_e32 v193, v62, v192
	v_fma_f32 v192, v193, 0.5, -v213
	v_fmac_f32_e32 v213, v37, v192
	v_lshlrev_b32_e32 v214, 16, v107
	v_lshlrev_b32_e32 v192, 16, v119
	v_lshlrev_b32_e32 v193, 16, v131
	v_mul_f32_e32 v193, v63, v193
	v_fmac_f32_e32 v193, v62, v192
	v_fma_f32 v192, v193, 0.5, -v214
	v_fmac_f32_e32 v214, v38, v192
	v_and_b32_e32 v215, 0xffff0000, v107
	v_and_b32_e32 v192, 0xffff0000, v119
	v_and_b32_e32 v193, 0xffff0000, v131
	v_mul_f32_e32 v193, v63, v193
	v_fmac_f32_e32 v193, v62, v192
	v_fma_f32 v192, v193, 0.5, -v215
	v_fmac_f32_e32 v215, v39, v192
	v_lshlrev_b32_e32 v152, 16, v108
	v_lshlrev_b32_e32 v192, 16, v120
	v_lshlrev_b32_e32 v193, 16, v132
	v_mul_f32_e32 v193, v63, v193
	v_fmac_f32_e32 v193, v62, v192
	v_fma_f32 v192, v193, 0.5, -v152
	v_fmac_f32_e32 v152, v40, v192
	v_and_b32_e32 v153, 0xffff0000, v108
	v_and_b32_e32 v192, 0xffff0000, v120
	v_and_b32_e32 v193, 0xffff0000, v132
	v_mul_f32_e32 v193, v63, v193
	v_fmac_f32_e32 v193, v62, v192
	v_fma_f32 v192, v193, 0.5, -v153
	v_fmac_f32_e32 v153, v41, v192
	v_lshlrev_b32_e32 v154, 16, v109
	v_lshlrev_b32_e32 v192, 16, v121
	v_lshlrev_b32_e32 v193, 16, v133
	v_mul_f32_e32 v193, v63, v193
	v_fmac_f32_e32 v193, v62, v192
	v_fma_f32 v192, v193, 0.5, -v154
	v_fmac_f32_e32 v154, v42, v192
	v_and_b32_e32 v155, 0xffff0000, v109
	v_and_b32_e32 v192, 0xffff0000, v121
	v_and_b32_e32 v193, 0xffff0000, v133
	v_mul_f32_e32 v193, v63, v193
	v_fmac_f32_e32 v193, v62, v192
	v_fma_f32 v192, v193, 0.5, -v155
	v_fmac_f32_e32 v155, v43, v192
	v_lshlrev_b32_e32 v156, 16, v110
	v_lshlrev_b32_e32 v192, 16, v122
	v_lshlrev_b32_e32 v193, 16, v134
	v_mul_f32_e32 v193, v63, v193
	v_fmac_f32_e32 v193, v62, v192
	v_fma_f32 v192, v193, 0.5, -v156
	v_fmac_f32_e32 v156, v44, v192
	v_and_b32_e32 v157, 0xffff0000, v110
	v_and_b32_e32 v192, 0xffff0000, v122
	v_and_b32_e32 v193, 0xffff0000, v134
	v_mul_f32_e32 v193, v63, v193
	v_fmac_f32_e32 v193, v62, v192
	v_fma_f32 v192, v193, 0.5, -v157
	v_fmac_f32_e32 v157, v45, v192
	v_lshlrev_b32_e32 v158, 16, v111
	v_lshlrev_b32_e32 v192, 16, v123
	v_lshlrev_b32_e32 v193, 16, v135
	v_mul_f32_e32 v193, v63, v193
	v_fmac_f32_e32 v193, v62, v192
	v_fma_f32 v192, v193, 0.5, -v158
	v_fmac_f32_e32 v158, v46, v192
	v_and_b32_e32 v159, 0xffff0000, v111
	v_and_b32_e32 v192, 0xffff0000, v123
	v_and_b32_e32 v193, 0xffff0000, v135
	v_mul_f32_e32 v193, v63, v193
	v_fmac_f32_e32 v193, v62, v192
	v_fma_f32 v192, v193, 0.5, -v159
	v_fmac_f32_e32 v159, v47, v192
	v_mul_f32_e32 v160, v0, v208
	v_mul_f32_e32 v161, v1, v209
	v_mul_f32_e32 v162, v2, v210
	v_mul_f32_e32 v163, v3, v211
	v_mul_f32_e32 v164, v4, v212
	v_mul_f32_e32 v165, v5, v213
	v_mul_f32_e32 v166, v6, v214
	v_mul_f32_e32 v167, v7, v215
	v_mul_f32_e32 v200, v160, v160
	v_fmac_f32_e32 v200, v161, v161
	v_fmac_f32_e32 v200, v162, v162
	v_fmac_f32_e32 v200, v163, v163
	v_fmac_f32_e32 v200, v164, v164
	v_fmac_f32_e32 v200, v165, v165
	v_fmac_f32_e32 v200, v166, v166
	v_fmac_f32_e32 v200, v167, v167
	s_waitcnt lgkmcnt(0)
	v_add_f32_e32 v192, -1.0, v184
	v_fma_f32 v192, v8, v192, 1.0
	v_mul_f32_e32 v176, v208, v192
	v_add_f32_dpp v200, v200, v200 quad_perm:[1,0,3,2] row_mask:0xf bank_mask:0xf bound_ctrl:1
	v_add_f32_e32 v192, -1.0, v185
	v_fma_f32 v192, v9, v192, 1.0
	v_mul_f32_e32 v177, v209, v192
	v_add_f32_dpp v200, v200, v200 quad_perm:[2,3,0,1] row_mask:0xf bank_mask:0xf bound_ctrl:1
	v_add_f32_e32 v192, -1.0, v186
	v_fma_f32 v192, v10, v192, 1.0
	v_mul_f32_e32 v178, v210, v192
	v_add_f32_dpp v200, v200, v200 row_half_mirror row_mask:0xf bank_mask:0xf bound_ctrl:1
	v_add_f32_e32 v192, -1.0, v187
	v_fma_f32 v192, v11, v192, 1.0
	v_mul_f32_e32 v179, v211, v192
	v_add_f32_e32 v192, -1.0, v188
	v_fma_f32 v192, v12, v192, 1.0
	v_mul_f32_e32 v180, v212, v192
	v_add_f32_e32 v192, -1.0, v189
	v_fma_f32 v192, v13, v192, 1.0
	v_mul_f32_e32 v181, v213, v192
	v_add_f32_e32 v192, -1.0, v190
	v_fma_f32 v192, v14, v192, 1.0
	v_mul_f32_e32 v182, v214, v192
	v_add_f32_e32 v192, -1.0, v191
	v_fma_f32 v192, v15, v192, 1.0
	v_mul_f32_e32 v183, v215, v192
	v_max_f32_e32 v200, v200, v200
	v_max_f32_e32 v200, 0x179abe15, v200
	v_rsq_f32_e32 v201, v200
	v_mul_f32_e32 v192, v136, v176
	v_mul_f32_e32 v202, v16, v192
	v_mul_f32_e32 v160, v160, v201
	v_mul_f32_e32 v161, v161, v201
	v_mul_f32_e32 v162, v162, v201
	v_mul_f32_e32 v163, v163, v201
	v_mul_f32_e32 v164, v164, v201
	v_mul_f32_e32 v165, v165, v201
	v_mul_f32_e32 v166, v166, v201
	v_mul_f32_e32 v167, v167, v201
	v_mul_f32_e32 v168, v184, v160
	v_mul_f32_e32 v169, v185, v161
	v_mul_f32_e32 v170, v186, v162
	v_mul_f32_e32 v171, v187, v163
	v_mul_f32_e32 v172, v188, v164
	v_mul_f32_e32 v173, v189, v165
	v_mul_f32_e32 v174, v190, v166
	v_mul_f32_e32 v175, v191, v167
	ds_write_b128 v54, v[160:163] offset:20480
	ds_write_b128 v54, v[164:167] offset:20496
	ds_write_b128 v54, v[168:171] offset:20736
	ds_write_b128 v54, v[172:175] offset:20752
	ds_write_b128 v54, v[176:179] offset:20992
	ds_write_b128 v54, v[180:183] offset:21008
	ds_write_b128 v54, v[136:139] offset:21248
	ds_write_b128 v54, v[140:143] offset:21264
	ds_write_b128 v54, v[152:155] offset:21504
	ds_write_b128 v54, v[156:159] offset:21520
	v_mul_f32_e32 v192, v137, v177
	v_fmac_f32_e32 v202, v17, v192
	v_mul_f32_e32 v192, v138, v178
	v_fmac_f32_e32 v202, v18, v192
	v_mul_f32_e32 v192, v139, v179
	v_fmac_f32_e32 v202, v19, v192
	v_mul_f32_e32 v192, v140, v180
	v_fmac_f32_e32 v202, v20, v192
	v_mul_f32_e32 v192, v141, v181
	v_fmac_f32_e32 v202, v21, v192
	v_mul_f32_e32 v192, v142, v182
	v_fmac_f32_e32 v202, v22, v192
	v_mul_f32_e32 v192, v143, v183
	v_fmac_f32_e32 v202, v23, v192
	s_nop 1
	v_add_f32_dpp v202, v202, v202 quad_perm:[1,0,3,2] row_mask:0xf bank_mask:0xf bound_ctrl:1
	s_nop 1
	v_add_f32_dpp v202, v202, v202 quad_perm:[2,3,0,1] row_mask:0xf bank_mask:0xf bound_ctrl:1
	s_nop 1
	v_add_f32_dpp v202, v202, v202 row_half_mirror row_mask:0xf bank_mask:0xf bound_ctrl:1
	v_add_u32_e32 v205, s90, v56
	v_lshl_add_u32 v205, v205, 7, s64
	s_and_saveexec_b64 s[56:57], s[8:9]
	global_store_dword v205, v202, s[24:25]
	s_or_b64 exec, exec, s[56:57]
	v_add_u32_e32 v56, v59, v56
	s_waitcnt lgkmcnt(0)
	s_barrier
	s_waitcnt lgkmcnt(0)
	s_barrier

; __device__ __forceinline__ int opaque_tid() { int t; asm volatile("v_mov_b32 %0, %1" : "=v"(t) : "v"((int)threadIdx.x)); return t; }
; template <int NS, bool LORA, int mat> ...
;     ...
;   const int ch = 64 * head + lane;
;   const float kk_c = p.k_k[ch], ka_c = p.k_a[ch], rk_c = p.r_k[ch];
;   const float mu_r = p.mu_shift[ch], mu_k = p.mu_shift[1024 + ch], mu_v = p.mu_shift[2048 + ch];
; template <int RG, int NSW>
; __device__ __forceinline__ void scan_job(const Params& p, float* lds, const size_t tok0, const int T, const int head,
;                                          const int dir, const int row_base, const int rk_sel) {
;   const int tidx = opaque_tid();
;   const int wave = tidx >> 6, lane = tidx & 63;
;   if (NSW == 4) {
;     if (wave < 4) scan_waves<RG, NSW>(p, lds, T, dir, wave, lane, tok0, head, row_base);
;     else if (wave == 4) prep_waves<1, true, 0>(p, lds, T, dir, lane, tok0, head, 0, rk_sel);
;     else if (wave == 5) prep_waves<3, true, 1>(p, lds, T, dir, lane, tok0, head, 1, rk_sel);
;     else prep_waves<6, false, 0>(p, lds, T, dir, lane, tok0, head, 4 + (wave - 6) * 6, rk_sel);
.LBB0_1226:
	s_andn2_b64 vcc, exec, s[0:1]
	s_cbranch_vccnz .LBB0_1354
	s_ashr_i32 s0, s2, 3
	s_add_i32 s4, s3, s0
	s_and_b32 s3, s0, 3
	s_ashr_i32 s59, s4, 3
	s_bfe_u32 s58, s0, 0x10002
	s_cmp_eq_u32 s58, 0
	s_waitcnt vmcnt(7)
	v_mov_b32 v140, v146
	s_cselect_b64 s[0:1], -1, 0
	s_waitcnt vmcnt(0)
	v_ashrrev_i32_e32 v6, 6, v140
	v_and_b32_e32 v148, 63, v140
	v_cmp_lt_i32_e32 vcc, 3, v6
	s_and_saveexec_b64 s[6:7], vcc
	s_xor_b64 s[46:47], exec, s[6:7]
	s_cbranch_execz .LBB0_1346
	s_lshl_b32 s61, s59, 6
	s_lshl_b32 s63, s58, 6
	s_lshl_b32 s5, s58, 10
	s_ashr_i32 s6, s61, 31
	s_add_u32 s64, s61, s5
	s_addc_u32 s65, s6, 0
	s_add_i32 s62, s61, s5
	s_and_b32 s4, s4, -8
	s_lshl_b32 s5, s58, 2
	s_or_b32 s60, s5, s4
	v_cmp_lt_i32_e32 vcc, 4, v6
	s_and_saveexec_b64 s[4:5], vcc
	s_xor_b64 s[48:49], exec, s[4:5]
	s_cbranch_execz .LBB0_1319
	v_cmp_ne_u32_e32 vcc, 5, v6
	s_and_saveexec_b64 s[4:5], vcc
	s_xor_b64 s[52:53], exec, s[4:5]
	s_cbranch_execz .LBB0_1276
	v_readfirstlane_b32 s4, v6
	v_and_b32_e32 v48, 7, v148
	v_lshrrev_b32_e32 v49, 3, v148
	s_sub_i32 s4, s4, 6
	s_lshl_b32 s4, s4, 3
	v_add_u32_e32 v50, s4, v49
	v_lshl_add_u32 v51, v48, 3, s61
	v_lshlrev_b32_e32 v52, 1, v51
	v_add_u32_e32 v52, 0x800, v52
	v_lshlrev_b32_e32 v51, 2, v51
	v_mov_b32_e32 v53, 0x1c00
	v_mov_b32_e32 v58, 0x3fff
	v_mov_b32_e32 v59, -16
	v_cndmask_b32_e64 v59, v59, 16, s[0:1]
	v_add_u32_e32 v205, 0x1000, v51
	v_add_u32_e32 v206, 0x2000, v51
	global_load_dwordx4 v[0:3], v51, s[50:51]
	global_load_dwordx4 v[4:7], v51, s[50:51] offset:16
	global_load_dwordx4 v[8:11], v51, s[16:17]
	global_load_dwordx4 v[12:15], v51, s[16:17] offset:16
	global_load_dwordx4 v[16:19], v51, s[18:19]
	global_load_dwordx4 v[20:23], v51, s[18:19] offset:16
	global_load_dwordx4 v[24:27], v51, s[38:39]
	global_load_dwordx4 v[28:31], v51, s[38:39] offset:16
	global_load_dwordx4 v[32:35], v205, s[38:39]
	global_load_dwordx4 v[36:39], v205, s[38:39] offset:16
	global_load_dwordx4 v[40:43], v206, s[38:39]
	global_load_dwordx4 v[44:47], v206, s[38:39] offset:16
	v_mul_u32_u24_e32 v54, 0x500, v50
	v_lshlrev_b32_e32 v55, 8, v50
	v_lshl_add_u32 v54, v48, 5, v54
	v_lshl_add_u32 v55, v48, 5, v55
	v_add_u32_e32 v54, 0x5000, v54
	v_add_u32_e32 v55, 0x3000, v55
	v_sub_u32_e32 v205, v58, v50
	v_cndmask_b32_e64 v56, v205, v50, s[0:1]
	v_and_b32_e32 v205, 3, v50
	v_cmp_eq_u32_e64 s[8:9], s3, v205
	v_cmp_eq_u32_e32 vcc, 0, v48
	s_and_b64 s[8:9], s[8:9], vcc
	s_waitcnt vmcnt(0)
	v_cmp_lt_i32_e64 s[10:11], 0, v56
	v_cmp_gt_i32_e64 s[12:13], v58, v56
	v_mad_u32_u24 v205, v56, v53, v52
	s_nop 0
	v_cndmask_b32_e64 v206, 0, v53, s[10:11]
	v_cndmask_b32_e64 v207, 0, v53, s[12:13]
	v_cndmask_b32_e64 v60, 0, 1.0, s[10:11]
	v_cndmask_b32_e64 v61, 0, 1.0, s[12:13]
	v_sub_u32_e32 v206, v205, v206
	v_add_u32_e32 v207, v205, v207
	global_load_dwordx4 v[64:67], v205, s[72:73] offset:-2048
	global_load_dwordx4 v[68:71], v205, s[72:73]
	global_load_dwordx4 v[72:75], v205, s[72:73] offset:2048
	global_load_dwordx4 v[76:79], v206, s[72:73] offset:-2048
	global_load_dwordx4 v[80:83], v206, s[72:73]
	global_load_dwordx4 v[84:87], v206, s[72:73] offset:2048
	global_load_dwordx4 v[88:91], v207, s[72:73] offset:-2048
	global_load_dwordx4 v[92:95], v207, s[72:73]
	global_load_dwordx4 v[96:99], v207, s[72:73] offset:2048
	v_add_u32_e32 v57, v59, v56
	v_cmp_lt_i32_e64 s[10:11], 0, v57
	v_cmp_gt_i32_e64 s[12:13], v58, v57
	v_mad_u32_u24 v205, v57, v53, v52
	s_nop 0
	v_cndmask_b32_e64 v206, 0, v53, s[10:11]
	v_cndmask_b32_e64 v207, 0, v53, s[12:13]
	v_cndmask_b32_e64 v62, 0, 1.0, s[10:11]
	v_cndmask_b32_e64 v63, 0, 1.0, s[12:13]
	v_sub_u32_e32 v206, v205, v206
	v_add_u32_e32 v207, v205, v207
	global_load_dwordx4 v[100:103], v205, s[72:73] offset:-2048
	global_load_dwordx4 v[104:107], v205, s[72:73]
	global_load_dwordx4 v[108:111], v205, s[72:73] offset:2048
	global_load_dwordx4 v[112:115], v206, s[72:73] offset:-2048
	global_load_dwordx4 v[116:119], v206, s[72:73]
	global_load_dwordx4 v[120:123], v206, s[72:73] offset:2048
	global_load_dwordx4 v[124:127], v207, s[72:73] offset:-2048
	global_load_dwordx4 v[128:131], v207, s[72:73]
	global_load_dwordx4 v[132:135], v207, s[72:73] offset:2048
	s_mov_b32 s66, 3
	s_waitcnt lgkmcnt(0)
	s_barrier
	ds_read_b128 v[184:187], v55 offset:0
	ds_read_b128 v[188:191], v55 offset:16
	s_waitcnt vmcnt(9)
	v_lshlrev_b32_e32 v136, 16, v64
	v_lshlrev_b32_e32 v192, 16, v76
	v_lshlrev_b32_e32 v193, 16, v88
	v_mul_f32_e32 v193, v61, v193
	v_fmac_f32_e32 v193, v60, v192
	v_fma_f32 v192, v193, 0.5, -v136
	v_fmac_f32_e32 v136, v24, v192
	v_and_b32_e32 v137, 0xffff0000, v64
	v_and_b32_e32 v192, 0xffff0000, v76
	v_and_b32_e32 v193, 0xffff0000, v88
	v_mul_f32_e32 v193, v61, v193
	v_fmac_f32_e32 v193, v60, v192
	v_fma_f32 v192, v193, 0.5, -v137
	v_fmac_f32_e32 v137, v25, v192
	v_lshlrev_b32_e32 v138, 16, v65
	v_lshlrev_b32_e32 v192, 16, v77
	v_lshlrev_b32_e32 v193, 16, v89
	v_mul_f32_e32 v193, v61, v193
	v_fmac_f32_e32 v193, v60, v192
	v_fma_f32 v192, v193, 0.5, -v138
	v_fmac_f32_e32 v138, v26, v192
	v_and_b32_e32 v139, 0xffff0000, v65
	v_and_b32_e32 v192, 0xffff0000, v77
	v_and_b32_e32 v193, 0xffff0000, v89
	v_mul_f32_e32 v193, v61, v193
	v_fmac_f32_e32 v193, v60, v192
	v_fma_f32 v192, v193, 0.5, -v139
	v_fmac_f32_e32 v139, v27, v192
	v_lshlrev_b32_e32 v140, 16, v66
	v_lshlrev_b32_e32 v192, 16, v78
	v_lshlrev_b32_e32 v193, 16, v90
	v_mul_f32_e32 v193, v61, v193
	v_fmac_f32_e32 v193, v60, v192
	v_fma_f32 v192, v193, 0.5, -v140
	v_fmac_f32_e32 v140, v28, v192
	v_and_b32_e32 v141, 0xffff0000, v66
	v_and_b32_e32 v192, 0xffff0000, v78
	v_and_b32_e32 v193, 0xffff0000, v90
	v_mul_f32_e32 v193, v61, v193
	v_fmac_f32_e32 v193, v60, v192
	v_fma_f32 v192, v193, 0.5, -v141
	v_fmac_f32_e32 v141, v29, v192
	v_lshlrev_b32_e32 v142, 16, v67
	v_lshlrev_b32_e32 v192, 16, v79
	v_lshlrev_b32_e32 v193, 16, v91
	v_mul_f32_e32 v193, v61, v193
	v_fmac_f32_e32 v193, v60, v192
	v_fma_f32 v192, v193, 0.5, -v142
	v_fmac_f32_e32 v142, v30, v192
	v_and_b32_e32 v143, 0xffff0000, v67
	v_and_b32_e32 v192, 0xffff0000, v79
	v_and_b32_e32 v193, 0xffff0000, v91
	v_mul_f32_e32 v193, v61, v193
	v_fmac_f32_e32 v193, v60, v192
	v_fma_f32 v192, v193, 0.5, -v143
	v_fmac_f32_e32 v143, v31, v192
	v_lshlrev_b32_e32 v208, 16, v68
	v_lshlrev_b32_e32 v192, 16, v80
	v_lshlrev_b32_e32 v193, 16, v92
	v_mul_f32_e32 v193, v61, v193
	v_fmac_f32_e32 v193, v60, v192
	v_fma_f32 v192, v193, 0.5, -v208
	v_fmac_f32_e32 v208, v32, v192
	v_and_b32_e32 v209, 0xffff0000, v68
	v_and_b32_e32 v192, 0xffff0000, v80
	v_and_b32_e32 v193, 0xffff0000, v92
	v_mul_f32_e32 v193, v61, v193
	v_fmac_f32_e32 v193, v60, v192
	v_fma_f32 v192, v193, 0.5, -v209
	v_fmac_f32_e32 v209, v33, v192
	v_lshlrev_b32_e32 v210, 16, v69
	v_lshlrev_b32_e32 v192, 16, v81
	v_lshlrev_b32_e32 v193, 16, v93
	v_mul_f32_e32 v193, v61, v193
	v_fmac_f32_e32 v193, v60, v192
	v_fma_f32 v192, v193, 0.5, -v210
	v_fmac_f32_e32 v210, v34, v192
	v_and_b32_e32 v211, 0xffff0000, v69
	v_and_b32_e32 v192, 0xffff0000, v81
	v_and_b32_e32 v193, 0xffff0000, v93
	v_mul_f32_e32 v193, v61, v193
	v_fmac_f32_e32 v193, v60, v192
	v_fma_f32 v192, v193, 0.5, -v211
	v_fmac_f32_e32 v211, v35, v192
	v_lshlrev_b32_e32 v212, 16, v70
	v_lshlrev_b32_e32 v192, 16, v82
	v_lshlrev_b32_e32 v193, 16, v94
	v_mul_f32_e32 v193, v61, v193
	v_fmac_f32_e32 v193, v60, v192
	v_fma_f32 v192, v193, 0.5, -v212
	v_fmac_f32_e32 v212, v36, v192
	v_and_b32_e32 v213, 0xffff0000, v70
	v_and_b32_e32 v192, 0xffff0000, v82
	v_and_b32_e32 v193, 0xffff0000, v94
	v_mul_f32_e32 v193, v61, v193
	v_fmac_f32_e32 v193, v60, v192
	v_fma_f32 v192, v193, 0.5, -v213
	v_fmac_f32_e32 v213, v37, v192
	v_lshlrev_b32_e32 v214, 16, v71
	v_lshlrev_b32_e32 v192, 16, v83
	v_lshlrev_b32_e32 v193, 16, v95
	v_mul_f32_e32 v193, v61, v193
	v_fmac_f32_e32 v193, v60, v192
	v_fma_f32 v192, v193, 0.5, -v214
	v_fmac_f32_e32 v214, v38, v192
	v_and_b32_e32 v215, 0xffff0000, v71
	v_and_b32_e32 v192, 0xffff0000, v83
	v_and_b32_e32 v193, 0xffff0000, v95
	v_mul_f32_e32 v193, v61, v193
	v_fmac_f32_e32 v193, v60, v192
	v_fma_f32 v192, v193, 0.5, -v215
	v_fmac_f32_e32 v215, v39, v192
	v_lshlrev_b32_e32 v152, 16, v72
	v_lshlrev_b32_e32 v192, 16, v84
	v_lshlrev_b32_e32 v193, 16, v96
	v_mul_f32_e32 v193, v61, v193
	v_fmac_f32_e32 v193, v60, v192
	v_fma_f32 v192, v193, 0.5, -v152
	v_fmac_f32_e32 v152, v40, v192
	v_and_b32_e32 v153, 0xffff0000, v72
	v_and_b32_e32 v192, 0xffff0000, v84
	v_and_b32_e32 v193, 0xffff0000, v96
	v_mul_f32_e32 v193, v61, v193
	v_fmac_f32_e32 v193, v60, v192
	v_fma_f32 v192, v193, 0.5, -v153
	v_fmac_f32_e32 v153, v41, v192
	v_lshlrev_b32_e32 v154, 16, v73
	v_lshlrev_b32_e32 v192, 16, v85
	v_lshlrev_b32_e32 v193, 16, v97
	v_mul_f32_e32 v193, v61, v193
	v_fmac_f32_e32 v193, v60, v192
	v_fma_f32 v192, v193, 0.5, -v154
	v_fmac_f32_e32 v154, v42, v192
	v_and_b32_e32 v155, 0xffff0000, v73
	v_and_b32_e32 v192, 0xffff0000, v85
	v_and_b32_e32 v193, 0xffff0000, v97
	v_mul_f32_e32 v193, v61, v193
	v_fmac_f32_e32 v193, v60, v192
	v_fma_f32 v192, v193, 0.5, -v155
	v_fmac_f32_e32 v155, v43, v192
	v_lshlrev_b32_e32 v156, 16, v74
	v_lshlrev_b32_e32 v192, 16, v86
	v_lshlrev_b32_e32 v193, 16, v98
	v_mul_f32_e32 v193, v61, v193
	v_fmac_f32_e32 v193, v60, v192
	v_fma_f32 v192, v193, 0.5, -v156
	v_fmac_f32_e32 v156, v44, v192
	v_and_b32_e32 v157, 0xffff0000, v74
	v_and_b32_e32 v192, 0xffff0000, v86
	v_and_b32_e32 v193, 0xffff0000, v98
	v_mul_f32_e32 v193, v61, v193
	v_fmac_f32_e32 v193, v60, v192
	v_fma_f32 v192, v193, 0.5, -v157
	v_fmac_f32_e32 v157, v45, v192
	v_lshlrev_b32_e32 v158, 16, v75
	v_lshlrev_b32_e32 v192, 16, v87
	v_lshlrev_b32_e32 v193, 16, v99
	v_mul_f32_e32 v193, v61, v193
	v_fmac_f32_e32 v193, v60, v192
	v_fma_f32 v192, v193, 0.5, -v158
	v_fmac_f32_e32 v158, v46, v192
	v_and_b32_e32 v159, 0xffff0000, v75
	v_and_b32_e32 v192, 0xffff0000, v87
	v_and_b32_e32 v193, 0xffff0000, v99
	v_mul_f32_e32 v193, v61, v193
	v_fmac_f32_e32 v193, v60, v192
	v_fma_f32 v192, v193, 0.5, -v159
	v_fmac_f32_e32 v159, v47, v192
	v_add_u32_e32 v57, v59, v56
	v_add_u32_e32 v57, v59, v57
	v_cmp_lt_i32_e64 s[10:11], 0, v57
	v_cmp_gt_i32_e64 s[12:13], v58, v57
	v_mad_u32_u24 v205, v57, v53, v52
	s_nop 0
	v_cndmask_b32_e64 v206, 0, v53, s[10:11]
	v_cndmask_b32_e64 v207, 0, v53, s[12:13]
	v_cndmask_b32_e64 v60, 0, 1.0, s[10:11]
	v_cndmask_b32_e64 v61, 0, 1.0, s[12:13]
	v_sub_u32_e32 v206, v205, v206
	v_add_u32_e32 v207, v205, v207
	global_load_dwordx4 v[64:67], v205, s[72:73] offset:-2048
	global_load_dwordx4 v[68:71], v205, s[72:73]
	global_load_dwordx4 v[72:75], v205, s[72:73] offset:2048
	global_load_dwordx4 v[76:79], v206, s[72:73] offset:-2048
	global_load_dwordx4 v[80:83], v206, s[72:73]
	global_load_dwordx4 v[84:87], v206, s[72:73] offset:2048
	global_load_dwordx4 v[88:91], v207, s[72:73] offset:-2048
	global_load_dwordx4 v[92:95], v207, s[72:73]
	global_load_dwordx4 v[96:99], v207, s[72:73] offset:2048
	v_mul_f32_e32 v160, v0, v208
	v_mul_f32_e32 v161, v1, v209
	v_mul_f32_e32 v162, v2, v210
	v_mul_f32_e32 v163, v3, v211
	v_mul_f32_e32 v164, v4, v212
	v_mul_f32_e32 v165, v5, v213
	v_mul_f32_e32 v166, v6, v214
	v_mul_f32_e32 v167, v7, v215
	v_mul_f32_e32 v200, v160, v160
	v_fmac_f32_e32 v200, v161, v161
	v_fmac_f32_e32 v200, v162, v162
	v_fmac_f32_e32 v200, v163, v163
	v_fmac_f32_e32 v200, v164, v164
	v_fmac_f32_e32 v200, v165, v165
	v_fmac_f32_e32 v200, v166, v166
	v_fmac_f32_e32 v200, v167, v167
	s_waitcnt lgkmcnt(0)
	v_add_f32_e32 v192, -1.0, v184
	v_fma_f32 v192, v8, v192, 1.0
	v_mul_f32_e32 v176, v208, v192
	v_add_f32_dpp v200, v200, v200 quad_perm:[1,0,3,2] row_mask:0xf bank_mask:0xf bound_ctrl:1
	v_add_f32_e32 v192, -1.0, v185
	v_fma_f32 v192, v9, v192, 1.0
	v_mul_f32_e32 v177, v209, v192
	v_add_f32_dpp v200, v200, v200 quad_perm:[2,3,0,1] row_mask:0xf bank_mask:0xf bound_ctrl:1
	v_add_f32_e32 v192, -1.0, v186
	v_fma_f32 v192, v10, v192, 1.0
	v_mul_f32_e32 v178, v210, v192
	v_add_f32_dpp v200, v200, v200 row_half_mirror row_mask:0xf bank_mask:0xf bound_ctrl:1
	v_add_f32_e32 v192, -1.0, v187
	v_fma_f32 v192, v11, v192, 1.0
	v_mul_f32_e32 v179, v211, v192
	v_add_f32_e32 v192, -1.0, v188
	v_fma_f32 v192, v12, v192, 1.0
	v_mul_f32_e32 v180, v212, v192
	v_add_f32_e32 v192, -1.0, v189
	v_fma_f32 v192, v13, v192, 1.0
	v_mul_f32_e32 v181, v213, v192
	v_add_f32_e32 v192, -1.0, v190
	v_fma_f32 v192, v14, v192, 1.0
	v_mul_f32_e32 v182, v214, v192
	v_add_f32_e32 v192, -1.0, v191
	v_fma_f32 v192, v15, v192, 1.0
	v_mul_f32_e32 v183, v215, v192
	v_max_f32_e32 v200, v200, v200
	v_max_f32_e32 v200, 0x179abe15, v200
	v_rsq_f32_e32 v201, v200
	v_mul_f32_e32 v192, v136, v176
	v_mul_f32_e32 v202, v16, v192
	v_mul_f32_e32 v160, v160, v201
	v_mul_f32_e32 v161, v161, v201
	v_mul_f32_e32 v162, v162, v201
	v_mul_f32_e32 v163, v163, v201
	v_mul_f32_e32 v164, v164, v201
	v_mul_f32_e32 v165, v165, v201
	v_mul_f32_e32 v166, v166, v201
	v_mul_f32_e32 v167, v167, v201
	v_mul_f32_e32 v168, v184, v160
	v_mul_f32_e32 v169, v185, v161
	v_mul_f32_e32 v170, v186, v162
	v_mul_f32_e32 v171, v187, v163
	v_mul_f32_e32 v172, v188, v164
	v_mul_f32_e32 v173, v189, v165
	v_mul_f32_e32 v174, v190, v166
	v_mul_f32_e32 v175, v191, v167
	ds_write_b128 v54, v[160:163] offset:0
	ds_write_b128 v54, v[164:167] offset:16
	ds_write_b128 v54, v[168:171] offset:256
	ds_write_b128 v54, v[172:175] offset:272
	ds_write_b128 v54, v[176:179] offset:512
	ds_write_b128 v54, v[180:183] offset:528
	ds_write_b128 v54, v[136:139] offset:768
	ds_write_b128 v54, v[140:143] offset:784
	ds_write_b128 v54, v[152:155] offset:1024
	ds_write_b128 v54, v[156:159] offset:1040
	v_mul_f32_e32 v192, v137, v177
	v_fmac_f32_e32 v202, v17, v192
	v_mul_f32_e32 v192, v138, v178
	v_fmac_f32_e32 v202, v18, v192
	v_mul_f32_e32 v192, v139, v179
	v_fmac_f32_e32 v202, v19, v192
	v_mul_f32_e32 v192, v140, v180
	v_fmac_f32_e32 v202, v20, v192
	v_mul_f32_e32 v192, v141, v181
	v_fmac_f32_e32 v202, v21, v192
	v_mul_f32_e32 v192, v142, v182
	v_fmac_f32_e32 v202, v22, v192
	v_mul_f32_e32 v192, v143, v183
	v_fmac_f32_e32 v202, v23, v192
	s_nop 1
	v_add_f32_dpp v202, v202, v202 quad_perm:[1,0,3,2] row_mask:0xf bank_mask:0xf bound_ctrl:1
	s_nop 1
	v_add_f32_dpp v202, v202, v202 quad_perm:[2,3,0,1] row_mask:0xf bank_mask:0xf bound_ctrl:1
	s_nop 1
	v_add_f32_dpp v202, v202, v202 row_half_mirror row_mask:0xf bank_mask:0xf bound_ctrl:1
	v_lshl_add_u32 v205, v56, 7, s60
	s_and_saveexec_b64 s[6:7], s[8:9]
	global_store_dword v205, v202, s[24:25]
	s_or_b64 exec, exec, s[6:7]
	v_add_u32_e32 v56, v59, v56
	s_waitcnt lgkmcnt(0)
	s_barrier
	ds_read_b128 v[184:187], v55 offset:4096
	ds_read_b128 v[188:191], v55 offset:4112
	s_waitcnt vmcnt(9)
	v_lshlrev_b32_e32 v136, 16, v100
	v_lshlrev_b32_e32 v192, 16, v112
	v_lshlrev_b32_e32 v193, 16, v124
	v_mul_f32_e32 v193, v63, v193
	v_fmac_f32_e32 v193, v62, v192
	v_fma_f32 v192, v193, 0.5, -v136
	v_fmac_f32_e32 v136, v24, v192
	v_and_b32_e32 v137, 0xffff0000, v100
	v_and_b32_e32 v192, 0xffff0000, v112
	v_and_b32_e32 v193, 0xffff0000, v124
	v_mul_f32_e32 v193, v63, v193
	v_fmac_f32_e32 v193, v62, v192
	v_fma_f32 v192, v193, 0.5, -v137
	v_fmac_f32_e32 v137, v25, v192
	v_lshlrev_b32_e32 v138, 16, v101
	v_lshlrev_b32_e32 v192, 16, v113
	v_lshlrev_b32_e32 v193, 16, v125
	v_mul_f32_e32 v193, v63, v193
	v_fmac_f32_e32 v193, v62, v192
	v_fma_f32 v192, v193, 0.5, -v138
	v_fmac_f32_e32 v138, v26, v192
	v_and_b32_e32 v139, 0xffff0000, v101
	v_and_b32_e32 v192, 0xffff0000, v113
	v_and_b32_e32 v193, 0xffff0000, v125
	v_mul_f32_e32 v193, v63, v193
	v_fmac_f32_e32 v193, v62, v192
	v_fma_f32 v192, v193, 0.5, -v139
	v_fmac_f32_e32 v139, v27, v192
	v_lshlrev_b32_e32 v140, 16, v102
	v_lshlrev_b32_e32 v192, 16, v114
	v_lshlrev_b32_e32 v193, 16, v126
	v_mul_f32_e32 v193, v63, v193
	v_fmac_f32_e32 v193, v62, v192
	v_fma_f32 v192, v193, 0.5, -v140
	v_fmac_f32_e32 v140, v28, v192
	v_and_b32_e32 v141, 0xffff0000, v102
	v_and_b32_e32 v192, 0xffff0000, v114
	v_and_b32_e32 v193, 0xffff0000, v126
	v_mul_f32_e32 v193, v63, v193
	v_fmac_f32_e32 v193, v62, v192
	v_fma_f32 v192, v193, 0.5, -v141
	v_fmac_f32_e32 v141, v29, v192
	v_lshlrev_b32_e32 v142, 16, v103
	v_lshlrev_b32_e32 v192, 16, v115
	v_lshlrev_b32_e32 v193, 16, v127
	v_mul_f32_e32 v193, v63, v193
	v_fmac_f32_e32 v193, v62, v192
	v_fma_f32 v192, v193, 0.5, -v142
	v_fmac_f32_e32 v142, v30, v192
	v_and_b32_e32 v143, 0xffff0000, v103
	v_and_b32_e32 v192, 0xffff0000, v115
	v_and_b32_e32 v193, 0xffff0000, v127
	v_mul_f32_e32 v193, v63, v193
	v_fmac_f32_e32 v193, v62, v192
	v_fma_f32 v192, v193, 0.5, -v143
	v_fmac_f32_e32 v143, v31, v192
	v_lshlrev_b32_e32 v208, 16, v104
	v_lshlrev_b32_e32 v192, 16, v116
	v_lshlrev_b32_e32 v193, 16, v128
	v_mul_f32_e32 v193, v63, v193
	v_fmac_f32_e32 v193, v62, v192
	v_fma_f32 v192, v193, 0.5, -v208
	v_fmac_f32_e32 v208, v32, v192
	v_and_b32_e32 v209, 0xffff0000, v104
	v_and_b32_e32 v192, 0xffff0000, v116
	v_and_b32_e32 v193, 0xffff0000, v128
	v_mul_f32_e32 v193, v63, v193
	v_fmac_f32_e32 v193, v62, v192
	v_fma_f32 v192, v193, 0.5, -v209
	v_fmac_f32_e32 v209, v33, v192
	v_lshlrev_b32_e32 v210, 16, v105
	v_lshlrev_b32_e32 v192, 16, v117
	v_lshlrev_b32_e32 v193, 16, v129
	v_mul_f32_e32 v193, v63, v193
	v_fmac_f32_e32 v193, v62, v192
	v_fma_f32 v192, v193, 0.5, -v210
	v_fmac_f32_e32 v210, v34, v192
	v_and_b32_e32 v211, 0xffff0000, v105
	v_and_b32_e32 v192, 0xffff0000, v117
	v_and_b32_e32 v193, 0xffff0000, v129
	v_mul_f32_e32 v193, v63, v193
	v_fmac_f32_e32 v193, v62, v192
	v_fma_f32 v192, v193, 0.5, -v211
	v_fmac_f32_e32 v211, v35, v192
	v_lshlrev_b32_e32 v212, 16, v106
	v_lshlrev_b32_e32 v192, 16, v118
	v_lshlrev_b32_e32 v193, 16, v130
	v_mul_f32_e32 v193, v63, v193
	v_fmac_f32_e32 v193, v62, v192
	v_fma_f32 v192, v193, 0.5, -v212
	v_fmac_f32_e32 v212, v36, v192
	v_and_b32_e32 v213, 0xffff0000, v106
	v_and_b32_e32 v192, 0xffff0000, v118
	v_and_b32_e32 v193, 0xffff0000, v130
	v_mul_f32_e32 v193, v63, v193
	v_fmac_f32_e32 v193, v62, v192
	v_fma_f32 v192, v193, 0.5, -v213
	v_fmac_f32_e32 v213, v37, v192
	v_lshlrev_b32_e32 v214, 16, v107
	v_lshlrev_b32_e32 v192, 16, v119
	v_lshlrev_b32_e32 v193, 16, v131
	v_mul_f32_e32 v193, v63, v193
	v_fmac_f32_e32 v193, v62, v192
	v_fma_f32 v192, v193, 0.5, -v214
	v_fmac_f32_e32 v214, v38, v192
	v_and_b32_e32 v215, 0xffff0000, v107
	v_and_b32_e32 v192, 0xffff0000, v119
	v_and_b32_e32 v193, 0xffff0000, v131
	v_mul_f32_e32 v193, v63, v193
	v_fmac_f32_e32 v193, v62, v192
	v_fma_f32 v192, v193, 0.5, -v215
	v_fmac_f32_e32 v215, v39, v192
	v_lshlrev_b32_e32 v152, 16, v108
	v_lshlrev_b32_e32 v192, 16, v120
	v_lshlrev_b32_e32 v193, 16, v132
	v_mul_f32_e32 v193, v63, v193
	v_fmac_f32_e32 v193, v62, v192
	v_fma_f32 v192, v193, 0.5, -v152
	v_fmac_f32_e32 v152, v40, v192
	v_and_b32_e32 v153, 0xffff0000, v108
	v_and_b32_e32 v192, 0xffff0000, v120
	v_and_b32_e32 v193, 0xffff0000, v132
	v_mul_f32_e32 v193, v63, v193
	v_fmac_f32_e32 v193, v62, v192
	v_fma_f32 v192, v193, 0.5, -v153
	v_fmac_f32_e32 v153, v41, v192
	v_lshlrev_b32_e32 v154, 16, v109
	v_lshlrev_b32_e32 v192, 16, v121
	v_lshlrev_b32_e32 v193, 16, v133
	v_mul_f32_e32 v193, v63, v193
	v_fmac_f32_e32 v193, v62, v192
	v_fma_f32 v192, v193, 0.5, -v154
	v_fmac_f32_e32 v154, v42, v192
	v_and_b32_e32 v155, 0xffff0000, v109
	v_and_b32_e32 v192, 0xffff0000, v121
	v_and_b32_e32 v193, 0xffff0000, v133
	v_mul_f32_e32 v193, v63, v193
	v_fmac_f32_e32 v193, v62, v192
	v_fma_f32 v192, v193, 0.5, -v155
	v_fmac_f32_e32 v155, v43, v192
	v_lshlrev_b32_e32 v156, 16, v110
	v_lshlrev_b32_e32 v192, 16, v122
	v_lshlrev_b32_e32 v193, 16, v134
	v_mul_f32_e32 v193, v63, v193
	v_fmac_f32_e32 v193, v62, v192
	v_fma_f32 v192, v193, 0.5, -v156
	v_fmac_f32_e32 v156, v44, v192
	v_and_b32_e32 v157, 0xffff0000, v110
	v_and_b32_e32 v192, 0xffff0000, v122
	v_and_b32_e32 v193, 0xffff0000, v134
	v_mul_f32_e32 v193, v63, v193
	v_fmac_f32_e32 v193, v62, v192
	v_fma_f32 v192, v193, 0.5, -v157
	v_fmac_f32_e32 v157, v45, v192
	v_lshlrev_b32_e32 v158, 16, v111
	v_lshlrev_b32_e32 v192, 16, v123
	v_lshlrev_b32_e32 v193, 16, v135
	v_mul_f32_e32 v193, v63, v193
	v_fmac_f32_e32 v193, v62, v192
	v_fma_f32 v192, v193, 0.5, -v158
	v_fmac_f32_e32 v158, v46, v192
	v_and_b32_e32 v159, 0xffff0000, v111
	v_and_b32_e32 v192, 0xffff0000, v123
	v_and_b32_e32 v193, 0xffff0000, v135
	v_mul_f32_e32 v193, v63, v193
	v_fmac_f32_e32 v193, v62, v192
	v_fma_f32 v192, v193, 0.5, -v159
	v_fmac_f32_e32 v159, v47, v192
	v_add_u32_e32 v57, v59, v56
	v_add_u32_e32 v57, v59, v57
	v_cmp_lt_i32_e64 s[10:11], 0, v57
	v_cmp_gt_i32_e64 s[12:13], v58, v57
	v_mad_u32_u24 v205, v57, v53, v52
	s_nop 0
	v_cndmask_b32_e64 v206, 0, v53, s[10:11]
	v_cndmask_b32_e64 v207, 0, v53, s[12:13]
	v_cndmask_b32_e64 v62, 0, 1.0, s[10:11]
	v_cndmask_b32_e64 v63, 0, 1.0, s[12:13]
	v_sub_u32_e32 v206, v205, v206
	v_add_u32_e32 v207, v205, v207
	global_load_dwordx4 v[100:103], v205, s[72:73] offset:-2048
	global_load_dwordx4 v[104:107], v205, s[72:73]
	global_load_dwordx4 v[108:111], v205, s[72:73] offset:2048
	global_load_dwordx4 v[112:115], v206, s[72:73] offset:-2048
	global_load_dwordx4 v[116:119], v206, s[72:73]
	global_load_dwordx4 v[120:123], v206, s[72:73] offset:2048
	global_load_dwordx4 v[124:127], v207, s[72:73] offset:-2048
	global_load_dwordx4 v[128:131], v207, s[72:73]
	global_load_dwordx4 v[132:135], v207, s[72:73] offset:2048
	v_mul_f32_e32 v160, v0, v208
	v_mul_f32_e32 v161, v1, v209
	v_mul_f32_e32 v162, v2, v210
	v_mul_f32_e32 v163, v3, v211
	v_mul_f32_e32 v164, v4, v212
	v_mul_f32_e32 v165, v5, v213
	v_mul_f32_e32 v166, v6, v214
	v_mul_f32_e32 v167, v7, v215
	v_mul_f32_e32 v200, v160, v160
	v_fmac_f32_e32 v200, v161, v161
	v_fmac_f32_e32 v200, v162, v162
	v_fmac_f32_e32 v200, v163, v163
	v_fmac_f32_e32 v200, v164, v164
	v_fmac_f32_e32 v200, v165, v165
	v_fmac_f32_e32 v200, v166, v166
	v_fmac_f32_e32 v200, v167, v167
	s_waitcnt lgkmcnt(0)
	v_add_f32_e32 v192, -1.0, v184
	v_fma_f32 v192, v8, v192, 1.0
	v_mul_f32_e32 v176, v208, v192
	v_add_f32_dpp v200, v200, v200 quad_perm:[1,0,3,2] row_mask:0xf bank_mask:0xf bound_ctrl:1
	v_add_f32_e32 v192, -1.0, v185
	v_fma_f32 v192, v9, v192, 1.0
	v_mul_f32_e32 v177, v209, v192
	v_add_f32_dpp v200, v200, v200 quad_perm:[2,3,0,1] row_mask:0xf bank_mask:0xf bound_ctrl:1
	v_add_f32_e32 v192, -1.0, v186
	v_fma_f32 v192, v10, v192, 1.0
	v_mul_f32_e32 v178, v210, v192
	v_add_f32_dpp v200, v200, v200 row_half_mirror row_mask:0xf bank_mask:0xf bound_ctrl:1
	v_add_f32_e32 v192, -1.0, v187
	v_fma_f32 v192, v11, v192, 1.0
	v_mul_f32_e32 v179, v211, v192
	v_add_f32_e32 v192, -1.0, v188
	v_fma_f32 v192, v12, v192, 1.0
	v_mul_f32_e32 v180, v212, v192
	v_add_f32_e32 v192, -1.0, v189
	v_fma_f32 v192, v13, v192, 1.0
	v_mul_f32_e32 v181, v213, v192
	v_add_f32_e32 v192, -1.0, v190
	v_fma_f32 v192, v14, v192, 1.0
	v_mul_f32_e32 v182, v214, v192
	v_add_f32_e32 v192, -1.0, v191
	v_fma_f32 v192, v15, v192, 1.0
	v_mul_f32_e32 v183, v215, v192
	v_max_f32_e32 v200, v200, v200
	v_max_f32_e32 v200, 0x179abe15, v200
	v_rsq_f32_e32 v201, v200
	v_mul_f32_e32 v192, v136, v176
	v_mul_f32_e32 v202, v16, v192
	v_mul_f32_e32 v160, v160, v201
	v_mul_f32_e32 v161, v161, v201
	v_mul_f32_e32 v162, v162, v201
	v_mul_f32_e32 v163, v163, v201
	v_mul_f32_e32 v164, v164, v201
	v_mul_f32_e32 v165, v165, v201
	v_mul_f32_e32 v166, v166, v201
	v_mul_f32_e32 v167, v167, v201
	v_mul_f32_e32 v168, v184, v160
	v_mul_f32_e32 v169, v185, v161
	v_mul_f32_e32 v170, v186, v162
	v_mul_f32_e32 v171, v187, v163
	v_mul_f32_e32 v172, v188, v164
	v_mul_f32_e32 v173, v189, v165
	v_mul_f32_e32 v174, v190, v166
	v_mul_f32_e32 v175, v191, v167
	ds_write_b128 v54, v[160:163] offset:20480
	ds_write_b128 v54, v[164:167] offset:20496
	ds_write_b128 v54, v[168:171] offset:20736
	ds_write_b128 v54, v[172:175] offset:20752
	ds_write_b128 v54, v[176:179] offset:20992
	ds_write_b128 v54, v[180:183] offset:21008
	ds_write_b128 v54, v[136:139] offset:21248
	ds_write_b128 v54, v[140:143] offset:21264
	ds_write_b128 v54, v[152:155] offset:21504
	ds_write_b128 v54, v[156:159] offset:21520
	v_mul_f32_e32 v192, v137, v177
	v_fmac_f32_e32 v202, v17, v192
	v_mul_f32_e32 v192, v138, v178
	v_fmac_f32_e32 v202, v18, v192
	v_mul_f32_e32 v192, v139, v179
	v_fmac_f32_e32 v202, v19, v192
	v_mul_f32_e32 v192, v140, v180
	v_fmac_f32_e32 v202, v20, v192
	v_mul_f32_e32 v192, v141, v181
	v_fmac_f32_e32 v202, v21, v192
	v_mul_f32_e32 v192, v142, v182
	v_fmac_f32_e32 v202, v22, v192
	v_mul_f32_e32 v192, v143, v183
	v_fmac_f32_e32 v202, v23, v192
	s_nop 1
	v_add_f32_dpp v202, v202, v202 quad_perm:[1,0,3,2] row_mask:0xf bank_mask:0xf bound_ctrl:1
	s_nop 1
	v_add_f32_dpp v202, v202, v202 quad_perm:[2,3,0,1] row_mask:0xf bank_mask:0xf bound_ctrl:1
	s_nop 1
	v_add_f32_dpp v202, v202, v202 row_half_mirror row_mask:0xf bank_mask:0xf bound_ctrl:1
	v_lshl_add_u32 v205, v56, 7, s60
	s_and_saveexec_b64 s[6:7], s[8:9]
	global_store_dword v205, v202, s[24:25]
	s_or_b64 exec, exec, s[6:7]
	v_add_u32_e32 v56, v59, v56
	s_waitcnt lgkmcnt(0)
	s_barrier
.Lmy_kp_loop:
	ds_read_b128 v[184:187], v55 offset:0
	ds_read_b128 v[188:191], v55 offset:16
	s_waitcnt vmcnt(9)
	v_lshlrev_b32_e32 v136, 16, v64
	v_lshlrev_b32_e32 v192, 16, v76
	v_lshlrev_b32_e32 v193, 16, v88
	v_add_f32_e32 v193, v193, v192
	v_fma_f32 v192, v193, 0.5, -v136
	v_fmac_f32_e32 v136, v24, v192
	v_and_b32_e32 v137, 0xffff0000, v64
	v_and_b32_e32 v192, 0xffff0000, v76
	v_and_b32_e32 v193, 0xffff0000, v88
	v_add_f32_e32 v193, v193, v192
	v_fma_f32 v192, v193, 0.5, -v137
	v_fmac_f32_e32 v137, v25, v192
	v_lshlrev_b32_e32 v138, 16, v65
	v_lshlrev_b32_e32 v192, 16, v77
	v_lshlrev_b32_e32 v193, 16, v89
	v_add_f32_e32 v193, v193, v192
	v_fma_f32 v192, v193, 0.5, -v138
	v_fmac_f32_e32 v138, v26, v192
	v_and_b32_e32 v139, 0xffff0000, v65
	v_and_b32_e32 v192, 0xffff0000, v77
	v_and_b32_e32 v193, 0xffff0000, v89
	v_add_f32_e32 v193, v193, v192
	v_fma_f32 v192, v193, 0.5, -v139
	v_fmac_f32_e32 v139, v27, v192
	v_lshlrev_b32_e32 v140, 16, v66
	v_lshlrev_b32_e32 v192, 16, v78
	v_lshlrev_b32_e32 v193, 16, v90
	v_add_f32_e32 v193, v193, v192
	v_fma_f32 v192, v193, 0.5, -v140
	v_fmac_f32_e32 v140, v28, v192
	v_and_b32_e32 v141, 0xffff0000, v66
	v_and_b32_e32 v192, 0xffff0000, v78
	v_and_b32_e32 v193, 0xffff0000, v90
	v_add_f32_e32 v193, v193, v192
	v_fma_f32 v192, v193, 0.5, -v141
	v_fmac_f32_e32 v141, v29, v192
	v_lshlrev_b32_e32 v142, 16, v67
	v_lshlrev_b32_e32 v192, 16, v79
	v_lshlrev_b32_e32 v193, 16, v91
	v_add_f32_e32 v193, v193, v192
	v_fma_f32 v192, v193, 0.5, -v142
	v_fmac_f32_e32 v142, v30, v192
	v_and_b32_e32 v143, 0xffff0000, v67
	v_and_b32_e32 v192, 0xffff0000, v79
	v_and_b32_e32 v193, 0xffff0000, v91
	v_add_f32_e32 v193, v193, v192
	v_fma_f32 v192, v193, 0.5, -v143
	v_fmac_f32_e32 v143, v31, v192
	v_lshlrev_b32_e32 v208, 16, v68
	v_lshlrev_b32_e32 v192, 16, v80
	v_lshlrev_b32_e32 v193, 16, v92
	v_add_f32_e32 v193, v193, v192
	v_fma_f32 v192, v193, 0.5, -v208
	v_fmac_f32_e32 v208, v32, v192
	v_and_b32_e32 v209, 0xffff0000, v68
	v_and_b32_e32 v192, 0xffff0000, v80
	v_and_b32_e32 v193, 0xffff0000, v92
	v_add_f32_e32 v193, v193, v192
	v_fma_f32 v192, v193, 0.5, -v209
	v_fmac_f32_e32 v209, v33, v192
	v_lshlrev_b32_e32 v210, 16, v69
	v_lshlrev_b32_e32 v192, 16, v81
	v_lshlrev_b32_e32 v193, 16, v93
	v_add_f32_e32 v193, v193, v192
	v_fma_f32 v192, v193, 0.5, -v210
	v_fmac_f32_e32 v210, v34, v192
	v_and_b32_e32 v211, 0xffff0000, v69
	v_and_b32_e32 v192, 0xffff0000, v81
	v_and_b32_e32 v193, 0xffff0000, v93
	v_add_f32_e32 v193, v193, v192
	v_fma_f32 v192, v193, 0.5, -v211
	v_fmac_f32_e32 v211, v35, v192
	v_lshlrev_b32_e32 v212, 16, v70
	v_lshlrev_b32_e32 v192, 16, v82
	v_lshlrev_b32_e32 v193, 16, v94
	v_add_f32_e32 v193, v193, v192
	v_fma_f32 v192, v193, 0.5, -v212
	v_fmac_f32_e32 v212, v36, v192
	v_and_b32_e32 v213, 0xffff0000, v70
	v_and_b32_e32 v192, 0xffff0000, v82
	v_and_b32_e32 v193, 0xffff0000, v94
	v_add_f32_e32 v193, v193, v192
	v_fma_f32 v192, v193, 0.5, -v213
	v_fmac_f32_e32 v213, v37, v192
	v_lshlrev_b32_e32 v214, 16, v71
	v_lshlrev_b32_e32 v192, 16, v83
	v_lshlrev_b32_e32 v193, 16, v95
	v_add_f32_e32 v193, v193, v192
	v_fma_f32 v192, v193, 0.5, -v214
	v_fmac_f32_e32 v214, v38, v192
	v_and_b32_e32 v215, 0xffff0000, v71
	v_and_b32_e32 v192, 0xffff0000, v83
	v_and_b32_e32 v193, 0xffff0000, v95
	v_add_f32_e32 v193, v193, v192
	v_fma_f32 v192, v193, 0.5, -v215
	v_fmac_f32_e32 v215, v39, v192
	v_lshlrev_b32_e32 v152, 16, v72
	v_lshlrev_b32_e32 v192, 16, v84
	v_lshlrev_b32_e32 v193, 16, v96
	v_add_f32_e32 v193, v193, v192
	v_fma_f32 v192, v193, 0.5, -v152
	v_fmac_f32_e32 v152, v40, v192
	v_and_b32_e32 v153, 0xffff0000, v72
	v_and_b32_e32 v192, 0xffff0000, v84
	v_and_b32_e32 v193, 0xffff0000, v96
	v_add_f32_e32 v193, v193, v192
	v_fma_f32 v192, v193, 0.5, -v153
	v_fmac_f32_e32 v153, v41, v192
	v_lshlrev_b32_e32 v154, 16, v73
	v_lshlrev_b32_e32 v192, 16, v85
	v_lshlrev_b32_e32 v193, 16, v97
	v_add_f32_e32 v193, v193, v192
	v_fma_f32 v192, v193, 0.5, -v154
	v_fmac_f32_e32 v154, v42, v192
	v_and_b32_e32 v155, 0xffff0000, v73
	v_and_b32_e32 v192, 0xffff0000, v85
	v_and_b32_e32 v193, 0xffff0000, v97
	v_add_f32_e32 v193, v193, v192
	v_fma_f32 v192, v193, 0.5, -v155
	v_fmac_f32_e32 v155, v43, v192
	v_lshlrev_b32_e32 v156, 16, v74
	v_lshlrev_b32_e32 v192, 16, v86
	v_lshlrev_b32_e32 v193, 16, v98
	v_add_f32_e32 v193, v193, v192
	v_fma_f32 v192, v193, 0.5, -v156
	v_fmac_f32_e32 v156, v44, v192
	v_and_b32_e32 v157, 0xffff0000, v74
	v_and_b32_e32 v192, 0xffff0000, v86
	v_and_b32_e32 v193, 0xffff0000, v98
	v_add_f32_e32 v193, v193, v192
	v_fma_f32 v192, v193, 0.5, -v157
	v_fmac_f32_e32 v157, v45, v192
	v_lshlrev_b32_e32 v158, 16, v75
	v_lshlrev_b32_e32 v192, 16, v87
	v_lshlrev_b32_e32 v193, 16, v99
	v_add_f32_e32 v193, v193, v192
	v_fma_f32 v192, v193, 0.5, -v158
	v_fmac_f32_e32 v158, v46, v192
	v_and_b32_e32 v159, 0xffff0000, v75
	v_and_b32_e32 v192, 0xffff0000, v87
	v_and_b32_e32 v193, 0xffff0000, v99
	v_add_f32_e32 v193, v193, v192
	v_fma_f32 v192, v193, 0.5, -v159
	v_fmac_f32_e32 v159, v47, v192
	v_add_u32_e32 v57, v59, v56
	v_add_u32_e32 v57, v59, v57
	v_cmp_lt_i32_e64 s[10:11], 0, v57
	v_cmp_gt_i32_e64 s[12:13], v58, v57
	v_mad_u32_u24 v205, v57, v53, v52
	s_nop 0
	v_cndmask_b32_e64 v206, 0, v53, s[10:11]
	v_cndmask_b32_e64 v207, 0, v53, s[12:13]
	v_cndmask_b32_e64 v60, 0, 1.0, s[10:11]
	v_cndmask_b32_e64 v61, 0, 1.0, s[12:13]
	v_sub_u32_e32 v206, v205, v206
	v_add_u32_e32 v207, v205, v207
	global_load_dwordx4 v[64:67], v205, s[72:73] offset:-2048
	global_load_dwordx4 v[68:71], v205, s[72:73]
	global_load_dwordx4 v[72:75], v205, s[72:73] offset:2048
	global_load_dwordx4 v[76:79], v206, s[72:73] offset:-2048
	global_load_dwordx4 v[80:83], v206, s[72:73]
	global_load_dwordx4 v[84:87], v206, s[72:73] offset:2048
	global_load_dwordx4 v[88:91], v207, s[72:73] offset:-2048
	global_load_dwordx4 v[92:95], v207, s[72:73]
	global_load_dwordx4 v[96:99], v207, s[72:73] offset:2048
	v_mul_f32_e32 v160, v0, v208
	v_mul_f32_e32 v161, v1, v209
	v_mul_f32_e32 v162, v2, v210
	v_mul_f32_e32 v163, v3, v211
	v_mul_f32_e32 v164, v4, v212
	v_mul_f32_e32 v165, v5, v213
	v_mul_f32_e32 v166, v6, v214
	v_mul_f32_e32 v167, v7, v215
	v_mul_f32_e32 v200, v160, v160
	v_fmac_f32_e32 v200, v161, v161
	v_fmac_f32_e32 v200, v162, v162
	v_fmac_f32_e32 v200, v163, v163
	v_fmac_f32_e32 v200, v164, v164
	v_fmac_f32_e32 v200, v165, v165
	v_fmac_f32_e32 v200, v166, v166
	v_fmac_f32_e32 v200, v167, v167
	s_waitcnt lgkmcnt(0)
	v_add_f32_e32 v192, -1.0, v184
	v_fma_f32 v192, v8, v192, 1.0
	v_mul_f32_e32 v176, v208, v192
	v_add_f32_dpp v200, v200, v200 quad_perm:[1,0,3,2] row_mask:0xf bank_mask:0xf bound_ctrl:1
	v_add_f32_e32 v192, -1.0, v185
	v_fma_f32 v192, v9, v192, 1.0
	v_mul_f32_e32 v177, v209, v192
	v_add_f32_dpp v200, v200, v200 quad_perm:[2,3,0,1] row_mask:0xf bank_mask:0xf bound_ctrl:1
	v_add_f32_e32 v192, -1.0, v186
	v_fma_f32 v192, v10, v192, 1.0
	v_mul_f32_e32 v178, v210, v192
	v_add_f32_dpp v200, v200, v200 row_half_mirror row_mask:0xf bank_mask:0xf bound_ctrl:1
	v_add_f32_e32 v192, -1.0, v187
	v_fma_f32 v192, v11, v192, 1.0
	v_mul_f32_e32 v179, v211, v192
	v_add_f32_e32 v192, -1.0, v188
	v_fma_f32 v192, v12, v192, 1.0
	v_mul_f32_e32 v180, v212, v192
	v_add_f32_e32 v192, -1.0, v189
	v_fma_f32 v192, v13, v192, 1.0
	v_mul_f32_e32 v181, v213, v192
	v_add_f32_e32 v192, -1.0, v190
	v_fma_f32 v192, v14, v192, 1.0
	v_mul_f32_e32 v182, v214, v192
	v_add_f32_e32 v192, -1.0, v191
	v_fma_f32 v192, v15, v192, 1.0
	v_mul_f32_e32 v183, v215, v192
	v_max_f32_e32 v200, v200, v200
	v_max_f32_e32 v200, 0x179abe15, v200
	v_rsq_f32_e32 v201, v200
	v_mul_f32_e32 v192, v136, v176
	v_mul_f32_e32 v202, v16, v192
	v_mul_f32_e32 v160, v160, v201
	v_mul_f32_e32 v161, v161, v201
	v_mul_f32_e32 v162, v162, v201
	v_mul_f32_e32 v163, v163, v201
	v_mul_f32_e32 v164, v164, v201
	v_mul_f32_e32 v165, v165, v201
	v_mul_f32_e32 v166, v166, v201
	v_mul_f32_e32 v167, v167, v201
	v_mul_f32_e32 v168, v184, v160
	v_mul_f32_e32 v169, v185, v161
	v_mul_f32_e32 v170, v186, v162
	v_mul_f32_e32 v171, v187, v163
	v_mul_f32_e32 v172, v188, v164
	v_mul_f32_e32 v173, v189, v165
	v_mul_f32_e32 v174, v190, v166
	v_mul_f32_e32 v175, v191, v167
	ds_write_b128 v54, v[160:163] offset:0
	ds_write_b128 v54, v[164:167] offset:16
	ds_write_b128 v54, v[168:171] offset:256
	ds_write_b128 v54, v[172:175] offset:272
	ds_write_b128 v54, v[176:179] offset:512
	ds_write_b128 v54, v[180:183] offset:528
	ds_write_b128 v54, v[136:139] offset:768
	ds_write_b128 v54, v[140:143] offset:784
	ds_write_b128 v54, v[152:155] offset:1024
	ds_write_b128 v54, v[156:159] offset:1040
	v_mul_f32_e32 v192, v137, v177
	v_fmac_f32_e32 v202, v17, v192
	v_mul_f32_e32 v192, v138, v178
	v_fmac_f32_e32 v202, v18, v192
	v_mul_f32_e32 v192, v139, v179
	v_fmac_f32_e32 v202, v19, v192
	v_mul_f32_e32 v192, v140, v180
	v_fmac_f32_e32 v202, v20, v192
	v_mul_f32_e32 v192, v141, v181
	v_fmac_f32_e32 v202, v21, v192
	v_mul_f32_e32 v192, v142, v182
	v_fmac_f32_e32 v202, v22, v192
	v_mul_f32_e32 v192, v143, v183
	v_fmac_f32_e32 v202, v23, v192
	s_nop 1
	v_add_f32_dpp v202, v202, v202 quad_perm:[1,0,3,2] row_mask:0xf bank_mask:0xf bound_ctrl:1
	s_nop 1
	v_add_f32_dpp v202, v202, v202 quad_perm:[2,3,0,1] row_mask:0xf bank_mask:0xf bound_ctrl:1
	s_nop 1
	v_add_f32_dpp v202, v202, v202 row_half_mirror row_mask:0xf bank_mask:0xf bound_ctrl:1
	v_lshl_add_u32 v205, v56, 7, s60
	s_and_saveexec_b64 s[6:7], s[8:9]
	global_store_dword v205, v202, s[24:25]
	s_or_b64 exec, exec, s[6:7]
	v_add_u32_e32 v56, v59, v56
	s_waitcnt lgkmcnt(0)
	s_barrier
	ds_read_b128 v[184:187], v55 offset:4096
	ds_read_b128 v[188:191], v55 offset:4112
	s_waitcnt vmcnt(9)
	v_lshlrev_b32_e32 v136, 16, v100
	v_lshlrev_b32_e32 v192, 16, v112
	v_lshlrev_b32_e32 v193, 16, v124
	v_add_f32_e32 v193, v193, v192
	v_fma_f32 v192, v193, 0.5, -v136
	v_fmac_f32_e32 v136, v24, v192
	v_and_b32_e32 v137, 0xffff0000, v100
	v_and_b32_e32 v192, 0xffff0000, v112
	v_and_b32_e32 v193, 0xffff0000, v124
	v_add_f32_e32 v193, v193, v192
	v_fma_f32 v192, v193, 0.5, -v137
	v_fmac_f32_e32 v137, v25, v192
	v_lshlrev_b32_e32 v138, 16, v101
	v_lshlrev_b32_e32 v192, 16, v113
	v_lshlrev_b32_e32 v193, 16, v125
	v_add_f32_e32 v193, v193, v192
	v_fma_f32 v192, v193, 0.5, -v138
	v_fmac_f32_e32 v138, v26, v192
	v_and_b32_e32 v139, 0xffff0000, v101
	v_and_b32_e32 v192, 0xffff0000, v113
	v_and_b32_e32 v193, 0xffff0000, v125
	v_add_f32_e32 v193, v193, v192
	v_fma_f32 v192, v193, 0.5, -v139
	v_fmac_f32_e32 v139, v27, v192
	v_lshlrev_b32_e32 v140, 16, v102
	v_lshlrev_b32_e32 v192, 16, v114
	v_lshlrev_b32_e32 v193, 16, v126
	v_add_f32_e32 v193, v193, v192
	v_fma_f32 v192, v193, 0.5, -v140
	v_fmac_f32_e32 v140, v28, v192
	v_and_b32_e32 v141, 0xffff0000, v102
	v_and_b32_e32 v192, 0xffff0000, v114
	v_and_b32_e32 v193, 0xffff0000, v126
	v_add_f32_e32 v193, v193, v192
	v_fma_f32 v192, v193, 0.5, -v141
	v_fmac_f32_e32 v141, v29, v192
	v_lshlrev_b32_e32 v142, 16, v103
	v_lshlrev_b32_e32 v192, 16, v115
	v_lshlrev_b32_e32 v193, 16, v127
	v_add_f32_e32 v193, v193, v192
	v_fma_f32 v192, v193, 0.5, -v142
	v_fmac_f32_e32 v142, v30, v192
	v_and_b32_e32 v143, 0xffff0000, v103
	v_and_b32_e32 v192, 0xffff0000, v115
	v_and_b32_e32 v193, 0xffff0000, v127
	v_add_f32_e32 v193, v193, v192
	v_fma_f32 v192, v193, 0.5, -v143
	v_fmac_f32_e32 v143, v31, v192
	v_lshlrev_b32_e32 v208, 16, v104
	v_lshlrev_b32_e32 v192, 16, v116
	v_lshlrev_b32_e32 v193, 16, v128
	v_add_f32_e32 v193, v193, v192
	v_fma_f32 v192, v193, 0.5, -v208
	v_fmac_f32_e32 v208, v32, v192
	v_and_b32_e32 v209, 0xffff0000, v104
	v_and_b32_e32 v192, 0xffff0000, v116
	v_and_b32_e32 v193, 0xffff0000, v128
	v_add_f32_e32 v193, v193, v192
	v_fma_f32 v192, v193, 0.5, -v209
	v_fmac_f32_e32 v209, v33, v192
	v_lshlrev_b32_e32 v210, 16, v105
	v_lshlrev_b32_e32 v192, 16, v117
	v_lshlrev_b32_e32 v193, 16, v129
	v_add_f32_e32 v193, v193, v192
	v_fma_f32 v192, v193, 0.5, -v210
	v_fmac_f32_e32 v210, v34, v192
	v_and_b32_e32 v211, 0xffff0000, v105
	v_and_b32_e32 v192, 0xffff0000, v117
	v_and_b32_e32 v193, 0xffff0000, v129
	v_add_f32_e32 v193, v193, v192
	v_fma_f32 v192, v193, 0.5, -v211
	v_fmac_f32_e32 v211, v35, v192
	v_lshlrev_b32_e32 v212, 16, v106
	v_lshlrev_b32_e32 v192, 16, v118
	v_lshlrev_b32_e32 v193, 16, v130
	v_add_f32_e32 v193, v193, v192
	v_fma_f32 v192, v193, 0.5, -v212
	v_fmac_f32_e32 v212, v36, v192
	v_and_b32_e32 v213, 0xffff0000, v106
	v_and_b32_e32 v192, 0xffff0000, v118
	v_and_b32_e32 v193, 0xffff0000, v130
	v_add_f32_e32 v193, v193, v192
	v_fma_f32 v192, v193, 0.5, -v213
	v_fmac_f32_e32 v213, v37, v192
	v_lshlrev_b32_e32 v214, 16, v107
	v_lshlrev_b32_e32 v192, 16, v119
	v_lshlrev_b32_e32 v193, 16, v131
	v_add_f32_e32 v193, v193, v192
	v_fma_f32 v192, v193, 0.5, -v214
	v_fmac_f32_e32 v214, v38, v192
	v_and_b32_e32 v215, 0xffff0000, v107
	v_and_b32_e32 v192, 0xffff0000, v119
	v_and_b32_e32 v193, 0xffff0000, v131
	v_add_f32_e32 v193, v193, v192
	v_fma_f32 v192, v193, 0.5, -v215
	v_fmac_f32_e32 v215, v39, v192
	v_lshlrev_b32_e32 v152, 16, v108
	v_lshlrev_b32_e32 v192, 16, v120
	v_lshlrev_b32_e32 v193, 16, v132
	v_add_f32_e32 v193, v193, v192
	v_fma_f32 v192, v193, 0.5, -v152
	v_fmac_f32_e32 v152, v40, v192
	v_and_b32_e32 v153, 0xffff0000, v108
	v_and_b32_e32 v192, 0xffff0000, v120
	v_and_b32_e32 v193, 0xffff0000, v132
	v_add_f32_e32 v193, v193, v192
	v_fma_f32 v192, v193, 0.5, -v153
	v_fmac_f32_e32 v153, v41, v192
	v_lshlrev_b32_e32 v154, 16, v109
	v_lshlrev_b32_e32 v192, 16, v121
	v_lshlrev_b32_e32 v193, 16, v133
	v_add_f32_e32 v193, v193, v192
	v_fma_f32 v192, v193, 0.5, -v154
	v_fmac_f32_e32 v154, v42, v192
	v_and_b32_e32 v155, 0xffff0000, v109
	v_and_b32_e32 v192, 0xffff0000, v121
	v_and_b32_e32 v193, 0xffff0000, v133
	v_add_f32_e32 v193, v193, v192
	v_fma_f32 v192, v193, 0.5, -v155
	v_fmac_f32_e32 v155, v43, v192
	v_lshlrev_b32_e32 v156, 16, v110
	v_lshlrev_b32_e32 v192, 16, v122
	v_lshlrev_b32_e32 v193, 16, v134
	v_add_f32_e32 v193, v193, v192
	v_fma_f32 v192, v193, 0.5, -v156
	v_fmac_f32_e32 v156, v44, v192
	v_and_b32_e32 v157, 0xffff0000, v110
	v_and_b32_e32 v192, 0xffff0000, v122
	v_and_b32_e32 v193, 0xffff0000, v134
	v_add_f32_e32 v193, v193, v192
	v_fma_f32 v192, v193, 0.5, -v157
	v_fmac_f32_e32 v157, v45, v192
	v_lshlrev_b32_e32 v158, 16, v111
	v_lshlrev_b32_e32 v192, 16, v123
	v_lshlrev_b32_e32 v193, 16, v135
	v_add_f32_e32 v193, v193, v192
	v_fma_f32 v192, v193, 0.5, -v158
	v_fmac_f32_e32 v158, v46, v192
	v_and_b32_e32 v159, 0xffff0000, v111
	v_and_b32_e32 v192, 0xffff0000, v123
	v_and_b32_e32 v193, 0xffff0000, v135
	v_add_f32_e32 v193, v193, v192
	v_fma_f32 v192, v193, 0.5, -v159
	v_fmac_f32_e32 v159, v47, v192
	v_add_u32_e32 v57, v59, v56
	v_add_u32_e32 v57, v59, v57
	v_cmp_lt_i32_e64 s[10:11], 0, v57
	v_cmp_gt_i32_e64 s[12:13], v58, v57
	v_mad_u32_u24 v205, v57, v53, v52
	s_nop 0
	v_cndmask_b32_e64 v206, 0, v53, s[10:11]
	v_cndmask_b32_e64 v207, 0, v53, s[12:13]
	v_cndmask_b32_e64 v62, 0, 1.0, s[10:11]
	v_cndmask_b32_e64 v63, 0, 1.0, s[12:13]
	v_sub_u32_e32 v206, v205, v206
	v_add_u32_e32 v207, v205, v207
	global_load_dwordx4 v[100:103], v205, s[72:73] offset:-2048
	global_load_dwordx4 v[104:107], v205, s[72:73]
	global_load_dwordx4 v[108:111], v205, s[72:73] offset:2048
	global_load_dwordx4 v[112:115], v206, s[72:73] offset:-2048
	global_load_dwordx4 v[116:119], v206, s[72:73]
	global_load_dwordx4 v[120:123], v206, s[72:73] offset:2048
	global_load_dwordx4 v[124:127], v207, s[72:73] offset:-2048
	global_load_dwordx4 v[128:131], v207, s[72:73]
	global_load_dwordx4 v[132:135], v207, s[72:73] offset:2048
	v_mul_f32_e32 v160, v0, v208
	v_mul_f32_e32 v161, v1, v209
	v_mul_f32_e32 v162, v2, v210
	v_mul_f32_e32 v163, v3, v211
	v_mul_f32_e32 v164, v4, v212
	v_mul_f32_e32 v165, v5, v213
	v_mul_f32_e32 v166, v6, v214
	v_mul_f32_e32 v167, v7, v215
	v_mul_f32_e32 v200, v160, v160
	v_fmac_f32_e32 v200, v161, v161
	v_fmac_f32_e32 v200, v162, v162
	v_fmac_f32_e32 v200, v163, v163
	v_fmac_f32_e32 v200, v164, v164
	v_fmac_f32_e32 v200, v165, v165
	v_fmac_f32_e32 v200, v166, v166
	v_fmac_f32_e32 v200, v167, v167
	s_waitcnt lgkmcnt(0)
	v_add_f32_e32 v192, -1.0, v184
	v_fma_f32 v192, v8, v192, 1.0
	v_mul_f32_e32 v176, v208, v192
	v_add_f32_dpp v200, v200, v200 quad_perm:[1,0,3,2] row_mask:0xf bank_mask:0xf bound_ctrl:1
	v_add_f32_e32 v192, -1.0, v185
	v_fma_f32 v192, v9, v192, 1.0
	v_mul_f32_e32 v177, v209, v192
	v_add_f32_dpp v200, v200, v200 quad_perm:[2,3,0,1] row_mask:0xf bank_mask:0xf bound_ctrl:1
	v_add_f32_e32 v192, -1.0, v186
	v_fma_f32 v192, v10, v192, 1.0
	v_mul_f32_e32 v178, v210, v192
	v_add_f32_dpp v200, v200, v200 row_half_mirror row_mask:0xf bank_mask:0xf bound_ctrl:1
	v_add_f32_e32 v192, -1.0, v187
	v_fma_f32 v192, v11, v192, 1.0
	v_mul_f32_e32 v179, v211, v192
	v_add_f32_e32 v192, -1.0, v188
	v_fma_f32 v192, v12, v192, 1.0
	v_mul_f32_e32 v180, v212, v192
	v_add_f32_e32 v192, -1.0, v189
	v_fma_f32 v192, v13, v192, 1.0
	v_mul_f32_e32 v181, v213, v192
	v_add_f32_e32 v192, -1.0, v190
	v_fma_f32 v192, v14, v192, 1.0
	v_mul_f32_e32 v182, v214, v192
	v_add_f32_e32 v192, -1.0, v191
	v_fma_f32 v192, v15, v192, 1.0
	v_mul_f32_e32 v183, v215, v192
	v_max_f32_e32 v200, v200, v200
	v_max_f32_e32 v200, 0x179abe15, v200
	v_rsq_f32_e32 v201, v200
	v_mul_f32_e32 v192, v136, v176
	v_mul_f32_e32 v202, v16, v192
	v_mul_f32_e32 v160, v160, v201
	v_mul_f32_e32 v161, v161, v201
	v_mul_f32_e32 v162, v162, v201
	v_mul_f32_e32 v163, v163, v201
	v_mul_f32_e32 v164, v164, v201
	v_mul_f32_e32 v165, v165, v201
	v_mul_f32_e32 v166, v166, v201
	v_mul_f32_e32 v167, v167, v201
	v_mul_f32_e32 v168, v184, v160
	v_mul_f32_e32 v169, v185, v161
	v_mul_f32_e32 v170, v186, v162
	v_mul_f32_e32 v171, v187, v163
	v_mul_f32_e32 v172, v188, v164
	v_mul_f32_e32 v173, v189, v165
	v_mul_f32_e32 v174, v190, v166
	v_mul_f32_e32 v175, v191, v167
	ds_write_b128 v54, v[160:163] offset:20480
	ds_write_b128 v54, v[164:167] offset:20496
	ds_write_b128 v54, v[168:171] offset:20736
	ds_write_b128 v54, v[172:175] offset:20752
	ds_write_b128 v54, v[176:179] offset:20992
	ds_write_b128 v54, v[180:183] offset:21008
	ds_write_b128 v54, v[136:139] offset:21248
	ds_write_b128 v54, v[140:143] offset:21264
	ds_write_b128 v54, v[152:155] offset:21504
	ds_write_b128 v54, v[156:159] offset:21520
	v_mul_f32_e32 v192, v137, v177
	v_fmac_f32_e32 v202, v17, v192
	v_mul_f32_e32 v192, v138, v178
	v_fmac_f32_e32 v202, v18, v192
	v_mul_f32_e32 v192, v139, v179
	v_fmac_f32_e32 v202, v19, v192
	v_mul_f32_e32 v192, v140, v180
	v_fmac_f32_e32 v202, v20, v192
	v_mul_f32_e32 v192, v141, v181
	v_fmac_f32_e32 v202, v21, v192
	v_mul_f32_e32 v192, v142, v182
	v_fmac_f32_e32 v202, v22, v192
	v_mul_f32_e32 v192, v143, v183
	v_fmac_f32_e32 v202, v23, v192
	s_nop 1
	v_add_f32_dpp v202, v202, v202 quad_perm:[1,0,3,2] row_mask:0xf bank_mask:0xf bound_ctrl:1
	s_nop 1
	v_add_f32_dpp v202, v202, v202 quad_perm:[2,3,0,1] row_mask:0xf bank_mask:0xf bound_ctrl:1
	s_nop 1
	v_add_f32_dpp v202, v202, v202 row_half_mirror row_mask:0xf bank_mask:0xf bound_ctrl:1
	v_lshl_add_u32 v205, v56, 7, s60
	s_and_saveexec_b64 s[6:7], s[8:9]
	global_store_dword v205, v202, s[24:25]
	s_or_b64 exec, exec, s[6:7]
	v_add_u32_e32 v56, v59, v56
	s_waitcnt lgkmcnt(0)
	s_barrier
	s_add_i32 s66, s66, 2
	s_cmp_lt_u32 s66, 1023
	s_cbranch_scc1 .Lmy_kp_loop
	ds_read_b128 v[184:187], v55 offset:0
	ds_read_b128 v[188:191], v55 offset:16
	s_waitcnt vmcnt(9)
	v_lshlrev_b32_e32 v136, 16, v64
	v_lshlrev_b32_e32 v192, 16, v76
	v_lshlrev_b32_e32 v193, 16, v88
	v_mul_f32_e32 v193, v61, v193
	v_fmac_f32_e32 v193, v60, v192
	v_fma_f32 v192, v193, 0.5, -v136
	v_fmac_f32_e32 v136, v24, v192
	v_and_b32_e32 v137, 0xffff0000, v64
	v_and_b32_e32 v192, 0xffff0000, v76
	v_and_b32_e32 v193, 0xffff0000, v88
	v_mul_f32_e32 v193, v61, v193
	v_fmac_f32_e32 v193, v60, v192
	v_fma_f32 v192, v193, 0.5, -v137
	v_fmac_f32_e32 v137, v25, v192
	v_lshlrev_b32_e32 v138, 16, v65
	v_lshlrev_b32_e32 v192, 16, v77
	v_lshlrev_b32_e32 v193, 16, v89
	v_mul_f32_e32 v193, v61, v193
	v_fmac_f32_e32 v193, v60, v192
	v_fma_f32 v192, v193, 0.5, -v138
	v_fmac_f32_e32 v138, v26, v192
	v_and_b32_e32 v139, 0xffff0000, v65
	v_and_b32_e32 v192, 0xffff0000, v77
	v_and_b32_e32 v193, 0xffff0000, v89
	v_mul_f32_e32 v193, v61, v193
	v_fmac_f32_e32 v193, v60, v192
	v_fma_f32 v192, v193, 0.5, -v139
	v_fmac_f32_e32 v139, v27, v192
	v_lshlrev_b32_e32 v140, 16, v66
	v_lshlrev_b32_e32 v192, 16, v78
	v_lshlrev_b32_e32 v193, 16, v90
	v_mul_f32_e32 v193, v61, v193
	v_fmac_f32_e32 v193, v60, v192
	v_fma_f32 v192, v193, 0.5, -v140
	v_fmac_f32_e32 v140, v28, v192
	v_and_b32_e32 v141, 0xffff0000, v66
	v_and_b32_e32 v192, 0xffff0000, v78
	v_and_b32_e32 v193, 0xffff0000, v90
	v_mul_f32_e32 v193, v61, v193
	v_fmac_f32_e32 v193, v60, v192
	v_fma_f32 v192, v193, 0.5, -v141
	v_fmac_f32_e32 v141, v29, v192
	v_lshlrev_b32_e32 v142, 16, v67
	v_lshlrev_b32_e32 v192, 16, v79
	v_lshlrev_b32_e32 v193, 16, v91
	v_mul_f32_e32 v193, v61, v193
	v_fmac_f32_e32 v193, v60, v192
	v_fma_f32 v192, v193, 0.5, -v142
	v_fmac_f32_e32 v142, v30, v192
	v_and_b32_e32 v143, 0xffff0000, v67
	v_and_b32_e32 v192, 0xffff0000, v79
	v_and_b32_e32 v193, 0xffff0000, v91
	v_mul_f32_e32 v193, v61, v193
	v_fmac_f32_e32 v193, v60, v192
	v_fma_f32 v192, v193, 0.5, -v143
	v_fmac_f32_e32 v143, v31, v192
	v_lshlrev_b32_e32 v208, 16, v68
	v_lshlrev_b32_e32 v192, 16, v80
	v_lshlrev_b32_e32 v193, 16, v92
	v_mul_f32_e32 v193, v61, v193
	v_fmac_f32_e32 v193, v60, v192
	v_fma_f32 v192, v193, 0.5, -v208
	v_fmac_f32_e32 v208, v32, v192
	v_and_b32_e32 v209, 0xffff0000, v68
	v_and_b32_e32 v192, 0xffff0000, v80
	v_and_b32_e32 v193, 0xffff0000, v92
	v_mul_f32_e32 v193, v61, v193
	v_fmac_f32_e32 v193, v60, v192
	v_fma_f32 v192, v193, 0.5, -v209
	v_fmac_f32_e32 v209, v33, v192
	v_lshlrev_b32_e32 v210, 16, v69
	v_lshlrev_b32_e32 v192, 16, v81
	v_lshlrev_b32_e32 v193, 16, v93
	v_mul_f32_e32 v193, v61, v193
	v_fmac_f32_e32 v193, v60, v192
	v_fma_f32 v192, v193, 0.5, -v210
	v_fmac_f32_e32 v210, v34, v192
	v_and_b32_e32 v211, 0xffff0000, v69
	v_and_b32_e32 v192, 0xffff0000, v81
	v_and_b32_e32 v193, 0xffff0000, v93
	v_mul_f32_e32 v193, v61, v193
	v_fmac_f32_e32 v193, v60, v192
	v_fma_f32 v192, v193, 0.5, -v211
	v_fmac_f32_e32 v211, v35, v192
	v_lshlrev_b32_e32 v212, 16, v70
	v_lshlrev_b32_e32 v192, 16, v82
	v_lshlrev_b32_e32 v193, 16, v94
	v_mul_f32_e32 v193, v61, v193
	v_fmac_f32_e32 v193, v60, v192
	v_fma_f32 v192, v193, 0.5, -v212
	v_fmac_f32_e32 v212, v36, v192
	v_and_b32_e32 v213, 0xffff0000, v70
	v_and_b32_e32 v192, 0xffff0000, v82
	v_and_b32_e32 v193, 0xffff0000, v94
	v_mul_f32_e32 v193, v61, v193
	v_fmac_f32_e32 v193, v60, v192
	v_fma_f32 v192, v193, 0.5, -v213
	v_fmac_f32_e32 v213, v37, v192
	v_lshlrev_b32_e32 v214, 16, v71
	v_lshlrev_b32_e32 v192, 16, v83
	v_lshlrev_b32_e32 v193, 16, v95
	v_mul_f32_e32 v193, v61, v193
	v_fmac_f32_e32 v193, v60, v192
	v_fma_f32 v192, v193, 0.5, -v214
	v_fmac_f32_e32 v214, v38, v192
	v_and_b32_e32 v215, 0xffff0000, v71
	v_and_b32_e32 v192, 0xffff0000, v83
	v_and_b32_e32 v193, 0xffff0000, v95
	v_mul_f32_e32 v193, v61, v193
	v_fmac_f32_e32 v193, v60, v192
	v_fma_f32 v192, v193, 0.5, -v215
	v_fmac_f32_e32 v215, v39, v192
	v_lshlrev_b32_e32 v152, 16, v72
	v_lshlrev_b32_e32 v192, 16, v84
	v_lshlrev_b32_e32 v193, 16, v96
	v_mul_f32_e32 v193, v61, v193
	v_fmac_f32_e32 v193, v60, v192
	v_fma_f32 v192, v193, 0.5, -v152
	v_fmac_f32_e32 v152, v40, v192
	v_and_b32_e32 v153, 0xffff0000, v72
	v_and_b32_e32 v192, 0xffff0000, v84
	v_and_b32_e32 v193, 0xffff0000, v96
	v_mul_f32_e32 v193, v61, v193
	v_fmac_f32_e32 v193, v60, v192
	v_fma_f32 v192, v193, 0.5, -v153
	v_fmac_f32_e32 v153, v41, v192
	v_lshlrev_b32_e32 v154, 16, v73
	v_lshlrev_b32_e32 v192, 16, v85
	v_lshlrev_b32_e32 v193, 16, v97
	v_mul_f32_e32 v193, v61, v193
	v_fmac_f32_e32 v193, v60, v192
	v_fma_f32 v192, v193, 0.5, -v154
	v_fmac_f32_e32 v154, v42, v192
	v_and_b32_e32 v155, 0xffff0000, v73
	v_and_b32_e32 v192, 0xffff0000, v85
	v_and_b32_e32 v193, 0xffff0000, v97
	v_mul_f32_e32 v193, v61, v193
	v_fmac_f32_e32 v193, v60, v192
	v_fma_f32 v192, v193, 0.5, -v155
	v_fmac_f32_e32 v155, v43, v192
	v_lshlrev_b32_e32 v156, 16, v74
	v_lshlrev_b32_e32 v192, 16, v86
	v_lshlrev_b32_e32 v193, 16, v98
	v_mul_f32_e32 v193, v61, v193
	v_fmac_f32_e32 v193, v60, v192
	v_fma_f32 v192, v193, 0.5, -v156
	v_fmac_f32_e32 v156, v44, v192
	v_and_b32_e32 v157, 0xffff0000, v74
	v_and_b32_e32 v192, 0xffff0000, v86
	v_and_b32_e32 v193, 0xffff0000, v98
	v_mul_f32_e32 v193, v61, v193
	v_fmac_f32_e32 v193, v60, v192
	v_fma_f32 v192, v193, 0.5, -v157
	v_fmac_f32_e32 v157, v45, v192
	v_lshlrev_b32_e32 v158, 16, v75
	v_lshlrev_b32_e32 v192, 16, v87
	v_lshlrev_b32_e32 v193, 16, v99
	v_mul_f32_e32 v193, v61, v193
	v_fmac_f32_e32 v193, v60, v192
	v_fma_f32 v192, v193, 0.5, -v158
	v_fmac_f32_e32 v158, v46, v192
	v_and_b32_e32 v159, 0xffff0000, v75
	v_and_b32_e32 v192, 0xffff0000, v87
	v_and_b32_e32 v193, 0xffff0000, v99
	v_mul_f32_e32 v193, v61, v193
	v_fmac_f32_e32 v193, v60, v192
	v_fma_f32 v192, v193, 0.5, -v159
	v_fmac_f32_e32 v159, v47, v192
	v_mul_f32_e32 v160, v0, v208
	v_mul_f32_e32 v161, v1, v209
	v_mul_f32_e32 v162, v2, v210
	v_mul_f32_e32 v163, v3, v211
	v_mul_f32_e32 v164, v4, v212
	v_mul_f32_e32 v165, v5, v213
	v_mul_f32_e32 v166, v6, v214
	v_mul_f32_e32 v167, v7, v215
	v_mul_f32_e32 v200, v160, v160
	v_fmac_f32_e32 v200, v161, v161
	v_fmac_f32_e32 v200, v162, v162
	v_fmac_f32_e32 v200, v163, v163
	v_fmac_f32_e32 v200, v164, v164
	v_fmac_f32_e32 v200, v165, v165
	v_fmac_f32_e32 v200, v166, v166
	v_fmac_f32_e32 v200, v167, v167
	s_waitcnt lgkmcnt(0)
	v_add_f32_e32 v192, -1.0, v184
	v_fma_f32 v192, v8, v192, 1.0
	v_mul_f32_e32 v176, v208, v192
	v_add_f32_dpp v200, v200, v200 quad_perm:[1,0,3,2] row_mask:0xf bank_mask:0xf bound_ctrl:1
	v_add_f32_e32 v192, -1.0, v185
	v_fma_f32 v192, v9, v192, 1.0
	v_mul_f32_e32 v177, v209, v192
	v_add_f32_dpp v200, v200, v200 quad_perm:[2,3,0,1] row_mask:0xf bank_mask:0xf bound_ctrl:1
	v_add_f32_e32 v192, -1.0, v186
	v_fma_f32 v192, v10, v192, 1.0
	v_mul_f32_e32 v178, v210, v192
	v_add_f32_dpp v200, v200, v200 row_half_mirror row_mask:0xf bank_mask:0xf bound_ctrl:1
	v_add_f32_e32 v192, -1.0, v187
	v_fma_f32 v192, v11, v192, 1.0
	v_mul_f32_e32 v179, v211, v192
	v_add_f32_e32 v192, -1.0, v188
	v_fma_f32 v192, v12, v192, 1.0
	v_mul_f32_e32 v180, v212, v192
	v_add_f32_e32 v192, -1.0, v189
	v_fma_f32 v192, v13, v192, 1.0
	v_mul_f32_e32 v181, v213, v192
	v_add_f32_e32 v192, -1.0, v190
	v_fma_f32 v192, v14, v192, 1.0
	v_mul_f32_e32 v182, v214, v192
	v_add_f32_e32 v192, -1.0, v191
	v_fma_f32 v192, v15, v192, 1.0
	v_mul_f32_e32 v183, v215, v192
	v_max_f32_e32 v200, v200, v200
	v_max_f32_e32 v200, 0x179abe15, v200
	v_rsq_f32_e32 v201, v200
	v_mul_f32_e32 v192, v136, v176
	v_mul_f32_e32 v202, v16, v192
	v_mul_f32_e32 v160, v160, v201
	v_mul_f32_e32 v161, v161, v201
	v_mul_f32_e32 v162, v162, v201
	v_mul_f32_e32 v163, v163, v201
	v_mul_f32_e32 v164, v164, v201
	v_mul_f32_e32 v165, v165, v201
	v_mul_f32_e32 v166, v166, v201
	v_mul_f32_e32 v167, v167, v201
	v_mul_f32_e32 v168, v184, v160
	v_mul_f32_e32 v169, v185, v161
	v_mul_f32_e32 v170, v186, v162
	v_mul_f32_e32 v171, v187, v163
	v_mul_f32_e32 v172, v188, v164
	v_mul_f32_e32 v173, v189, v165
	v_mul_f32_e32 v174, v190, v166
	v_mul_f32_e32 v175, v191, v167
	ds_write_b128 v54, v[160:163] offset:0
	ds_write_b128 v54, v[164:167] offset:16
	ds_write_b128 v54, v[168:171] offset:256
	ds_write_b128 v54, v[172:175] offset:272
	ds_write_b128 v54, v[176:179] offset:512
	ds_write_b128 v54, v[180:183] offset:528
	ds_write_b128 v54, v[136:139] offset:768
	ds_write_b128 v54, v[140:143] offset:784
	ds_write_b128 v54, v[152:155] offset:1024
	ds_write_b128 v54, v[156:159] offset:1040
	v_mul_f32_e32 v192, v137, v177
	v_fmac_f32_e32 v202, v17, v192
	v_mul_f32_e32 v192, v138, v178
	v_fmac_f32_e32 v202, v18, v192
	v_mul_f32_e32 v192, v139, v179
	v_fmac_f32_e32 v202, v19, v192
	v_mul_f32_e32 v192, v140, v180
	v_fmac_f32_e32 v202, v20, v192
	v_mul_f32_e32 v192, v141, v181
	v_fmac_f32_e32 v202, v21, v192
	v_mul_f32_e32 v192, v142, v182
	v_fmac_f32_e32 v202, v22, v192
	v_mul_f32_e32 v192, v143, v183
	v_fmac_f32_e32 v202, v23, v192
	s_nop 1
	v_add_f32_dpp v202, v202, v202 quad_perm:[1,0,3,2] row_mask:0xf bank_mask:0xf bound_ctrl:1
	s_nop 1
	v_add_f32_dpp v202, v202, v202 quad_perm:[2,3,0,1] row_mask:0xf bank_mask:0xf bound_ctrl:1
	s_nop 1
	v_add_f32_dpp v202, v202, v202 row_half_mirror row_mask:0xf bank_mask:0xf bound_ctrl:1
	v_lshl_add_u32 v205, v56, 7, s60
	s_and_saveexec_b64 s[6:7], s[8:9]
	global_store_dword v205, v202, s[24:25]
	s_or_b64 exec, exec, s[6:7]
	v_add_u32_e32 v56, v59, v56
	s_waitcnt lgkmcnt(0)
	s_barrier
	ds_read_b128 v[184:187], v55 offset:4096
	ds_read_b128 v[188:191], v55 offset:4112
	s_waitcnt vmcnt(0)
	v_lshlrev_b32_e32 v136, 16, v100
	v_lshlrev_b32_e32 v192, 16, v112
	v_lshlrev_b32_e32 v193, 16, v124
	v_mul_f32_e32 v193, v63, v193
	v_fmac_f32_e32 v193, v62, v192
	v_fma_f32 v192, v193, 0.5, -v136
	v_fmac_f32_e32 v136, v24, v192
	v_and_b32_e32 v137, 0xffff0000, v100
	v_and_b32_e32 v192, 0xffff0000, v112
	v_and_b32_e32 v193, 0xffff0000, v124
	v_mul_f32_e32 v193, v63, v193
	v_fmac_f32_e32 v193, v62, v192
	v_fma_f32 v192, v193, 0.5, -v137
	v_fmac_f32_e32 v137, v25, v192
	v_lshlrev_b32_e32 v138, 16, v101
	v_lshlrev_b32_e32 v192, 16, v113
	v_lshlrev_b32_e32 v193, 16, v125
	v_mul_f32_e32 v193, v63, v193
	v_fmac_f32_e32 v193, v62, v192
	v_fma_f32 v192, v193, 0.5, -v138
	v_fmac_f32_e32 v138, v26, v192
	v_and_b32_e32 v139, 0xffff0000, v101
	v_and_b32_e32 v192, 0xffff0000, v113
	v_and_b32_e32 v193, 0xffff0000, v125
	v_mul_f32_e32 v193, v63, v193
	v_fmac_f32_e32 v193, v62, v192
	v_fma_f32 v192, v193, 0.5, -v139
	v_fmac_f32_e32 v139, v27, v192
	v_lshlrev_b32_e32 v140, 16, v102
	v_lshlrev_b32_e32 v192, 16, v114
	v_lshlrev_b32_e32 v193, 16, v126
	v_mul_f32_e32 v193, v63, v193
	v_fmac_f32_e32 v193, v62, v192
	v_fma_f32 v192, v193, 0.5, -v140
	v_fmac_f32_e32 v140, v28, v192
	v_and_b32_e32 v141, 0xffff0000, v102
	v_and_b32_e32 v192, 0xffff0000, v114
	v_and_b32_e32 v193, 0xffff0000, v126
	v_mul_f32_e32 v193, v63, v193
	v_fmac_f32_e32 v193, v62, v192
	v_fma_f32 v192, v193, 0.5, -v141
	v_fmac_f32_e32 v141, v29, v192
	v_lshlrev_b32_e32 v142, 16, v103
	v_lshlrev_b32_e32 v192, 16, v115
	v_lshlrev_b32_e32 v193, 16, v127
	v_mul_f32_e32 v193, v63, v193
	v_fmac_f32_e32 v193, v62, v192
	v_fma_f32 v192, v193, 0.5, -v142
	v_fmac_f32_e32 v142, v30, v192
	v_and_b32_e32 v143, 0xffff0000, v103
	v_and_b32_e32 v192, 0xffff0000, v115
	v_and_b32_e32 v193, 0xffff0000, v127
	v_mul_f32_e32 v193, v63, v193
	v_fmac_f32_e32 v193, v62, v192
	v_fma_f32 v192, v193, 0.5, -v143
	v_fmac_f32_e32 v143, v31, v192
	v_lshlrev_b32_e32 v208, 16, v104
	v_lshlrev_b32_e32 v192, 16, v116
	v_lshlrev_b32_e32 v193, 16, v128
	v_mul_f32_e32 v193, v63, v193
	v_fmac_f32_e32 v193, v62, v192
	v_fma_f32 v192, v193, 0.5, -v208
	v_fmac_f32_e32 v208, v32, v192
	v_and_b32_e32 v209, 0xffff0000, v104
	v_and_b32_e32 v192, 0xffff0000, v116
	v_and_b32_e32 v193, 0xffff0000, v128
	v_mul_f32_e32 v193, v63, v193
	v_fmac_f32_e32 v193, v62, v192
	v_fma_f32 v192, v193, 0.5, -v209
	v_fmac_f32_e32 v209, v33, v192
	v_lshlrev_b32_e32 v210, 16, v105
	v_lshlrev_b32_e32 v192, 16, v117
	v_lshlrev_b32_e32 v193, 16, v129
	v_mul_f32_e32 v193, v63, v193
	v_fmac_f32_e32 v193, v62, v192
	v_fma_f32 v192, v193, 0.5, -v210
	v_fmac_f32_e32 v210, v34, v192
	v_and_b32_e32 v211, 0xffff0000, v105
	v_and_b32_e32 v192, 0xffff0000, v117
	v_and_b32_e32 v193, 0xffff0000, v129
	v_mul_f32_e32 v193, v63, v193
	v_fmac_f32_e32 v193, v62, v192
	v_fma_f32 v192, v193, 0.5, -v211
	v_fmac_f32_e32 v211, v35, v192
	v_lshlrev_b32_e32 v212, 16, v106
	v_lshlrev_b32_e32 v192, 16, v118
	v_lshlrev_b32_e32 v193, 16, v130
	v_mul_f32_e32 v193, v63, v193
	v_fmac_f32_e32 v193, v62, v192
	v_fma_f32 v192, v193, 0.5, -v212
	v_fmac_f32_e32 v212, v36, v192
	v_and_b32_e32 v213, 0xffff0000, v106
	v_and_b32_e32 v192, 0xffff0000, v118
	v_and_b32_e32 v193, 0xffff0000, v130
	v_mul_f32_e32 v193, v63, v193
	v_fmac_f32_e32 v193, v62, v192
	v_fma_f32 v192, v193, 0.5, -v213
	v_fmac_f32_e32 v213, v37, v192
	v_lshlrev_b32_e32 v214, 16, v107
	v_lshlrev_b32_e32 v192, 16, v119
	v_lshlrev_b32_e32 v193, 16, v131
	v_mul_f32_e32 v193, v63, v193
	v_fmac_f32_e32 v193, v62, v192
	v_fma_f32 v192, v193, 0.5, -v214
	v_fmac_f32_e32 v214, v38, v192
	v_and_b32_e32 v215, 0xffff0000, v107
	v_and_b32_e32 v192, 0xffff0000, v119
	v_and_b32_e32 v193, 0xffff0000, v131
	v_mul_f32_e32 v193, v63, v193
	v_fmac_f32_e32 v193, v62, v192
	v_fma_f32 v192, v193, 0.5, -v215
	v_fmac_f32_e32 v215, v39, v192
	v_lshlrev_b32_e32 v152, 16, v108
	v_lshlrev_b32_e32 v192, 16, v120
	v_lshlrev_b32_e32 v193, 16, v132
	v_mul_f32_e32 v193, v63, v193
	v_fmac_f32_e32 v193, v62, v192
	v_fma_f32 v192, v193, 0.5, -v152
	v_fmac_f32_e32 v152, v40, v192
	v_and_b32_e32 v153, 0xffff0000, v108
	v_and_b32_e32 v192, 0xffff0000, v120
	v_and_b32_e32 v193, 0xffff0000, v132
	v_mul_f32_e32 v193, v63, v193
	v_fmac_f32_e32 v193, v62, v192
	v_fma_f32 v192, v193, 0.5, -v153
	v_fmac_f32_e32 v153, v41, v192
	v_lshlrev_b32_e32 v154, 16, v109
	v_lshlrev_b32_e32 v192, 16, v121
	v_lshlrev_b32_e32 v193, 16, v133
	v_mul_f32_e32 v193, v63, v193
	v_fmac_f32_e32 v193, v62, v192
	v_fma_f32 v192, v193, 0.5, -v154
	v_fmac_f32_e32 v154, v42, v192
	v_and_b32_e32 v155, 0xffff0000, v109
	v_and_b32_e32 v192, 0xffff0000, v121
	v_and_b32_e32 v193, 0xffff0000, v133
	v_mul_f32_e32 v193, v63, v193
	v_fmac_f32_e32 v193, v62, v192
	v_fma_f32 v192, v193, 0.5, -v155
	v_fmac_f32_e32 v155, v43, v192
	v_lshlrev_b32_e32 v156, 16, v110
	v_lshlrev_b32_e32 v192, 16, v122
	v_lshlrev_b32_e32 v193, 16, v134
	v_mul_f32_e32 v193, v63, v193
	v_fmac_f32_e32 v193, v62, v192
	v_fma_f32 v192, v193, 0.5, -v156
	v_fmac_f32_e32 v156, v44, v192
	v_and_b32_e32 v157, 0xffff0000, v110
	v_and_b32_e32 v192, 0xffff0000, v122
	v_and_b32_e32 v193, 0xffff0000, v134
	v_mul_f32_e32 v193, v63, v193
	v_fmac_f32_e32 v193, v62, v192
	v_fma_f32 v192, v193, 0.5, -v157
	v_fmac_f32_e32 v157, v45, v192
	v_lshlrev_b32_e32 v158, 16, v111
	v_lshlrev_b32_e32 v192, 16, v123
	v_lshlrev_b32_e32 v193, 16, v135
	v_mul_f32_e32 v193, v63, v193
	v_fmac_f32_e32 v193, v62, v192
	v_fma_f32 v192, v193, 0.5, -v158
	v_fmac_f32_e32 v158, v46, v192
	v_and_b32_e32 v159, 0xffff0000, v111
	v_and_b32_e32 v192, 0xffff0000, v123
	v_and_b32_e32 v193, 0xffff0000, v135
	v_mul_f32_e32 v193, v63, v193
	v_fmac_f32_e32 v193, v62, v192
	v_fma_f32 v192, v193, 0.5, -v159
	v_fmac_f32_e32 v159, v47, v192
	v_mul_f32_e32 v160, v0, v208
	v_mul_f32_e32 v161, v1, v209
	v_mul_f32_e32 v162, v2, v210
	v_mul_f32_e32 v163, v3, v211
	v_mul_f32_e32 v164, v4, v212
	v_mul_f32_e32 v165, v5, v213
	v_mul_f32_e32 v166, v6, v214
	v_mul_f32_e32 v167, v7, v215
	v_mul_f32_e32 v200, v160, v160
	v_fmac_f32_e32 v200, v161, v161
	v_fmac_f32_e32 v200, v162, v162
	v_fmac_f32_e32 v200, v163, v163
	v_fmac_f32_e32 v200, v164, v164
	v_fmac_f32_e32 v200, v165, v165
	v_fmac_f32_e32 v200, v166, v166
	v_fmac_f32_e32 v200, v167, v167
	s_waitcnt lgkmcnt(0)
	v_add_f32_e32 v192, -1.0, v184
	v_fma_f32 v192, v8, v192, 1.0
	v_mul_f32_e32 v176, v208, v192
	v_add_f32_dpp v200, v200, v200 quad_perm:[1,0,3,2] row_mask:0xf bank_mask:0xf bound_ctrl:1
	v_add_f32_e32 v192, -1.0, v185
	v_fma_f32 v192, v9, v192, 1.0
	v_mul_f32_e32 v177, v209, v192
	v_add_f32_dpp v200, v200, v200 quad_perm:[2,3,0,1] row_mask:0xf bank_mask:0xf bound_ctrl:1
	v_add_f32_e32 v192, -1.0, v186
	v_fma_f32 v192, v10, v192, 1.0
	v_mul_f32_e32 v178, v210, v192
	v_add_f32_dpp v200, v200, v200 row_half_mirror row_mask:0xf bank_mask:0xf bound_ctrl:1
	v_add_f32_e32 v192, -1.0, v187
	v_fma_f32 v192, v11, v192, 1.0
	v_mul_f32_e32 v179, v211, v192
	v_add_f32_e32 v192, -1.0, v188
	v_fma_f32 v192, v12, v192, 1.0
	v_mul_f32_e32 v180, v212, v192
	v_add_f32_e32 v192, -1.0, v189
	v_fma_f32 v192, v13, v192, 1.0
	v_mul_f32_e32 v181, v213, v192
	v_add_f32_e32 v192, -1.0, v190
	v_fma_f32 v192, v14, v192, 1.0
	v_mul_f32_e32 v182, v214, v192
	v_add_f32_e32 v192, -1.0, v191
	v_fma_f32 v192, v15, v192, 1.0
	v_mul_f32_e32 v183, v215, v192
	v_max_f32_e32 v200, v200, v200
	v_max_f32_e32 v200, 0x179abe15, v200
	v_rsq_f32_e32 v201, v200
	v_mul_f32_e32 v192, v136, v176
	v_mul_f32_e32 v202, v16, v192
	v_mul_f32_e32 v160, v160, v201
	v_mul_f32_e32 v161, v161, v201
	v_mul_f32_e32 v162, v162, v201
	v_mul_f32_e32 v163, v163, v201
	v_mul_f32_e32 v164, v164, v201
	v_mul_f32_e32 v165, v165, v201
	v_mul_f32_e32 v166, v166, v201
	v_mul_f32_e32 v167, v167, v201
	v_mul_f32_e32 v168, v184, v160
	v_mul_f32_e32 v169, v185, v161
	v_mul_f32_e32 v170, v186, v162
	v_mul_f32_e32 v171, v187, v163
	v_mul_f32_e32 v172, v188, v164
	v_mul_f32_e32 v173, v189, v165
	v_mul_f32_e32 v174, v190, v166
	v_mul_f32_e32 v175, v191, v167
	ds_write_b128 v54, v[160:163] offset:20480
	ds_write_b128 v54, v[164:167] offset:20496
	ds_write_b128 v54, v[168:171] offset:20736
	ds_write_b128 v54, v[172:175] offset:20752
	ds_write_b128 v54, v[176:179] offset:20992
	ds_write_b128 v54, v[180:183] offset:21008
	ds_write_b128 v54, v[136:139] offset:21248
	ds_write_b128 v54, v[140:143] offset:21264
	ds_write_b128 v54, v[152:155] offset:21504
	ds_write_b128 v54, v[156:159] offset:21520
	v_mul_f32_e32 v192, v137, v177
	v_fmac_f32_e32 v202, v17, v192
	v_mul_f32_e32 v192, v138, v178
	v_fmac_f32_e32 v202, v18, v192
	v_mul_f32_e32 v192, v139, v179
	v_fmac_f32_e32 v202, v19, v192
	v_mul_f32_e32 v192, v140, v180
	v_fmac_f32_e32 v202, v20, v192
	v_mul_f32_e32 v192, v141, v181
	v_fmac_f32_e32 v202, v21, v192
	v_mul_f32_e32 v192, v142, v182
	v_fmac_f32_e32 v202, v22, v192
	v_mul_f32_e32 v192, v143, v183
	v_fmac_f32_e32 v202, v23, v192
	s_nop 1
	v_add_f32_dpp v202, v202, v202 quad_perm:[1,0,3,2] row_mask:0xf bank_mask:0xf bound_ctrl:1
	s_nop 1
	v_add_f32_dpp v202, v202, v202 quad_perm:[2,3,0,1] row_mask:0xf bank_mask:0xf bound_ctrl:1
	s_nop 1
	v_add_f32_dpp v202, v202, v202 row_half_mirror row_mask:0xf bank_mask:0xf bound_ctrl:1
	v_lshl_add_u32 v205, v56, 7, s60
	s_and_saveexec_b64 s[6:7], s[8:9]
	global_store_dword v205, v202, s[24:25]
	s_or_b64 exec, exec, s[6:7]
	v_add_u32_e32 v56, v59, v56
	s_waitcnt lgkmcnt(0)
	s_barrier
	s_waitcnt lgkmcnt(0)
	s_barrier

; __device__ __forceinline__ float row16_sum(float x) { x = red8_sum(x); x += dpp_f<0x140>(x); return x; }
; template <int RG>
; __device__ __forceinline__ void scan_waves16(const Params& p, float* lds, const int T, const int dir, const int wave, const int lane,
;                                            const size_t tok0, const int head, const int row_base) {
;     ...
;       LD16(0, 0);
; #pragma unroll
;       for (int st = 0; st < 16; ++st) {
;         const int B = st & 1;
;         if (st + 1 < 16) LD16(1 - B, st + 1);
;         asm volatile("" ::: "memory");
;         float sa[RG], o[RG];
; #pragma unroll
;         for (int g = 0; g < RG; ++g) {
;           const f32x2_t a0 = __builtin_elementwise_fma(S[g][1], kk[B][1], S[g][0] * kk[B][0]);
;           sa[g] = a0.x + a0.y;
;         }
; #pragma unroll
;         for (int g = 0; g < RG; ++g) sa[g] = -row16_sum(sa[g]);
; #pragma unroll
;         for (int g = 0; g < RG; ++g) {
;           const f32x2_t sav = {sa[g], sa[g]}, vvv = {vv[B][g], vv[B][g]};
;           S[g][0] = __builtin_elementwise_fma(vvv, kd[B][0], __builtin_elementwise_fma(sav, qa[B][0], S[g][0] * w[B][0]));
;           S[g][1] = __builtin_elementwise_fma(vvv, kd[B][1], __builtin_elementwise_fma(sav, qa[B][1], S[g][1] * w[B][1]));
;         }
; #pragma unroll
;         for (int g = 0; g < RG; ++g) {
;           const f32x2_t a0 = __builtin_elementwise_fma(S[g][1], r[B][1], S[g][0] * r[B][0]);
;           o[g] = a0.x + a0.y;
;         }
; #pragma unroll
;         for (int g = 0; g < RG; ++g) o[g] = row16_sum(o[g]);
;         float os = o[0];
; #pragma unroll
;         for (int g = 1; g < RG; ++g) os = (part == g) ? o[g] : os;
;         osv[st] = os;
;       }
.LBB0_1350:
	s_cmp_lt_i32 s3, 0
	s_cbranch_scc1 .LBB0_1349
	s_bitcmp1_b32 s3, 0
	s_cselect_b32 s8, 0x5000, 0
	v_lshl_add_u32 v10, v4, 2, s8
	v_lshl_add_u32 v11, s10, 12, v7
	v_lshl_add_u32 v12, v5, 2, s8
	ds_read_b128 v[20:23], v10 offset:20480
	ds_read_b128 v[16:19], v11
	ds_read_b128 v[28:31], v10 offset:20992
	ds_read_b32 v36, v12 offset:21504
	ds_read_b128 v[24:27], v10 offset:20736
	ds_read_b128 v[32:35], v10 offset:21248
	s_waitcnt lgkmcnt(0)
	ds_read_b128 v[44:47], v10 offset:21760
	ds_read_b128 v[40:43], v11 offset:256
	v_pk_mul_f32 v[80:81], v[0:1], v[20:21]
	v_pk_fma_f32 v[80:81], v[2:3], v[22:23], v[80:81]
	v_add_f32_e32 v82, v80, v81
	v_pk_mul_f32 v[84:85], v[0:1], v[16:17]
	v_pk_mul_f32 v[86:87], v[2:3], v[18:19]
	v_add_f32_dpp v82, v82, v82 quad_perm:[1,0,3,2] row_mask:0xf bank_mask:0xf bound_ctrl:1
	v_pk_fma_f32 v[84:85], v[36:37], v[28:29], v[84:85] op_sel_hi:[0,1,1]
	v_pk_fma_f32 v[86:87], v[36:37], v[30:31], v[86:87] op_sel_hi:[0,1,1]
	v_add_f32_dpp v82, v82, v82 quad_perm:[2,3,0,1] row_mask:0xf bank_mask:0xf bound_ctrl:1
	ds_read_b128 v[52:55], v10 offset:22272
	ds_read_b32 v60, v12 offset:22784
	v_add_f32_dpp v82, v82, v82 row_half_mirror row_mask:0xf bank_mask:0xf bound_ctrl:1
	ds_read_b128 v[48:51], v10 offset:22016
	ds_read_b128 v[56:59], v10 offset:22528
	v_add_f32_dpp v82, v82, v82 row_mirror row_mask:0xf bank_mask:0xf bound_ctrl:1
	v_pk_fma_f32 v[0:1], v[82:83], v[24:25], v[84:85] op_sel_hi:[0,1,1] neg_lo:[1,0,0] neg_hi:[1,0,0]
	v_pk_fma_f32 v[2:3], v[82:83], v[26:27], v[86:87] op_sel_hi:[0,1,1] neg_lo:[1,0,0] neg_hi:[1,0,0]
	s_waitcnt lgkmcnt(1)
	ds_read_b128 v[20:23], v10 offset:23040
	ds_read_b128 v[16:19], v11 offset:512
	ds_read_b128 v[28:31], v10 offset:23552
	ds_read_b32 v36, v12 offset:24064
	ds_read_b128 v[24:27], v10 offset:23296
	v_pk_mul_f32 v[80:81], v[0:1], v[44:45]
	v_pk_fma_f32 v[80:81], v[2:3], v[46:47], v[80:81]
	v_add_f32_e32 v82, v80, v81
	v_pk_mul_f32 v[84:85], v[0:1], v[40:41]
	v_pk_mul_f32 v[86:87], v[2:3], v[42:43]
	v_add_f32_dpp v82, v82, v82 quad_perm:[1,0,3,2] row_mask:0xf bank_mask:0xf bound_ctrl:1
	v_pk_fma_f32 v[84:85], v[60:61], v[52:53], v[84:85] op_sel_hi:[0,1,1]
	v_pk_fma_f32 v[86:87], v[60:61], v[54:55], v[86:87] op_sel_hi:[0,1,1]
	v_add_f32_dpp v82, v82, v82 quad_perm:[2,3,0,1] row_mask:0xf bank_mask:0xf bound_ctrl:1
	v_pk_mul_f32 v[88:89], v[0:1], v[32:33]
	v_pk_fma_f32 v[88:89], v[2:3], v[34:35], v[88:89]
	v_add_f32_dpp v82, v82, v82 row_half_mirror row_mask:0xf bank_mask:0xf bound_ctrl:1
	v_add_f32_e32 v64, v88, v89
	ds_read_b128 v[96:99], v10 offset:23808
	v_add_f32_dpp v82, v82, v82 row_mirror row_mask:0xf bank_mask:0xf bound_ctrl:1
	v_pk_fma_f32 v[0:1], v[82:83], v[48:49], v[84:85] op_sel_hi:[0,1,1] neg_lo:[1,0,0] neg_hi:[1,0,0]
	v_pk_fma_f32 v[2:3], v[82:83], v[50:51], v[86:87] op_sel_hi:[0,1,1] neg_lo:[1,0,0] neg_hi:[1,0,0]
	s_waitcnt lgkmcnt(1)
	ds_read_b128 v[44:47], v10 offset:24320
	ds_read_b128 v[40:43], v11 offset:768
	ds_read_b128 v[52:55], v10 offset:24832
	ds_read_b32 v60, v12 offset:25344
	ds_read_b128 v[48:51], v10 offset:24576
	v_pk_mul_f32 v[80:81], v[0:1], v[20:21]
	v_pk_fma_f32 v[80:81], v[2:3], v[22:23], v[80:81]
	v_add_f32_e32 v82, v80, v81
	v_pk_mul_f32 v[84:85], v[0:1], v[16:17]
	v_pk_mul_f32 v[86:87], v[2:3], v[18:19]
	v_add_f32_dpp v82, v82, v82 quad_perm:[1,0,3,2] row_mask:0xf bank_mask:0xf bound_ctrl:1
	v_pk_fma_f32 v[84:85], v[36:37], v[28:29], v[84:85] op_sel_hi:[0,1,1]
	v_pk_fma_f32 v[86:87], v[36:37], v[30:31], v[86:87] op_sel_hi:[0,1,1]
	v_add_f32_dpp v82, v82, v82 quad_perm:[2,3,0,1] row_mask:0xf bank_mask:0xf bound_ctrl:1
	v_pk_mul_f32 v[88:89], v[0:1], v[56:57]
	v_pk_fma_f32 v[88:89], v[2:3], v[58:59], v[88:89]
	v_add_f32_dpp v82, v82, v82 row_half_mirror row_mask:0xf bank_mask:0xf bound_ctrl:1
	v_add_f32_e32 v65, v88, v89
	ds_read_b128 v[32:35], v10 offset:25088
	v_add_f32_dpp v82, v82, v82 row_mirror row_mask:0xf bank_mask:0xf bound_ctrl:1
	v_pk_fma_f32 v[0:1], v[82:83], v[24:25], v[84:85] op_sel_hi:[0,1,1] neg_lo:[1,0,0] neg_hi:[1,0,0]
	v_pk_fma_f32 v[2:3], v[82:83], v[26:27], v[86:87] op_sel_hi:[0,1,1] neg_lo:[1,0,0] neg_hi:[1,0,0]
	s_waitcnt lgkmcnt(1)
	ds_read_b128 v[20:23], v10 offset:25600
	ds_read_b128 v[16:19], v11 offset:1024
	ds_read_b128 v[28:31], v10 offset:26112
	ds_read_b32 v36, v12 offset:26624
	ds_read_b128 v[24:27], v10 offset:25856
	v_pk_mul_f32 v[80:81], v[0:1], v[44:45]
	v_pk_fma_f32 v[80:81], v[2:3], v[46:47], v[80:81]
	v_add_f32_e32 v82, v80, v81
	v_pk_mul_f32 v[84:85], v[0:1], v[40:41]
	v_pk_mul_f32 v[86:87], v[2:3], v[42:43]
	v_add_f32_dpp v82, v82, v82 quad_perm:[1,0,3,2] row_mask:0xf bank_mask:0xf bound_ctrl:1
	v_pk_fma_f32 v[84:85], v[60:61], v[52:53], v[84:85] op_sel_hi:[0,1,1]
	v_pk_fma_f32 v[86:87], v[60:61], v[54:55], v[86:87] op_sel_hi:[0,1,1]
	v_add_f32_dpp v82, v82, v82 quad_perm:[2,3,0,1] row_mask:0xf bank_mask:0xf bound_ctrl:1
	v_pk_mul_f32 v[88:89], v[0:1], v[96:97]
	v_pk_fma_f32 v[88:89], v[2:3], v[98:99], v[88:89]
	v_add_f32_dpp v82, v82, v82 row_half_mirror row_mask:0xf bank_mask:0xf bound_ctrl:1
	v_add_f32_e32 v66, v88, v89
	ds_read_b128 v[56:59], v10 offset:26368
	v_add_f32_dpp v82, v82, v82 row_mirror row_mask:0xf bank_mask:0xf bound_ctrl:1
	v_pk_fma_f32 v[0:1], v[82:83], v[48:49], v[84:85] op_sel_hi:[0,1,1] neg_lo:[1,0,0] neg_hi:[1,0,0]
	v_pk_fma_f32 v[2:3], v[82:83], v[50:51], v[86:87] op_sel_hi:[0,1,1] neg_lo:[1,0,0] neg_hi:[1,0,0]
	s_waitcnt lgkmcnt(1)
; __device__ __forceinline__ float row16_sum(float x) { x = red8_sum(x); x += dpp_f<0x140>(x); return x; }
; template <int RG>
; __device__ __forceinline__ void scan_waves16(const Params& p, float* lds, const int T, const int dir, const int wave, const int lane,
;                                            const size_t tok0, const int head, const int row_base) {
;     ...
;       LD16(0, 0);
; #pragma unroll
;       for (int st = 0; st < 16; ++st) {
;         const int B = st & 1;
;         if (st + 1 < 16) LD16(1 - B, st + 1);
;         asm volatile("" ::: "memory");
;         float sa[RG], o[RG];
; #pragma unroll
;         for (int g = 0; g < RG; ++g) {
;           const f32x2_t a0 = __builtin_elementwise_fma(S[g][1], kk[B][1], S[g][0] * kk[B][0]);
;           sa[g] = a0.x + a0.y;
;         }
; #pragma unroll
;         for (int g = 0; g < RG; ++g) sa[g] = -row16_sum(sa[g]);
; #pragma unroll
;         for (int g = 0; g < RG; ++g) {
;           const f32x2_t sav = {sa[g], sa[g]}, vvv = {vv[B][g], vv[B][g]};
;           S[g][0] = __builtin_elementwise_fma(vvv, kd[B][0], __builtin_elementwise_fma(sav, qa[B][0], S[g][0] * w[B][0]));
;           S[g][1] = __builtin_elementwise_fma(vvv, kd[B][1], __builtin_elementwise_fma(sav, qa[B][1], S[g][1] * w[B][1]));
;         }
; #pragma unroll
;         for (int g = 0; g < RG; ++g) {
;           const f32x2_t a0 = __builtin_elementwise_fma(S[g][1], r[B][1], S[g][0] * r[B][0]);
;           o[g] = a0.x + a0.y;
;         }
; #pragma unroll
;         for (int g = 0; g < RG; ++g) o[g] = row16_sum(o[g]);
;         float os = o[0];
; #pragma unroll
;         for (int g = 1; g < RG; ++g) os = (part == g) ? o[g] : os;
;         osv[st] = os;
;       }
	ds_read_b128 v[44:47], v10 offset:26880
	ds_read_b128 v[40:43], v11 offset:1280
	ds_read_b128 v[52:55], v10 offset:27392
	ds_read_b32 v60, v12 offset:27904
	ds_read_b128 v[48:51], v10 offset:27136
	v_pk_mul_f32 v[80:81], v[0:1], v[20:21]
	v_pk_fma_f32 v[80:81], v[2:3], v[22:23], v[80:81]
	v_add_f32_e32 v82, v80, v81
	v_pk_mul_f32 v[84:85], v[0:1], v[16:17]
	v_pk_mul_f32 v[86:87], v[2:3], v[18:19]
	v_add_f32_dpp v82, v82, v82 quad_perm:[1,0,3,2] row_mask:0xf bank_mask:0xf bound_ctrl:1
	v_pk_fma_f32 v[84:85], v[36:37], v[28:29], v[84:85] op_sel_hi:[0,1,1]
	v_pk_fma_f32 v[86:87], v[36:37], v[30:31], v[86:87] op_sel_hi:[0,1,1]
	v_add_f32_dpp v82, v82, v82 quad_perm:[2,3,0,1] row_mask:0xf bank_mask:0xf bound_ctrl:1
	v_pk_mul_f32 v[88:89], v[0:1], v[32:33]
	v_pk_fma_f32 v[88:89], v[2:3], v[34:35], v[88:89]
	v_add_f32_dpp v82, v82, v82 row_half_mirror row_mask:0xf bank_mask:0xf bound_ctrl:1
	v_add_f32_e32 v67, v88, v89
	ds_read_b128 v[96:99], v10 offset:27648
	v_add_f32_dpp v82, v82, v82 row_mirror row_mask:0xf bank_mask:0xf bound_ctrl:1
	v_pk_fma_f32 v[0:1], v[82:83], v[24:25], v[84:85] op_sel_hi:[0,1,1] neg_lo:[1,0,0] neg_hi:[1,0,0]
	v_pk_fma_f32 v[2:3], v[82:83], v[26:27], v[86:87] op_sel_hi:[0,1,1] neg_lo:[1,0,0] neg_hi:[1,0,0]
	s_waitcnt lgkmcnt(1)
	ds_read_b128 v[20:23], v10 offset:28160
	ds_read_b128 v[16:19], v11 offset:1536
	ds_read_b128 v[28:31], v10 offset:28672
	ds_read_b32 v36, v12 offset:29184
	ds_read_b128 v[24:27], v10 offset:28416
	v_pk_mul_f32 v[80:81], v[0:1], v[44:45]
	v_pk_fma_f32 v[80:81], v[2:3], v[46:47], v[80:81]
	v_add_f32_e32 v82, v80, v81
	v_pk_mul_f32 v[84:85], v[0:1], v[40:41]
	v_pk_mul_f32 v[86:87], v[2:3], v[42:43]
	v_add_f32_dpp v82, v82, v82 quad_perm:[1,0,3,2] row_mask:0xf bank_mask:0xf bound_ctrl:1
	v_pk_fma_f32 v[84:85], v[60:61], v[52:53], v[84:85] op_sel_hi:[0,1,1]
	v_pk_fma_f32 v[86:87], v[60:61], v[54:55], v[86:87] op_sel_hi:[0,1,1]
	v_add_f32_dpp v82, v82, v82 quad_perm:[2,3,0,1] row_mask:0xf bank_mask:0xf bound_ctrl:1
	v_pk_mul_f32 v[88:89], v[0:1], v[56:57]
	v_pk_fma_f32 v[88:89], v[2:3], v[58:59], v[88:89]
	v_add_f32_dpp v82, v82, v82 row_half_mirror row_mask:0xf bank_mask:0xf bound_ctrl:1
	v_add_f32_e32 v68, v88, v89
	ds_read_b128 v[32:35], v10 offset:28928
	v_add_f32_dpp v82, v82, v82 row_mirror row_mask:0xf bank_mask:0xf bound_ctrl:1
	v_pk_fma_f32 v[0:1], v[82:83], v[48:49], v[84:85] op_sel_hi:[0,1,1] neg_lo:[1,0,0] neg_hi:[1,0,0]
	v_pk_fma_f32 v[2:3], v[82:83], v[50:51], v[86:87] op_sel_hi:[0,1,1] neg_lo:[1,0,0] neg_hi:[1,0,0]
	s_waitcnt lgkmcnt(1)
	ds_read_b128 v[44:47], v10 offset:29440
	ds_read_b128 v[40:43], v11 offset:1792
	ds_read_b128 v[52:55], v10 offset:29952
	ds_read_b32 v60, v12 offset:30464
	ds_read_b128 v[48:51], v10 offset:29696
	v_pk_mul_f32 v[80:81], v[0:1], v[20:21]
	v_pk_fma_f32 v[80:81], v[2:3], v[22:23], v[80:81]
	v_add_f32_e32 v82, v80, v81
	v_pk_mul_f32 v[84:85], v[0:1], v[16:17]
	v_pk_mul_f32 v[86:87], v[2:3], v[18:19]
	v_add_f32_dpp v82, v82, v82 quad_perm:[1,0,3,2] row_mask:0xf bank_mask:0xf bound_ctrl:1
	v_pk_fma_f32 v[84:85], v[36:37], v[28:29], v[84:85] op_sel_hi:[0,1,1]
	v_pk_fma_f32 v[86:87], v[36:37], v[30:31], v[86:87] op_sel_hi:[0,1,1]
	v_add_f32_dpp v82, v82, v82 quad_perm:[2,3,0,1] row_mask:0xf bank_mask:0xf bound_ctrl:1
	v_pk_mul_f32 v[88:89], v[0:1], v[96:97]
	v_pk_fma_f32 v[88:89], v[2:3], v[98:99], v[88:89]
	v_add_f32_dpp v82, v82, v82 row_half_mirror row_mask:0xf bank_mask:0xf bound_ctrl:1
	v_add_f32_e32 v69, v88, v89
	ds_read_b128 v[56:59], v10 offset:30208
	v_add_f32_dpp v82, v82, v82 row_mirror row_mask:0xf bank_mask:0xf bound_ctrl:1
	v_pk_fma_f32 v[0:1], v[82:83], v[24:25], v[84:85] op_sel_hi:[0,1,1] neg_lo:[1,0,0] neg_hi:[1,0,0]
	v_pk_fma_f32 v[2:3], v[82:83], v[26:27], v[86:87] op_sel_hi:[0,1,1] neg_lo:[1,0,0] neg_hi:[1,0,0]
	s_waitcnt lgkmcnt(1)
	ds_read_b128 v[20:23], v10 offset:30720
	ds_read_b128 v[16:19], v11 offset:2048
	ds_read_b128 v[28:31], v10 offset:31232
	ds_read_b32 v36, v12 offset:31744
	ds_read_b128 v[24:27], v10 offset:30976
	v_pk_mul_f32 v[80:81], v[0:1], v[44:45]
	v_pk_fma_f32 v[80:81], v[2:3], v[46:47], v[80:81]
	v_add_f32_e32 v82, v80, v81
	v_pk_mul_f32 v[84:85], v[0:1], v[40:41]
	v_pk_mul_f32 v[86:87], v[2:3], v[42:43]
	v_add_f32_dpp v82, v82, v82 quad_perm:[1,0,3,2] row_mask:0xf bank_mask:0xf bound_ctrl:1
	v_pk_fma_f32 v[84:85], v[60:61], v[52:53], v[84:85] op_sel_hi:[0,1,1]
	v_pk_fma_f32 v[86:87], v[60:61], v[54:55], v[86:87] op_sel_hi:[0,1,1]
	v_add_f32_dpp v82, v82, v82 quad_perm:[2,3,0,1] row_mask:0xf bank_mask:0xf bound_ctrl:1
	v_pk_mul_f32 v[88:89], v[0:1], v[32:33]
	v_pk_fma_f32 v[88:89], v[2:3], v[34:35], v[88:89]
	v_add_f32_dpp v82, v82, v82 row_half_mirror row_mask:0xf bank_mask:0xf bound_ctrl:1
	v_add_f32_e32 v70, v88, v89
	ds_read_b128 v[96:99], v10 offset:31488
	v_add_f32_dpp v82, v82, v82 row_mirror row_mask:0xf bank_mask:0xf bound_ctrl:1
	v_pk_fma_f32 v[0:1], v[82:83], v[48:49], v[84:85] op_sel_hi:[0,1,1] neg_lo:[1,0,0] neg_hi:[1,0,0]
	v_pk_fma_f32 v[2:3], v[82:83], v[50:51], v[86:87] op_sel_hi:[0,1,1] neg_lo:[1,0,0] neg_hi:[1,0,0]
	s_waitcnt lgkmcnt(1)
; __device__ __forceinline__ float row16_sum(float x) { x = red8_sum(x); x += dpp_f<0x140>(x); return x; }
; template <int RG>
; __device__ __forceinline__ void scan_waves16(const Params& p, float* lds, const int T, const int dir, const int wave, const int lane,
;                                            const size_t tok0, const int head, const int row_base) {
;     ...
;       LD16(0, 0);
; #pragma unroll
;       for (int st = 0; st < 16; ++st) {
;         const int B = st & 1;
;         if (st + 1 < 16) LD16(1 - B, st + 1);
;         asm volatile("" ::: "memory");
;         float sa[RG], o[RG];
; #pragma unroll
;         for (int g = 0; g < RG; ++g) {
;           const f32x2_t a0 = __builtin_elementwise_fma(S[g][1], kk[B][1], S[g][0] * kk[B][0]);
;           sa[g] = a0.x + a0.y;
;         }
; #pragma unroll
;         for (int g = 0; g < RG; ++g) sa[g] = -row16_sum(sa[g]);
; #pragma unroll
;         for (int g = 0; g < RG; ++g) {
;           const f32x2_t sav = {sa[g], sa[g]}, vvv = {vv[B][g], vv[B][g]};
;           S[g][0] = __builtin_elementwise_fma(vvv, kd[B][0], __builtin_elementwise_fma(sav, qa[B][0], S[g][0] * w[B][0]));
;           S[g][1] = __builtin_elementwise_fma(vvv, kd[B][1], __builtin_elementwise_fma(sav, qa[B][1], S[g][1] * w[B][1]));
;         }
; #pragma unroll
;         for (int g = 0; g < RG; ++g) {
;           const f32x2_t a0 = __builtin_elementwise_fma(S[g][1], r[B][1], S[g][0] * r[B][0]);
;           o[g] = a0.x + a0.y;
;         }
; #pragma unroll
;         for (int g = 0; g < RG; ++g) o[g] = row16_sum(o[g]);
;         float os = o[0];
; #pragma unroll
;         for (int g = 1; g < RG; ++g) os = (part == g) ? o[g] : os;
;         osv[st] = os;
;       }
	ds_read_b128 v[44:47], v10 offset:32000
	ds_read_b128 v[40:43], v11 offset:2304
	ds_read_b128 v[52:55], v10 offset:32512
	ds_read_b32 v60, v12 offset:33024
	ds_read_b128 v[48:51], v10 offset:32256
	v_pk_mul_f32 v[80:81], v[0:1], v[20:21]
	v_pk_fma_f32 v[80:81], v[2:3], v[22:23], v[80:81]
	v_add_f32_e32 v82, v80, v81
	v_pk_mul_f32 v[84:85], v[0:1], v[16:17]
	v_pk_mul_f32 v[86:87], v[2:3], v[18:19]
	v_add_f32_dpp v82, v82, v82 quad_perm:[1,0,3,2] row_mask:0xf bank_mask:0xf bound_ctrl:1
	v_pk_fma_f32 v[84:85], v[36:37], v[28:29], v[84:85] op_sel_hi:[0,1,1]
	v_pk_fma_f32 v[86:87], v[36:37], v[30:31], v[86:87] op_sel_hi:[0,1,1]
	v_add_f32_dpp v82, v82, v82 quad_perm:[2,3,0,1] row_mask:0xf bank_mask:0xf bound_ctrl:1
	v_pk_mul_f32 v[88:89], v[0:1], v[56:57]
	v_pk_fma_f32 v[88:89], v[2:3], v[58:59], v[88:89]
	v_add_f32_dpp v82, v82, v82 row_half_mirror row_mask:0xf bank_mask:0xf bound_ctrl:1
	v_add_f32_e32 v71, v88, v89
	ds_read_b128 v[32:35], v10 offset:32768
	v_add_f32_dpp v82, v82, v82 row_mirror row_mask:0xf bank_mask:0xf bound_ctrl:1
	v_pk_fma_f32 v[0:1], v[82:83], v[24:25], v[84:85] op_sel_hi:[0,1,1] neg_lo:[1,0,0] neg_hi:[1,0,0]
	v_pk_fma_f32 v[2:3], v[82:83], v[26:27], v[86:87] op_sel_hi:[0,1,1] neg_lo:[1,0,0] neg_hi:[1,0,0]
	s_waitcnt lgkmcnt(1)
	ds_read_b128 v[20:23], v10 offset:33280
	ds_read_b128 v[16:19], v11 offset:2560
	ds_read_b128 v[28:31], v10 offset:33792
	ds_read_b32 v36, v12 offset:34304
	ds_read_b128 v[24:27], v10 offset:33536
	v_pk_mul_f32 v[80:81], v[0:1], v[44:45]
	v_pk_fma_f32 v[80:81], v[2:3], v[46:47], v[80:81]
	v_add_f32_e32 v82, v80, v81
	v_pk_mul_f32 v[84:85], v[0:1], v[40:41]
	v_pk_mul_f32 v[86:87], v[2:3], v[42:43]
	v_add_f32_dpp v82, v82, v82 quad_perm:[1,0,3,2] row_mask:0xf bank_mask:0xf bound_ctrl:1
	v_pk_fma_f32 v[84:85], v[60:61], v[52:53], v[84:85] op_sel_hi:[0,1,1]
	v_pk_fma_f32 v[86:87], v[60:61], v[54:55], v[86:87] op_sel_hi:[0,1,1]
	v_add_f32_dpp v82, v82, v82 quad_perm:[2,3,0,1] row_mask:0xf bank_mask:0xf bound_ctrl:1
	v_pk_mul_f32 v[88:89], v[0:1], v[96:97]
	v_pk_fma_f32 v[88:89], v[2:3], v[98:99], v[88:89]
	v_add_f32_dpp v82, v82, v82 row_half_mirror row_mask:0xf bank_mask:0xf bound_ctrl:1
	v_add_f32_e32 v72, v88, v89
	ds_read_b128 v[56:59], v10 offset:34048
	v_add_f32_dpp v82, v82, v82 row_mirror row_mask:0xf bank_mask:0xf bound_ctrl:1
	v_pk_fma_f32 v[0:1], v[82:83], v[48:49], v[84:85] op_sel_hi:[0,1,1] neg_lo:[1,0,0] neg_hi:[1,0,0]
	v_pk_fma_f32 v[2:3], v[82:83], v[50:51], v[86:87] op_sel_hi:[0,1,1] neg_lo:[1,0,0] neg_hi:[1,0,0]
	s_waitcnt lgkmcnt(1)
	ds_read_b128 v[44:47], v10 offset:34560
	ds_read_b128 v[40:43], v11 offset:2816
	ds_read_b128 v[52:55], v10 offset:35072
	ds_read_b32 v60, v12 offset:35584
	ds_read_b128 v[48:51], v10 offset:34816
	v_pk_mul_f32 v[80:81], v[0:1], v[20:21]
	v_pk_fma_f32 v[80:81], v[2:3], v[22:23], v[80:81]
	v_add_f32_e32 v82, v80, v81
	v_pk_mul_f32 v[84:85], v[0:1], v[16:17]
	v_pk_mul_f32 v[86:87], v[2:3], v[18:19]
	v_add_f32_dpp v82, v82, v82 quad_perm:[1,0,3,2] row_mask:0xf bank_mask:0xf bound_ctrl:1
	v_pk_fma_f32 v[84:85], v[36:37], v[28:29], v[84:85] op_sel_hi:[0,1,1]
	v_pk_fma_f32 v[86:87], v[36:37], v[30:31], v[86:87] op_sel_hi:[0,1,1]
	v_add_f32_dpp v82, v82, v82 quad_perm:[2,3,0,1] row_mask:0xf bank_mask:0xf bound_ctrl:1
	v_pk_mul_f32 v[88:89], v[0:1], v[32:33]
	v_pk_fma_f32 v[88:89], v[2:3], v[34:35], v[88:89]
	v_add_f32_dpp v82, v82, v82 row_half_mirror row_mask:0xf bank_mask:0xf bound_ctrl:1
	v_add_f32_e32 v73, v88, v89
	ds_read_b128 v[96:99], v10 offset:35328
	v_add_f32_dpp v82, v82, v82 row_mirror row_mask:0xf bank_mask:0xf bound_ctrl:1
	v_pk_fma_f32 v[0:1], v[82:83], v[24:25], v[84:85] op_sel_hi:[0,1,1] neg_lo:[1,0,0] neg_hi:[1,0,0]
	v_pk_fma_f32 v[2:3], v[82:83], v[26:27], v[86:87] op_sel_hi:[0,1,1] neg_lo:[1,0,0] neg_hi:[1,0,0]
	s_waitcnt lgkmcnt(1)
	ds_read_b128 v[20:23], v10 offset:35840
	ds_read_b128 v[16:19], v11 offset:3072
	ds_read_b128 v[28:31], v10 offset:36352
	ds_read_b32 v36, v12 offset:36864
	ds_read_b128 v[24:27], v10 offset:36096
	v_pk_mul_f32 v[80:81], v[0:1], v[44:45]
	v_pk_fma_f32 v[80:81], v[2:3], v[46:47], v[80:81]
	v_add_f32_e32 v82, v80, v81
	v_pk_mul_f32 v[84:85], v[0:1], v[40:41]
	v_pk_mul_f32 v[86:87], v[2:3], v[42:43]
	v_add_f32_dpp v82, v82, v82 quad_perm:[1,0,3,2] row_mask:0xf bank_mask:0xf bound_ctrl:1
	v_pk_fma_f32 v[84:85], v[60:61], v[52:53], v[84:85] op_sel_hi:[0,1,1]
	v_pk_fma_f32 v[86:87], v[60:61], v[54:55], v[86:87] op_sel_hi:[0,1,1]
	v_add_f32_dpp v82, v82, v82 quad_perm:[2,3,0,1] row_mask:0xf bank_mask:0xf bound_ctrl:1
	v_pk_mul_f32 v[88:89], v[0:1], v[56:57]
	v_pk_fma_f32 v[88:89], v[2:3], v[58:59], v[88:89]
	v_add_f32_dpp v82, v82, v82 row_half_mirror row_mask:0xf bank_mask:0xf bound_ctrl:1
	v_add_f32_e32 v74, v88, v89
	ds_read_b128 v[32:35], v10 offset:36608
	v_add_f32_dpp v82, v82, v82 row_mirror row_mask:0xf bank_mask:0xf bound_ctrl:1
	v_pk_fma_f32 v[0:1], v[82:83], v[48:49], v[84:85] op_sel_hi:[0,1,1] neg_lo:[1,0,0] neg_hi:[1,0,0]
	v_pk_fma_f32 v[2:3], v[82:83], v[50:51], v[86:87] op_sel_hi:[0,1,1] neg_lo:[1,0,0] neg_hi:[1,0,0]
	s_waitcnt lgkmcnt(1)
; __device__ __forceinline__ float row16_sum(float x) { x = red8_sum(x); x += dpp_f<0x140>(x); return x; }
; template <int RG>
; __device__ __forceinline__ void scan_waves16(const Params& p, float* lds, const int T, const int dir, const int wave, const int lane,
;                                            const size_t tok0, const int head, const int row_base) {
;     ...
;       for (int st = 0; st < 16; ++st) {
;         const int B = st & 1;
;         if (st + 1 < 16) LD16(1 - B, st + 1);
;         asm volatile("" ::: "memory");
;         float sa[RG], o[RG];
; #pragma unroll
;         for (int g = 0; g < RG; ++g) {
;           const f32x2_t a0 = __builtin_elementwise_fma(S[g][1], kk[B][1], S[g][0] * kk[B][0]);
;           sa[g] = a0.x + a0.y;
;         }
; #pragma unroll
;         for (int g = 0; g < RG; ++g) sa[g] = -row16_sum(sa[g]);
; #pragma unroll
;         for (int g = 0; g < RG; ++g) {
;           const f32x2_t sav = {sa[g], sa[g]}, vvv = {vv[B][g], vv[B][g]};
;           S[g][0] = __builtin_elementwise_fma(vvv, kd[B][0], __builtin_elementwise_fma(sav, qa[B][0], S[g][0] * w[B][0]));
;           S[g][1] = __builtin_elementwise_fma(vvv, kd[B][1], __builtin_elementwise_fma(sav, qa[B][1], S[g][1] * w[B][1]));
;         }
; #pragma unroll
;         for (int g = 0; g < RG; ++g) {
;           const f32x2_t a0 = __builtin_elementwise_fma(S[g][1], r[B][1], S[g][0] * r[B][0]);
;           o[g] = a0.x + a0.y;
;         }
	ds_read_b128 v[44:47], v10 offset:37120
	ds_read_b128 v[40:43], v11 offset:3328
	ds_read_b128 v[52:55], v10 offset:37632
	ds_read_b32 v60, v12 offset:38144
	ds_read_b128 v[48:51], v10 offset:37376
	v_pk_mul_f32 v[80:81], v[0:1], v[20:21]
	v_pk_fma_f32 v[80:81], v[2:3], v[22:23], v[80:81]
	v_add_f32_e32 v82, v80, v81
	v_pk_mul_f32 v[84:85], v[0:1], v[16:17]
	v_pk_mul_f32 v[86:87], v[2:3], v[18:19]
	v_add_f32_dpp v82, v82, v82 quad_perm:[1,0,3,2] row_mask:0xf bank_mask:0xf bound_ctrl:1
	v_pk_fma_f32 v[84:85], v[36:37], v[28:29], v[84:85] op_sel_hi:[0,1,1]
	v_pk_fma_f32 v[86:87], v[36:37], v[30:31], v[86:87] op_sel_hi:[0,1,1]
	v_add_f32_dpp v82, v82, v82 quad_perm:[2,3,0,1] row_mask:0xf bank_mask:0xf bound_ctrl:1
	v_pk_mul_f32 v[88:89], v[0:1], v[96:97]
	v_pk_fma_f32 v[88:89], v[2:3], v[98:99], v[88:89]
	v_add_f32_dpp v82, v82, v82 row_half_mirror row_mask:0xf bank_mask:0xf bound_ctrl:1
	v_add_f32_e32 v75, v88, v89
	ds_read_b128 v[56:59], v10 offset:37888
	v_add_f32_dpp v82, v82, v82 row_mirror row_mask:0xf bank_mask:0xf bound_ctrl:1
	v_pk_fma_f32 v[0:1], v[82:83], v[24:25], v[84:85] op_sel_hi:[0,1,1] neg_lo:[1,0,0] neg_hi:[1,0,0]
	v_pk_fma_f32 v[2:3], v[82:83], v[26:27], v[86:87] op_sel_hi:[0,1,1] neg_lo:[1,0,0] neg_hi:[1,0,0]
	s_waitcnt lgkmcnt(1)
	ds_read_b128 v[20:23], v10 offset:38400
	ds_read_b128 v[16:19], v11 offset:3584
	ds_read_b128 v[28:31], v10 offset:38912
	ds_read_b32 v36, v12 offset:39424
	ds_read_b128 v[24:27], v10 offset:38656
	v_pk_mul_f32 v[80:81], v[0:1], v[44:45]
	v_pk_fma_f32 v[80:81], v[2:3], v[46:47], v[80:81]
	v_add_f32_e32 v82, v80, v81
	v_pk_mul_f32 v[84:85], v[0:1], v[40:41]
	v_pk_mul_f32 v[86:87], v[2:3], v[42:43]
	v_add_f32_dpp v82, v82, v82 quad_perm:[1,0,3,2] row_mask:0xf bank_mask:0xf bound_ctrl:1
	v_pk_fma_f32 v[84:85], v[60:61], v[52:53], v[84:85] op_sel_hi:[0,1,1]
	v_pk_fma_f32 v[86:87], v[60:61], v[54:55], v[86:87] op_sel_hi:[0,1,1]
	v_add_f32_dpp v82, v82, v82 quad_perm:[2,3,0,1] row_mask:0xf bank_mask:0xf bound_ctrl:1
	v_pk_mul_f32 v[88:89], v[0:1], v[32:33]
	v_pk_fma_f32 v[88:89], v[2:3], v[34:35], v[88:89]
	v_add_f32_dpp v82, v82, v82 row_half_mirror row_mask:0xf bank_mask:0xf bound_ctrl:1
	v_add_f32_e32 v76, v88, v89
	ds_read_b128 v[96:99], v10 offset:39168
	v_add_f32_dpp v82, v82, v82 row_mirror row_mask:0xf bank_mask:0xf bound_ctrl:1
	v_pk_fma_f32 v[0:1], v[82:83], v[48:49], v[84:85] op_sel_hi:[0,1,1] neg_lo:[1,0,0] neg_hi:[1,0,0]
	v_pk_fma_f32 v[2:3], v[82:83], v[50:51], v[86:87] op_sel_hi:[0,1,1] neg_lo:[1,0,0] neg_hi:[1,0,0]
	s_waitcnt lgkmcnt(1)
	ds_read_b128 v[44:47], v10 offset:39680
	ds_read_b128 v[40:43], v11 offset:3840
	ds_read_b128 v[52:55], v10 offset:40192
	ds_read_b32 v60, v12 offset:40704
	ds_read_b128 v[48:51], v10 offset:39936
	v_pk_mul_f32 v[80:81], v[0:1], v[20:21]
	v_pk_fma_f32 v[80:81], v[2:3], v[22:23], v[80:81]
	v_add_f32_e32 v82, v80, v81
	v_pk_mul_f32 v[84:85], v[0:1], v[16:17]
	v_pk_mul_f32 v[86:87], v[2:3], v[18:19]
	v_add_f32_dpp v82, v82, v82 quad_perm:[1,0,3,2] row_mask:0xf bank_mask:0xf bound_ctrl:1
	v_pk_fma_f32 v[84:85], v[36:37], v[28:29], v[84:85] op_sel_hi:[0,1,1]
	v_pk_fma_f32 v[86:87], v[36:37], v[30:31], v[86:87] op_sel_hi:[0,1,1]
	v_add_f32_dpp v82, v82, v82 quad_perm:[2,3,0,1] row_mask:0xf bank_mask:0xf bound_ctrl:1
	v_pk_mul_f32 v[88:89], v[0:1], v[56:57]
	v_pk_fma_f32 v[88:89], v[2:3], v[58:59], v[88:89]
	v_add_f32_dpp v82, v82, v82 row_half_mirror row_mask:0xf bank_mask:0xf bound_ctrl:1
	v_add_f32_e32 v77, v88, v89
	ds_read_b128 v[32:35], v10 offset:40448
	v_add_f32_dpp v82, v82, v82 row_mirror row_mask:0xf bank_mask:0xf bound_ctrl:1
	v_pk_fma_f32 v[0:1], v[82:83], v[24:25], v[84:85] op_sel_hi:[0,1,1] neg_lo:[1,0,0] neg_hi:[1,0,0]
	v_pk_fma_f32 v[2:3], v[82:83], v[26:27], v[86:87] op_sel_hi:[0,1,1] neg_lo:[1,0,0] neg_hi:[1,0,0]
	s_waitcnt lgkmcnt(1)
; __device__ __forceinline__ u16 f2bf(float f) { unsigned u = __float_as_uint(f); u += 0x7fffu + ((u >> 16) & 1u); return (u16)(u >> 16); }
; __device__ __forceinline__ float row16_sum(float x) { x = red8_sum(x); x += dpp_f<0x140>(x); return x; }
; template <int RG>
; __device__ __forceinline__ void scan_waves16(const Params& p, float* lds, const int T, const int dir, const int wave, const int lane,
;                                            const size_t tok0, const int head, const int row_base) {
;     ...
;         for (int g = 0; g < RG; ++g) {
;           const f32x2_t a0 = __builtin_elementwise_fma(S[g][1], r[B][1], S[g][0] * r[B][0]);
;           o[g] = a0.x + a0.y;
;         }
; #pragma unroll
;         for (int g = 0; g < RG; ++g) o[g] = row16_sum(o[g]);
;         float os = o[0];
; #pragma unroll
;         for (int g = 1; g < RG; ++g) os = (part == g) ? o[g] : os;
;         osv[st] = os;
;       }
;     ...
;       if (part < RG) {
;         const int s0 = i * 16; const unsigned t0 = dir ? (unsigned)(T - 1 - s0) : (unsigned)s0;
;         unsigned off = ooff0 + t0 * ostride; const unsigned dt = dir ? 0u - ostride : ostride;
; #pragma unroll
;         for (int st = 0; st < 16; ++st) { *(u16*)(obase + (size_t)off) = f2bf(osv[st]); off += dt; }
	v_pk_mul_f32 v[80:81], v[0:1], v[44:45]
	v_pk_fma_f32 v[80:81], v[2:3], v[46:47], v[80:81]
	v_add_f32_e32 v82, v80, v81
	v_pk_mul_f32 v[84:85], v[0:1], v[40:41]
	v_pk_mul_f32 v[86:87], v[2:3], v[42:43]
	v_add_f32_dpp v82, v82, v82 quad_perm:[1,0,3,2] row_mask:0xf bank_mask:0xf bound_ctrl:1
	v_pk_fma_f32 v[84:85], v[60:61], v[52:53], v[84:85] op_sel_hi:[0,1,1]
	v_pk_fma_f32 v[86:87], v[60:61], v[54:55], v[86:87] op_sel_hi:[0,1,1]
	v_add_f32_dpp v82, v82, v82 quad_perm:[2,3,0,1] row_mask:0xf bank_mask:0xf bound_ctrl:1
	v_pk_mul_f32 v[88:89], v[0:1], v[96:97]
	v_pk_fma_f32 v[88:89], v[2:3], v[98:99], v[88:89]
	v_add_f32_dpp v82, v82, v82 row_half_mirror row_mask:0xf bank_mask:0xf bound_ctrl:1
	v_add_f32_e32 v78, v88, v89
	s_nop 0
	v_add_f32_dpp v82, v82, v82 row_mirror row_mask:0xf bank_mask:0xf bound_ctrl:1
	v_pk_fma_f32 v[0:1], v[82:83], v[48:49], v[84:85] op_sel_hi:[0,1,1] neg_lo:[1,0,0] neg_hi:[1,0,0]
	v_pk_fma_f32 v[2:3], v[82:83], v[50:51], v[86:87] op_sel_hi:[0,1,1] neg_lo:[1,0,0] neg_hi:[1,0,0]
	s_waitcnt lgkmcnt(0)
	v_pk_mul_f32 v[88:89], v[0:1], v[32:33]
	v_pk_fma_f32 v[88:89], v[2:3], v[34:35], v[88:89]
	v_add_f32_e32 v79, v88, v89
	v_cmp_ne_u32_e32 vcc, 0, v9
	v_add_f32_dpp v64, v64, v64 row_mirror row_mask:0xf bank_mask:0x3 bound_ctrl:1
	v_add_f32_dpp v64, v72, v72 row_mirror row_mask:0xf bank_mask:0xc bound_ctrl:1
	v_add_f32_dpp v65, v65, v65 row_mirror row_mask:0xf bank_mask:0x3 bound_ctrl:1
	v_add_f32_dpp v65, v73, v73 row_mirror row_mask:0xf bank_mask:0xc bound_ctrl:1
	v_add_f32_dpp v66, v66, v66 row_mirror row_mask:0xf bank_mask:0x3 bound_ctrl:1
	v_add_f32_dpp v66, v74, v74 row_mirror row_mask:0xf bank_mask:0xc bound_ctrl:1
	v_add_f32_dpp v67, v67, v67 row_mirror row_mask:0xf bank_mask:0x3 bound_ctrl:1
	v_add_f32_dpp v67, v75, v75 row_mirror row_mask:0xf bank_mask:0xc bound_ctrl:1
	v_add_f32_dpp v68, v68, v68 row_mirror row_mask:0xf bank_mask:0x3 bound_ctrl:1
	v_add_f32_dpp v68, v76, v76 row_mirror row_mask:0xf bank_mask:0xc bound_ctrl:1
	v_add_f32_dpp v69, v69, v69 row_mirror row_mask:0xf bank_mask:0x3 bound_ctrl:1
	v_add_f32_dpp v69, v77, v77 row_mirror row_mask:0xf bank_mask:0xc bound_ctrl:1
	v_add_f32_dpp v70, v70, v70 row_mirror row_mask:0xf bank_mask:0x3 bound_ctrl:1
	v_add_f32_dpp v70, v78, v78 row_mirror row_mask:0xf bank_mask:0xc bound_ctrl:1
	v_add_f32_dpp v71, v71, v71 row_mirror row_mask:0xf bank_mask:0x3 bound_ctrl:1
	v_add_f32_dpp v71, v79, v79 row_mirror row_mask:0xf bank_mask:0xc bound_ctrl:1
	v_add_f32_dpp v64, v64, v64 row_half_mirror row_mask:0xf bank_mask:0x5 bound_ctrl:1
	v_add_f32_dpp v64, v68, v68 row_half_mirror row_mask:0xf bank_mask:0xa bound_ctrl:1
	v_add_f32_dpp v65, v65, v65 row_half_mirror row_mask:0xf bank_mask:0x5 bound_ctrl:1
	v_add_f32_dpp v65, v69, v69 row_half_mirror row_mask:0xf bank_mask:0xa bound_ctrl:1
	v_add_f32_dpp v66, v66, v66 row_half_mirror row_mask:0xf bank_mask:0x5 bound_ctrl:1
	v_add_f32_dpp v66, v70, v70 row_half_mirror row_mask:0xf bank_mask:0xa bound_ctrl:1
	v_add_f32_dpp v67, v67, v67 row_half_mirror row_mask:0xf bank_mask:0x5 bound_ctrl:1
	v_add_f32_dpp v67, v71, v71 row_half_mirror row_mask:0xf bank_mask:0xa bound_ctrl:1
	s_nop 0
	v_cndmask_b32_e32 v90, v66, v64, vcc
	v_cndmask_b32_e32 v91, v67, v65, vcc
	v_cndmask_b32_e32 v92, v64, v66, vcc
	v_cndmask_b32_e32 v93, v65, v67, vcc
	v_cmp_ne_u32_e32 vcc, 0, v13
	v_add_f32_dpp v94, v90, v92 quad_perm:[2,3,0,1] row_mask:0xf bank_mask:0xf bound_ctrl:1
	v_add_f32_dpp v95, v91, v93 quad_perm:[2,3,0,1] row_mask:0xf bank_mask:0xf bound_ctrl:1
	s_and_b64 s[16:17], s[0:1], exec
	v_cndmask_b32_e32 v90, v95, v94, vcc
	v_cndmask_b32_e32 v92, v94, v95, vcc
	s_cselect_b32 s16, s13, s14
	s_lshl_b32 s16, s16, s12
	v_add_f32_dpp v94, v90, v92 quad_perm:[1,0,3,2] row_mask:0xf bank_mask:0xf bound_ctrl:1
	v_add3_u32 v91, v6, v8, s16
	v_cvt_pk_bf16_f32 v94, v94, v94
	global_store_short v91, v94, s[6:7]
	s_branch .Lmy_sw_next
